# rows: nt hint on the X (f32 residual) stores only
# speedup vs baseline: 1.0249x; 1.0074x over previous
_Z10fwd_kernelILi4ELi5EEv4Args:
	s_load_dword s3, s[0:1], 0xe8
	s_load_dwordx4 s[4:7], s[0:1], 0xd0
	s_load_dwordx2 s[8:9], s[0:1], 0xa8
	s_load_dwordx2 s[10:11], s[0:1], 0xb0
	s_load_dwordx4 s[12:15], s[0:1], 0x0
	s_waitcnt lgkmcnt(0)
	s_cmp_lg_u32 s3, 0x100
	s_cbranch_scc1 .Lrows4_orig
	v_readfirstlane_b32 s16, v0
	s_lshr_b32 s16, s16, 6
	s_lshl_b32 s18, s2, 3
	s_add_u32 s16, s16, s18
	s_mov_b32 s17, 0x3a800000
	v_mov_b32_e32 v3, 0x358637bd
	v_and_b32_e32 v10, 63, v0
	v_lshlrev_b32_e32 v1, 4, v10
	v_lshlrev_b32_e32 v2, 3, v10
	v_xor_b32_e32 v4, 1, v10
	v_xor_b32_e32 v5, 2, v10
	v_xor_b32_e32 v6, 4, v10
	v_xor_b32_e32 v7, 8, v10
	v_xor_b32_e32 v8, 16, v10
	v_xor_b32_e32 v9, 32, v10
	v_lshlrev_b32_e32 v4, 2, v4
	v_lshlrev_b32_e32 v5, 2, v5
	v_lshlrev_b32_e32 v6, 2, v6
	v_lshlrev_b32_e32 v7, 2, v7
	v_lshlrev_b32_e32 v8, 2, v8
	v_lshlrev_b32_e32 v9, 2, v9
	global_load_dwordx4 v[20:23], v1, s[8:9] offset:0
	global_load_dwordx4 v[24:27], v1, s[8:9] offset:1024
	global_load_dwordx4 v[28:31], v1, s[8:9] offset:2048
	global_load_dwordx4 v[32:35], v1, s[8:9] offset:3072
	global_load_dwordx4 v[36:39], v1, s[10:11] offset:0
	global_load_dwordx4 v[40:43], v1, s[10:11] offset:1024
	global_load_dwordx4 v[44:47], v1, s[10:11] offset:2048
	global_load_dwordx4 v[48:51], v1, s[10:11] offset:3072
	s_lshr_b32 s54, s16, 2
	s_and_b32 s55, s16, 3
	s_lshl_b32 s55, s55, 10
	s_lshl_b32 s18, s54, 12
	s_add_u32 s18, s18, s55
	s_add_u32 s56, s6, s18
	s_addc_u32 s57, s7, 0
	s_add_u32 s56, s56, 0x7400000
	s_addc_u32 s57, s57, 0
	global_load_dwordx4 v[208:211], v1, s[56:57]
	s_add_u32 s56, s56, 0x200000
	s_addc_u32 s57, s57, 0
	global_load_dwordx4 v[212:215], v1, s[56:57]
	s_add_u32 s56, s14, s18
	s_addc_u32 s57, s15, 0
	global_load_dwordx4 v[240:243], v1, s[56:57]
	s_add_u32 s56, s8, s55
	s_addc_u32 s57, s9, 0
	global_load_dwordx4 v[244:247], v1, s[56:57]
	s_add_u32 s56, s10, s55
	s_addc_u32 s57, s11, 0
	global_load_dwordx4 v[248:251], v1, s[56:57]
	s_add_u32 s53, s16, 0x0
	s_lshl_b32 s18, s53, 12
	s_lshl_b32 s19, s53, 11
	s_add_u32 s20, s12, s18
	s_addc_u32 s21, s13, 0
	s_add_u32 s22, s6, s19
	s_addc_u32 s23, s7, 0
	s_add_u32 s22, s22, 0x5200000
	s_addc_u32 s23, s23, 0
	s_add_u32 s24, s4, s18
	s_addc_u32 s25, s5, 0
	s_add_u32 s26, s6, s19
	s_addc_u32 s27, s7, 0
	s_add_u32 s26, s26, 0x3100000
	s_addc_u32 s27, s27, 0
	global_load_dwordx2 v[66:67], v2, s[22:23] offset:0
	global_load_dwordx2 v[70:71], v2, s[22:23] offset:512
	global_load_dwordx2 v[74:75], v2, s[22:23] offset:1024
	global_load_dwordx2 v[78:79], v2, s[22:23] offset:1536
	global_load_dwordx4 v[80:83], v1, s[20:21] offset:0
	global_load_dwordx4 v[84:87], v1, s[20:21] offset:1024
	global_load_dwordx4 v[88:91], v1, s[20:21] offset:2048
	global_load_dwordx4 v[92:95], v1, s[20:21] offset:3072
	s_add_u32 s53, s16, 0x800
	s_lshl_b32 s18, s53, 12
	s_lshl_b32 s19, s53, 11
	s_add_u32 s28, s12, s18
	s_addc_u32 s29, s13, 0
	s_add_u32 s30, s6, s19
	s_addc_u32 s31, s7, 0
	s_add_u32 s30, s30, 0x5200000
	s_addc_u32 s31, s31, 0
	s_add_u32 s32, s4, s18
	s_addc_u32 s33, s5, 0
	s_add_u32 s34, s6, s19
	s_addc_u32 s35, s7, 0
	s_add_u32 s34, s34, 0x3100000
	s_addc_u32 s35, s35, 0
	global_load_dwordx2 v[98:99], v2, s[30:31] offset:0
	global_load_dwordx2 v[102:103], v2, s[30:31] offset:512
	global_load_dwordx2 v[106:107], v2, s[30:31] offset:1024
	global_load_dwordx2 v[110:111], v2, s[30:31] offset:1536
	global_load_dwordx4 v[112:115], v1, s[28:29] offset:0
	global_load_dwordx4 v[116:119], v1, s[28:29] offset:1024
	global_load_dwordx4 v[120:123], v1, s[28:29] offset:2048
	global_load_dwordx4 v[124:127], v1, s[28:29] offset:3072
	s_add_u32 s53, s16, 0x1000
	s_lshl_b32 s18, s53, 12
	s_lshl_b32 s19, s53, 11
	s_add_u32 s36, s12, s18
	s_addc_u32 s37, s13, 0
	s_add_u32 s38, s6, s19
	s_addc_u32 s39, s7, 0
	s_add_u32 s38, s38, 0x5200000
	s_addc_u32 s39, s39, 0
	s_add_u32 s40, s4, s18
	s_addc_u32 s41, s5, 0
	s_add_u32 s42, s6, s19
	s_addc_u32 s43, s7, 0
	s_add_u32 s42, s42, 0x3100000
	s_addc_u32 s43, s43, 0
	global_load_dwordx2 v[130:131], v2, s[38:39] offset:0
	global_load_dwordx2 v[134:135], v2, s[38:39] offset:512
	global_load_dwordx2 v[138:139], v2, s[38:39] offset:1024
	global_load_dwordx2 v[142:143], v2, s[38:39] offset:1536
	global_load_dwordx4 v[144:147], v1, s[36:37] offset:0
	global_load_dwordx4 v[148:151], v1, s[36:37] offset:1024
	global_load_dwordx4 v[152:155], v1, s[36:37] offset:2048
	global_load_dwordx4 v[156:159], v1, s[36:37] offset:3072
	s_add_u32 s53, s16, 0x1800
	s_lshl_b32 s18, s53, 12
	s_lshl_b32 s19, s53, 11
	s_add_u32 s44, s12, s18
	s_addc_u32 s45, s13, 0
	s_add_u32 s46, s6, s19
	s_addc_u32 s47, s7, 0
	s_add_u32 s46, s46, 0x5200000
	s_addc_u32 s47, s47, 0
	s_add_u32 s48, s4, s18
	s_addc_u32 s49, s5, 0
	s_add_u32 s50, s6, s19
	s_addc_u32 s51, s7, 0
	s_add_u32 s50, s50, 0x3100000
	s_addc_u32 s51, s51, 0
	global_load_dwordx2 v[162:163], v2, s[46:47] offset:0
	global_load_dwordx2 v[166:167], v2, s[46:47] offset:512
	global_load_dwordx2 v[170:171], v2, s[46:47] offset:1024
	global_load_dwordx2 v[174:175], v2, s[46:47] offset:1536
	global_load_dwordx4 v[176:179], v1, s[44:45] offset:0
	global_load_dwordx4 v[180:183], v1, s[44:45] offset:1024
	global_load_dwordx4 v[184:187], v1, s[44:45] offset:2048
	global_load_dwordx4 v[188:191], v1, s[44:45] offset:3072
	s_waitcnt vmcnt(16)
	v_lshlrev_b32_e32 v64, 16, v66
	v_and_b32_e32 v65, 0xffff0000, v66
	v_lshlrev_b32_e32 v66, 16, v67
	v_and_b32_e32 v67, 0xffff0000, v67
	v_lshlrev_b32_e32 v68, 16, v70
	v_and_b32_e32 v69, 0xffff0000, v70
	v_lshlrev_b32_e32 v70, 16, v71
	v_and_b32_e32 v71, 0xffff0000, v71
	v_lshlrev_b32_e32 v72, 16, v74
	v_and_b32_e32 v73, 0xffff0000, v74
	v_lshlrev_b32_e32 v74, 16, v75
	v_and_b32_e32 v75, 0xffff0000, v75
	v_lshlrev_b32_e32 v76, 16, v78
	v_and_b32_e32 v77, 0xffff0000, v78
	v_lshlrev_b32_e32 v78, 16, v79
	v_and_b32_e32 v79, 0xffff0000, v79
	v_lshlrev_b32_e32 v96, 16, v98
	v_and_b32_e32 v97, 0xffff0000, v98
	v_lshlrev_b32_e32 v98, 16, v99
	v_and_b32_e32 v99, 0xffff0000, v99
	v_lshlrev_b32_e32 v100, 16, v102
	v_and_b32_e32 v101, 0xffff0000, v102
	v_lshlrev_b32_e32 v102, 16, v103
	v_and_b32_e32 v103, 0xffff0000, v103
	v_lshlrev_b32_e32 v104, 16, v106
	v_and_b32_e32 v105, 0xffff0000, v106
	v_lshlrev_b32_e32 v106, 16, v107
	v_and_b32_e32 v107, 0xffff0000, v107
	v_lshlrev_b32_e32 v108, 16, v110
	v_and_b32_e32 v109, 0xffff0000, v110
	v_lshlrev_b32_e32 v110, 16, v111
	v_and_b32_e32 v111, 0xffff0000, v111
	v_mul_f32_e32 v10, v64, v64
	v_fmac_f32_e32 v10, v65, v65
	v_fmac_f32_e32 v10, v66, v66
	v_fmac_f32_e32 v10, v67, v67
	v_fmac_f32_e32 v10, v68, v68
	v_fmac_f32_e32 v10, v69, v69
	v_fmac_f32_e32 v10, v70, v70
	v_fmac_f32_e32 v10, v71, v71
	v_fmac_f32_e32 v10, v72, v72
	v_fmac_f32_e32 v10, v73, v73
	v_fmac_f32_e32 v10, v74, v74
	v_fmac_f32_e32 v10, v75, v75
	v_fmac_f32_e32 v10, v76, v76
	v_fmac_f32_e32 v10, v77, v77
	v_fmac_f32_e32 v10, v78, v78
	v_fmac_f32_e32 v10, v79, v79
	v_mul_f32_e32 v11, v96, v96
	v_fmac_f32_e32 v11, v97, v97
	v_fmac_f32_e32 v11, v98, v98
	v_fmac_f32_e32 v11, v99, v99
	v_fmac_f32_e32 v11, v100, v100
	v_fmac_f32_e32 v11, v101, v101
	v_fmac_f32_e32 v11, v102, v102
	v_fmac_f32_e32 v11, v103, v103
	v_fmac_f32_e32 v11, v104, v104
	v_fmac_f32_e32 v11, v105, v105
	v_fmac_f32_e32 v11, v106, v106
	v_fmac_f32_e32 v11, v107, v107
	v_fmac_f32_e32 v11, v108, v108
	v_fmac_f32_e32 v11, v109, v109
	v_fmac_f32_e32 v11, v110, v110
	v_fmac_f32_e32 v11, v111, v111
	ds_bpermute_b32 v12, v4, v10
	ds_bpermute_b32 v13, v4, v11
	s_waitcnt lgkmcnt(0)
	v_add_f32_e32 v10, v10, v12
	v_add_f32_e32 v11, v11, v13
	ds_bpermute_b32 v12, v5, v10
	ds_bpermute_b32 v13, v5, v11
	s_waitcnt lgkmcnt(0)
	v_add_f32_e32 v10, v10, v12
	v_add_f32_e32 v11, v11, v13
	ds_bpermute_b32 v12, v6, v10
	ds_bpermute_b32 v13, v6, v11
	s_waitcnt lgkmcnt(0)
	v_add_f32_e32 v10, v10, v12
	v_add_f32_e32 v11, v11, v13
	ds_bpermute_b32 v12, v7, v10
	ds_bpermute_b32 v13, v7, v11
	s_waitcnt lgkmcnt(0)
	v_add_f32_e32 v10, v10, v12
	v_add_f32_e32 v11, v11, v13
	ds_bpermute_b32 v12, v8, v10
	ds_bpermute_b32 v13, v8, v11
	s_waitcnt lgkmcnt(0)
	v_add_f32_e32 v10, v10, v12
	v_add_f32_e32 v11, v11, v13
	ds_bpermute_b32 v12, v9, v10
	ds_bpermute_b32 v13, v9, v11
	s_waitcnt lgkmcnt(0)
	v_add_f32_e32 v10, v10, v12
	v_add_f32_e32 v11, v11, v13
	v_fma_f32 v14, v10, s17, v3
	v_fma_f32 v15, v11, s17, v3
	v_rsq_f32_e32 v14, v14
	v_rsq_f32_e32 v15, v15
	s_nop 0
	v_mul_f32_e32 v64, v64, v14
	v_mul_f32_e32 v65, v65, v14
	v_mul_f32_e32 v66, v66, v14
	v_mul_f32_e32 v67, v67, v14
	v_mul_f32_e32 v68, v68, v14
	v_mul_f32_e32 v69, v69, v14
	v_mul_f32_e32 v70, v70, v14
	v_mul_f32_e32 v71, v71, v14
	v_mul_f32_e32 v72, v72, v14
	v_mul_f32_e32 v73, v73, v14
	v_mul_f32_e32 v74, v74, v14
	v_mul_f32_e32 v75, v75, v14
	v_mul_f32_e32 v76, v76, v14
	v_mul_f32_e32 v77, v77, v14
	v_mul_f32_e32 v78, v78, v14
	v_mul_f32_e32 v79, v79, v14
	v_fmac_f32_e32 v80, v64, v20
	v_fmac_f32_e32 v81, v65, v21
	v_fmac_f32_e32 v82, v66, v22
	v_fmac_f32_e32 v83, v67, v23
	v_fmac_f32_e32 v84, v68, v24
	v_fmac_f32_e32 v85, v69, v25
	v_fmac_f32_e32 v86, v70, v26
	v_fmac_f32_e32 v87, v71, v27
	v_fmac_f32_e32 v88, v72, v28
	v_fmac_f32_e32 v89, v73, v29
	v_fmac_f32_e32 v90, v74, v30
	v_fmac_f32_e32 v91, v75, v31
	v_fmac_f32_e32 v92, v76, v32
	v_fmac_f32_e32 v93, v77, v33
	v_fmac_f32_e32 v94, v78, v34
	v_fmac_f32_e32 v95, v79, v35
	global_store_dwordx4 v1, v[80:83], s[24:25] offset:0 nt
	global_store_dwordx4 v1, v[84:87], s[24:25] offset:1024 nt
	global_store_dwordx4 v1, v[88:91], s[24:25] offset:2048 nt
	global_store_dwordx4 v1, v[92:95], s[24:25] offset:3072 nt
	v_mul_f32_e32 v96, v96, v15
	v_mul_f32_e32 v97, v97, v15
	v_mul_f32_e32 v98, v98, v15
	v_mul_f32_e32 v99, v99, v15
	v_mul_f32_e32 v100, v100, v15
	v_mul_f32_e32 v101, v101, v15
	v_mul_f32_e32 v102, v102, v15
	v_mul_f32_e32 v103, v103, v15
	v_mul_f32_e32 v104, v104, v15
	v_mul_f32_e32 v105, v105, v15
	v_mul_f32_e32 v106, v106, v15
	v_mul_f32_e32 v107, v107, v15
	v_mul_f32_e32 v108, v108, v15
	v_mul_f32_e32 v109, v109, v15
	v_mul_f32_e32 v110, v110, v15
	v_mul_f32_e32 v111, v111, v15
	v_fmac_f32_e32 v112, v96, v20
	v_fmac_f32_e32 v113, v97, v21
	v_fmac_f32_e32 v114, v98, v22
	v_fmac_f32_e32 v115, v99, v23
	v_fmac_f32_e32 v116, v100, v24
	v_fmac_f32_e32 v117, v101, v25
	v_fmac_f32_e32 v118, v102, v26
	v_fmac_f32_e32 v119, v103, v27
	v_fmac_f32_e32 v120, v104, v28
	v_fmac_f32_e32 v121, v105, v29
	v_fmac_f32_e32 v122, v106, v30
	v_fmac_f32_e32 v123, v107, v31
	v_fmac_f32_e32 v124, v108, v32
	v_fmac_f32_e32 v125, v109, v33
	v_fmac_f32_e32 v126, v110, v34
	v_fmac_f32_e32 v127, v111, v35
	global_store_dwordx4 v1, v[112:115], s[32:33] offset:0 nt
	global_store_dwordx4 v1, v[116:119], s[32:33] offset:1024 nt
	global_store_dwordx4 v1, v[120:123], s[32:33] offset:2048 nt
	global_store_dwordx4 v1, v[124:127], s[32:33] offset:3072 nt
	v_mul_f32_e32 v10, v80, v80
	v_fmac_f32_e32 v10, v81, v81
	v_fmac_f32_e32 v10, v82, v82
	v_fmac_f32_e32 v10, v83, v83
	v_fmac_f32_e32 v10, v84, v84
	v_fmac_f32_e32 v10, v85, v85
	v_fmac_f32_e32 v10, v86, v86
	v_fmac_f32_e32 v10, v87, v87
	v_fmac_f32_e32 v10, v88, v88
	v_fmac_f32_e32 v10, v89, v89
	v_fmac_f32_e32 v10, v90, v90
	v_fmac_f32_e32 v10, v91, v91
	v_fmac_f32_e32 v10, v92, v92
	v_fmac_f32_e32 v10, v93, v93
	v_fmac_f32_e32 v10, v94, v94
	v_fmac_f32_e32 v10, v95, v95
	v_mul_f32_e32 v11, v112, v112
	v_fmac_f32_e32 v11, v113, v113
	v_fmac_f32_e32 v11, v114, v114
	v_fmac_f32_e32 v11, v115, v115
	v_fmac_f32_e32 v11, v116, v116
	v_fmac_f32_e32 v11, v117, v117
	v_fmac_f32_e32 v11, v118, v118
	v_fmac_f32_e32 v11, v119, v119
	v_fmac_f32_e32 v11, v120, v120
	v_fmac_f32_e32 v11, v121, v121
	v_fmac_f32_e32 v11, v122, v122
	v_fmac_f32_e32 v11, v123, v123
	v_fmac_f32_e32 v11, v124, v124
	v_fmac_f32_e32 v11, v125, v125
	v_fmac_f32_e32 v11, v126, v126
	v_fmac_f32_e32 v11, v127, v127
	ds_bpermute_b32 v12, v4, v10
	ds_bpermute_b32 v13, v4, v11
	s_waitcnt lgkmcnt(0)
	v_add_f32_e32 v10, v10, v12
	v_add_f32_e32 v11, v11, v13
	ds_bpermute_b32 v12, v5, v10
	ds_bpermute_b32 v13, v5, v11
	s_waitcnt lgkmcnt(0)
	v_add_f32_e32 v10, v10, v12
	v_add_f32_e32 v11, v11, v13
	ds_bpermute_b32 v12, v6, v10
	ds_bpermute_b32 v13, v6, v11
	s_waitcnt lgkmcnt(0)
	v_add_f32_e32 v10, v10, v12
	v_add_f32_e32 v11, v11, v13
	ds_bpermute_b32 v12, v7, v10
	ds_bpermute_b32 v13, v7, v11
	s_waitcnt lgkmcnt(0)
	v_add_f32_e32 v10, v10, v12
	v_add_f32_e32 v11, v11, v13
	ds_bpermute_b32 v12, v8, v10
	ds_bpermute_b32 v13, v8, v11
	s_waitcnt lgkmcnt(0)
	v_add_f32_e32 v10, v10, v12
	v_add_f32_e32 v11, v11, v13
	ds_bpermute_b32 v12, v9, v10
	ds_bpermute_b32 v13, v9, v11
	s_waitcnt lgkmcnt(0)
	v_add_f32_e32 v10, v10, v12
	v_add_f32_e32 v11, v11, v13
	v_fma_f32 v14, v10, s17, v3
	v_fma_f32 v15, v11, s17, v3
	v_rsq_f32_e32 v14, v14
	v_rsq_f32_e32 v15, v15
	s_nop 0
	v_mul_f32_e32 v64, v80, v14
	v_mul_f32_e32 v65, v81, v14
	v_mul_f32_e32 v66, v82, v14
	v_mul_f32_e32 v67, v83, v14
	v_mul_f32_e32 v68, v84, v14
	v_mul_f32_e32 v69, v85, v14
	v_mul_f32_e32 v70, v86, v14
	v_mul_f32_e32 v71, v87, v14
	v_mul_f32_e32 v72, v88, v14
	v_mul_f32_e32 v73, v89, v14
	v_mul_f32_e32 v74, v90, v14
	v_mul_f32_e32 v75, v91, v14
	v_mul_f32_e32 v76, v92, v14
	v_mul_f32_e32 v77, v93, v14
	v_mul_f32_e32 v78, v94, v14
	v_mul_f32_e32 v79, v95, v14
	v_mul_f32_e32 v64, v64, v36
	v_mul_f32_e32 v65, v65, v37
	v_mul_f32_e32 v66, v66, v38
	v_mul_f32_e32 v67, v67, v39
	v_mul_f32_e32 v68, v68, v40
	v_mul_f32_e32 v69, v69, v41
	v_mul_f32_e32 v70, v70, v42
	v_mul_f32_e32 v71, v71, v43
	v_mul_f32_e32 v72, v72, v44
	v_mul_f32_e32 v73, v73, v45
	v_mul_f32_e32 v74, v74, v46
	v_mul_f32_e32 v75, v75, v47
	v_mul_f32_e32 v76, v76, v48
	v_mul_f32_e32 v77, v77, v49
	v_mul_f32_e32 v78, v78, v50
	v_mul_f32_e32 v79, v79, v51
	v_cvt_pk_bf16_f32 v64, v64, v65
	v_cvt_pk_bf16_f32 v65, v66, v67
	v_cvt_pk_bf16_f32 v68, v68, v69
	v_cvt_pk_bf16_f32 v69, v70, v71
	v_cvt_pk_bf16_f32 v72, v72, v73
	v_cvt_pk_bf16_f32 v73, v74, v75
	v_cvt_pk_bf16_f32 v76, v76, v77
	v_cvt_pk_bf16_f32 v77, v78, v79
	global_store_dwordx2 v2, v[64:65], s[26:27] offset:0
	global_store_dwordx2 v2, v[68:69], s[26:27] offset:512
	global_store_dwordx2 v2, v[72:73], s[26:27] offset:1024
	global_store_dwordx2 v2, v[76:77], s[26:27] offset:1536
	v_mul_f32_e32 v96, v112, v15
	v_mul_f32_e32 v97, v113, v15
	v_mul_f32_e32 v98, v114, v15
	v_mul_f32_e32 v99, v115, v15
	v_mul_f32_e32 v100, v116, v15
	v_mul_f32_e32 v101, v117, v15
	v_mul_f32_e32 v102, v118, v15
	v_mul_f32_e32 v103, v119, v15
	v_mul_f32_e32 v104, v120, v15
	v_mul_f32_e32 v105, v121, v15
	v_mul_f32_e32 v106, v122, v15
	v_mul_f32_e32 v107, v123, v15
	v_mul_f32_e32 v108, v124, v15
	v_mul_f32_e32 v109, v125, v15
	v_mul_f32_e32 v110, v126, v15
	v_mul_f32_e32 v111, v127, v15
	v_mul_f32_e32 v96, v96, v36
	v_mul_f32_e32 v97, v97, v37
	v_mul_f32_e32 v98, v98, v38
	v_mul_f32_e32 v99, v99, v39
	v_mul_f32_e32 v100, v100, v40
	v_mul_f32_e32 v101, v101, v41
	v_mul_f32_e32 v102, v102, v42
	v_mul_f32_e32 v103, v103, v43
	v_mul_f32_e32 v104, v104, v44
	v_mul_f32_e32 v105, v105, v45
	v_mul_f32_e32 v106, v106, v46
	v_mul_f32_e32 v107, v107, v47
	v_mul_f32_e32 v108, v108, v48
	v_mul_f32_e32 v109, v109, v49
	v_mul_f32_e32 v110, v110, v50
	v_mul_f32_e32 v111, v111, v51
	v_cvt_pk_bf16_f32 v96, v96, v97
	v_cvt_pk_bf16_f32 v97, v98, v99
	v_cvt_pk_bf16_f32 v100, v100, v101
	v_cvt_pk_bf16_f32 v101, v102, v103
	v_cvt_pk_bf16_f32 v104, v104, v105
	v_cvt_pk_bf16_f32 v105, v106, v107
	v_cvt_pk_bf16_f32 v108, v108, v109
	v_cvt_pk_bf16_f32 v109, v110, v111
	global_store_dwordx2 v2, v[96:97], s[34:35] offset:0
	global_store_dwordx2 v2, v[100:101], s[34:35] offset:512
	global_store_dwordx2 v2, v[104:105], s[34:35] offset:1024
	global_store_dwordx2 v2, v[108:109], s[34:35] offset:1536
	s_add_u32 s53, s16, 0x2000
	s_lshl_b32 s18, s53, 12
	s_lshl_b32 s19, s53, 11
	s_add_u32 s20, s12, s18
	s_addc_u32 s21, s13, 0
	s_add_u32 s22, s6, s19
	s_addc_u32 s23, s7, 0
	s_add_u32 s22, s22, 0x5200000
	s_addc_u32 s23, s23, 0
	s_add_u32 s24, s4, s18
	s_addc_u32 s25, s5, 0
	s_add_u32 s26, s6, s19
	s_addc_u32 s27, s7, 0
	s_add_u32 s26, s26, 0x3100000
	s_addc_u32 s27, s27, 0
	global_load_dwordx2 v[66:67], v2, s[22:23] offset:0
	global_load_dwordx2 v[70:71], v2, s[22:23] offset:512
	global_load_dwordx2 v[74:75], v2, s[22:23] offset:1024
	global_load_dwordx2 v[78:79], v2, s[22:23] offset:1536
	global_load_dwordx4 v[80:83], v1, s[20:21] offset:0
	global_load_dwordx4 v[84:87], v1, s[20:21] offset:1024
	global_load_dwordx4 v[88:91], v1, s[20:21] offset:2048
	global_load_dwordx4 v[92:95], v1, s[20:21] offset:3072
	s_add_u32 s53, s16, 0x2800
	s_lshl_b32 s18, s53, 12
	s_lshl_b32 s19, s53, 11
	s_add_u32 s28, s12, s18
	s_addc_u32 s29, s13, 0
	s_add_u32 s30, s6, s19
	s_addc_u32 s31, s7, 0
	s_add_u32 s30, s30, 0x5200000
	s_addc_u32 s31, s31, 0
	s_add_u32 s32, s4, s18
	s_addc_u32 s33, s5, 0
	s_add_u32 s34, s6, s19
	s_addc_u32 s35, s7, 0
	s_add_u32 s34, s34, 0x3100000
	s_addc_u32 s35, s35, 0
	global_load_dwordx2 v[98:99], v2, s[30:31] offset:0
	global_load_dwordx2 v[102:103], v2, s[30:31] offset:512
	global_load_dwordx2 v[106:107], v2, s[30:31] offset:1024
	global_load_dwordx2 v[110:111], v2, s[30:31] offset:1536
	global_load_dwordx4 v[112:115], v1, s[28:29] offset:0
	global_load_dwordx4 v[116:119], v1, s[28:29] offset:1024
	global_load_dwordx4 v[120:123], v1, s[28:29] offset:2048
	global_load_dwordx4 v[124:127], v1, s[28:29] offset:3072
	s_waitcnt vmcnt(32)
	v_lshlrev_b32_e32 v128, 16, v130
	v_and_b32_e32 v129, 0xffff0000, v130
	v_lshlrev_b32_e32 v130, 16, v131
	v_and_b32_e32 v131, 0xffff0000, v131
	v_lshlrev_b32_e32 v132, 16, v134
	v_and_b32_e32 v133, 0xffff0000, v134
	v_lshlrev_b32_e32 v134, 16, v135
	v_and_b32_e32 v135, 0xffff0000, v135
	v_lshlrev_b32_e32 v136, 16, v138
	v_and_b32_e32 v137, 0xffff0000, v138
	v_lshlrev_b32_e32 v138, 16, v139
	v_and_b32_e32 v139, 0xffff0000, v139
	v_lshlrev_b32_e32 v140, 16, v142
	v_and_b32_e32 v141, 0xffff0000, v142
	v_lshlrev_b32_e32 v142, 16, v143
	v_and_b32_e32 v143, 0xffff0000, v143
	v_lshlrev_b32_e32 v160, 16, v162
	v_and_b32_e32 v161, 0xffff0000, v162
	v_lshlrev_b32_e32 v162, 16, v163
	v_and_b32_e32 v163, 0xffff0000, v163
	v_lshlrev_b32_e32 v164, 16, v166
	v_and_b32_e32 v165, 0xffff0000, v166
	v_lshlrev_b32_e32 v166, 16, v167
	v_and_b32_e32 v167, 0xffff0000, v167
	v_lshlrev_b32_e32 v168, 16, v170
	v_and_b32_e32 v169, 0xffff0000, v170
	v_lshlrev_b32_e32 v170, 16, v171
	v_and_b32_e32 v171, 0xffff0000, v171
	v_lshlrev_b32_e32 v172, 16, v174
	v_and_b32_e32 v173, 0xffff0000, v174
	v_lshlrev_b32_e32 v174, 16, v175
	v_and_b32_e32 v175, 0xffff0000, v175
	v_mul_f32_e32 v10, v128, v128
	v_fmac_f32_e32 v10, v129, v129
	v_fmac_f32_e32 v10, v130, v130
	v_fmac_f32_e32 v10, v131, v131
	v_fmac_f32_e32 v10, v132, v132
	v_fmac_f32_e32 v10, v133, v133
	v_fmac_f32_e32 v10, v134, v134
	v_fmac_f32_e32 v10, v135, v135
	v_fmac_f32_e32 v10, v136, v136
	v_fmac_f32_e32 v10, v137, v137
	v_fmac_f32_e32 v10, v138, v138
	v_fmac_f32_e32 v10, v139, v139
	v_fmac_f32_e32 v10, v140, v140
	v_fmac_f32_e32 v10, v141, v141
	v_fmac_f32_e32 v10, v142, v142
	v_fmac_f32_e32 v10, v143, v143
	v_mul_f32_e32 v11, v160, v160
	v_fmac_f32_e32 v11, v161, v161
	v_fmac_f32_e32 v11, v162, v162
	v_fmac_f32_e32 v11, v163, v163
	v_fmac_f32_e32 v11, v164, v164
	v_fmac_f32_e32 v11, v165, v165
	v_fmac_f32_e32 v11, v166, v166
	v_fmac_f32_e32 v11, v167, v167
	v_fmac_f32_e32 v11, v168, v168
	v_fmac_f32_e32 v11, v169, v169
	v_fmac_f32_e32 v11, v170, v170
	v_fmac_f32_e32 v11, v171, v171
	v_fmac_f32_e32 v11, v172, v172
	v_fmac_f32_e32 v11, v173, v173
	v_fmac_f32_e32 v11, v174, v174
	v_fmac_f32_e32 v11, v175, v175
	ds_bpermute_b32 v12, v4, v10
	ds_bpermute_b32 v13, v4, v11
	s_waitcnt lgkmcnt(0)
	v_add_f32_e32 v10, v10, v12
	v_add_f32_e32 v11, v11, v13
	ds_bpermute_b32 v12, v5, v10
	ds_bpermute_b32 v13, v5, v11
	s_waitcnt lgkmcnt(0)
	v_add_f32_e32 v10, v10, v12
	v_add_f32_e32 v11, v11, v13
	ds_bpermute_b32 v12, v6, v10
	ds_bpermute_b32 v13, v6, v11
	s_waitcnt lgkmcnt(0)
	v_add_f32_e32 v10, v10, v12
	v_add_f32_e32 v11, v11, v13
	ds_bpermute_b32 v12, v7, v10
	ds_bpermute_b32 v13, v7, v11
	s_waitcnt lgkmcnt(0)
	v_add_f32_e32 v10, v10, v12
	v_add_f32_e32 v11, v11, v13
	ds_bpermute_b32 v12, v8, v10
	ds_bpermute_b32 v13, v8, v11
	s_waitcnt lgkmcnt(0)
	v_add_f32_e32 v10, v10, v12
	v_add_f32_e32 v11, v11, v13
	ds_bpermute_b32 v12, v9, v10
	ds_bpermute_b32 v13, v9, v11
	s_waitcnt lgkmcnt(0)
	v_add_f32_e32 v10, v10, v12
	v_add_f32_e32 v11, v11, v13
	v_fma_f32 v14, v10, s17, v3
	v_fma_f32 v15, v11, s17, v3
	v_rsq_f32_e32 v14, v14
	v_rsq_f32_e32 v15, v15
	s_nop 0
	v_mul_f32_e32 v128, v128, v14
	v_mul_f32_e32 v129, v129, v14
	v_mul_f32_e32 v130, v130, v14
	v_mul_f32_e32 v131, v131, v14
	v_mul_f32_e32 v132, v132, v14
	v_mul_f32_e32 v133, v133, v14
	v_mul_f32_e32 v134, v134, v14
	v_mul_f32_e32 v135, v135, v14
	v_mul_f32_e32 v136, v136, v14
	v_mul_f32_e32 v137, v137, v14
	v_mul_f32_e32 v138, v138, v14
	v_mul_f32_e32 v139, v139, v14
	v_mul_f32_e32 v140, v140, v14
	v_mul_f32_e32 v141, v141, v14
	v_mul_f32_e32 v142, v142, v14
	v_mul_f32_e32 v143, v143, v14
	v_fmac_f32_e32 v144, v128, v20
	v_fmac_f32_e32 v145, v129, v21
	v_fmac_f32_e32 v146, v130, v22
	v_fmac_f32_e32 v147, v131, v23
	v_fmac_f32_e32 v148, v132, v24
	v_fmac_f32_e32 v149, v133, v25
	v_fmac_f32_e32 v150, v134, v26
	v_fmac_f32_e32 v151, v135, v27
	v_fmac_f32_e32 v152, v136, v28
	v_fmac_f32_e32 v153, v137, v29
	v_fmac_f32_e32 v154, v138, v30
	v_fmac_f32_e32 v155, v139, v31
	v_fmac_f32_e32 v156, v140, v32
	v_fmac_f32_e32 v157, v141, v33
	v_fmac_f32_e32 v158, v142, v34
	v_fmac_f32_e32 v159, v143, v35
	global_store_dwordx4 v1, v[144:147], s[40:41] offset:0 nt
	global_store_dwordx4 v1, v[148:151], s[40:41] offset:1024 nt
	global_store_dwordx4 v1, v[152:155], s[40:41] offset:2048 nt
	global_store_dwordx4 v1, v[156:159], s[40:41] offset:3072 nt
	v_mul_f32_e32 v160, v160, v15
	v_mul_f32_e32 v161, v161, v15
	v_mul_f32_e32 v162, v162, v15
	v_mul_f32_e32 v163, v163, v15
	v_mul_f32_e32 v164, v164, v15
	v_mul_f32_e32 v165, v165, v15
	v_mul_f32_e32 v166, v166, v15
	v_mul_f32_e32 v167, v167, v15
	v_mul_f32_e32 v168, v168, v15
	v_mul_f32_e32 v169, v169, v15
	v_mul_f32_e32 v170, v170, v15
	v_mul_f32_e32 v171, v171, v15
	v_mul_f32_e32 v172, v172, v15
	v_mul_f32_e32 v173, v173, v15
	v_mul_f32_e32 v174, v174, v15
	v_mul_f32_e32 v175, v175, v15
	v_fmac_f32_e32 v176, v160, v20
	v_fmac_f32_e32 v177, v161, v21
	v_fmac_f32_e32 v178, v162, v22
	v_fmac_f32_e32 v179, v163, v23
	v_fmac_f32_e32 v180, v164, v24
	v_fmac_f32_e32 v181, v165, v25
	v_fmac_f32_e32 v182, v166, v26
	v_fmac_f32_e32 v183, v167, v27
	v_fmac_f32_e32 v184, v168, v28
	v_fmac_f32_e32 v185, v169, v29
	v_fmac_f32_e32 v186, v170, v30
	v_fmac_f32_e32 v187, v171, v31
	v_fmac_f32_e32 v188, v172, v32
	v_fmac_f32_e32 v189, v173, v33
	v_fmac_f32_e32 v190, v174, v34
	v_fmac_f32_e32 v191, v175, v35
	global_store_dwordx4 v1, v[176:179], s[48:49] offset:0 nt
	global_store_dwordx4 v1, v[180:183], s[48:49] offset:1024 nt
	global_store_dwordx4 v1, v[184:187], s[48:49] offset:2048 nt
	global_store_dwordx4 v1, v[188:191], s[48:49] offset:3072 nt
	v_mul_f32_e32 v10, v144, v144
	v_fmac_f32_e32 v10, v145, v145
	v_fmac_f32_e32 v10, v146, v146
	v_fmac_f32_e32 v10, v147, v147
	v_fmac_f32_e32 v10, v148, v148
	v_fmac_f32_e32 v10, v149, v149
	v_fmac_f32_e32 v10, v150, v150
	v_fmac_f32_e32 v10, v151, v151
	v_fmac_f32_e32 v10, v152, v152
	v_fmac_f32_e32 v10, v153, v153
	v_fmac_f32_e32 v10, v154, v154
	v_fmac_f32_e32 v10, v155, v155
	v_fmac_f32_e32 v10, v156, v156
	v_fmac_f32_e32 v10, v157, v157
	v_fmac_f32_e32 v10, v158, v158
	v_fmac_f32_e32 v10, v159, v159
	v_mul_f32_e32 v11, v176, v176
	v_fmac_f32_e32 v11, v177, v177
	v_fmac_f32_e32 v11, v178, v178
	v_fmac_f32_e32 v11, v179, v179
	v_fmac_f32_e32 v11, v180, v180
	v_fmac_f32_e32 v11, v181, v181
	v_fmac_f32_e32 v11, v182, v182
	v_fmac_f32_e32 v11, v183, v183
	v_fmac_f32_e32 v11, v184, v184
	v_fmac_f32_e32 v11, v185, v185
	v_fmac_f32_e32 v11, v186, v186
	v_fmac_f32_e32 v11, v187, v187
	v_fmac_f32_e32 v11, v188, v188
	v_fmac_f32_e32 v11, v189, v189
	v_fmac_f32_e32 v11, v190, v190
	v_fmac_f32_e32 v11, v191, v191
	ds_bpermute_b32 v12, v4, v10
	ds_bpermute_b32 v13, v4, v11
	s_waitcnt lgkmcnt(0)
	v_add_f32_e32 v10, v10, v12
	v_add_f32_e32 v11, v11, v13
	ds_bpermute_b32 v12, v5, v10
	ds_bpermute_b32 v13, v5, v11
	s_waitcnt lgkmcnt(0)
	v_add_f32_e32 v10, v10, v12
	v_add_f32_e32 v11, v11, v13
	ds_bpermute_b32 v12, v6, v10
	ds_bpermute_b32 v13, v6, v11
	s_waitcnt lgkmcnt(0)
	v_add_f32_e32 v10, v10, v12
	v_add_f32_e32 v11, v11, v13
	ds_bpermute_b32 v12, v7, v10
	ds_bpermute_b32 v13, v7, v11
	s_waitcnt lgkmcnt(0)
	v_add_f32_e32 v10, v10, v12
	v_add_f32_e32 v11, v11, v13
	ds_bpermute_b32 v12, v8, v10
	ds_bpermute_b32 v13, v8, v11
	s_waitcnt lgkmcnt(0)
	v_add_f32_e32 v10, v10, v12
	v_add_f32_e32 v11, v11, v13
	ds_bpermute_b32 v12, v9, v10
	ds_bpermute_b32 v13, v9, v11
	s_waitcnt lgkmcnt(0)
	v_add_f32_e32 v10, v10, v12
	v_add_f32_e32 v11, v11, v13
	v_fma_f32 v14, v10, s17, v3
	v_fma_f32 v15, v11, s17, v3
	v_rsq_f32_e32 v14, v14
	v_rsq_f32_e32 v15, v15
	s_nop 0
	v_mul_f32_e32 v128, v144, v14
	v_mul_f32_e32 v129, v145, v14
	v_mul_f32_e32 v130, v146, v14
	v_mul_f32_e32 v131, v147, v14
	v_mul_f32_e32 v132, v148, v14
	v_mul_f32_e32 v133, v149, v14
	v_mul_f32_e32 v134, v150, v14
	v_mul_f32_e32 v135, v151, v14
	v_mul_f32_e32 v136, v152, v14
	v_mul_f32_e32 v137, v153, v14
	v_mul_f32_e32 v138, v154, v14
	v_mul_f32_e32 v139, v155, v14
	v_mul_f32_e32 v140, v156, v14
	v_mul_f32_e32 v141, v157, v14
	v_mul_f32_e32 v142, v158, v14
	v_mul_f32_e32 v143, v159, v14
	v_mul_f32_e32 v128, v128, v36
	v_mul_f32_e32 v129, v129, v37
	v_mul_f32_e32 v130, v130, v38
	v_mul_f32_e32 v131, v131, v39
	v_mul_f32_e32 v132, v132, v40
	v_mul_f32_e32 v133, v133, v41
	v_mul_f32_e32 v134, v134, v42
	v_mul_f32_e32 v135, v135, v43
	v_mul_f32_e32 v136, v136, v44
	v_mul_f32_e32 v137, v137, v45
	v_mul_f32_e32 v138, v138, v46
	v_mul_f32_e32 v139, v139, v47
	v_mul_f32_e32 v140, v140, v48
	v_mul_f32_e32 v141, v141, v49
	v_mul_f32_e32 v142, v142, v50
	v_mul_f32_e32 v143, v143, v51
	v_cvt_pk_bf16_f32 v128, v128, v129
	v_cvt_pk_bf16_f32 v129, v130, v131
	v_cvt_pk_bf16_f32 v132, v132, v133
	v_cvt_pk_bf16_f32 v133, v134, v135
	v_cvt_pk_bf16_f32 v136, v136, v137
	v_cvt_pk_bf16_f32 v137, v138, v139
	v_cvt_pk_bf16_f32 v140, v140, v141
	v_cvt_pk_bf16_f32 v141, v142, v143
	global_store_dwordx2 v2, v[128:129], s[42:43] offset:0
	global_store_dwordx2 v2, v[132:133], s[42:43] offset:512
	global_store_dwordx2 v2, v[136:137], s[42:43] offset:1024
	global_store_dwordx2 v2, v[140:141], s[42:43] offset:1536
	v_mul_f32_e32 v160, v176, v15
	v_mul_f32_e32 v161, v177, v15
	v_mul_f32_e32 v162, v178, v15
	v_mul_f32_e32 v163, v179, v15
	v_mul_f32_e32 v164, v180, v15
	v_mul_f32_e32 v165, v181, v15
	v_mul_f32_e32 v166, v182, v15
	v_mul_f32_e32 v167, v183, v15
	v_mul_f32_e32 v168, v184, v15
	v_mul_f32_e32 v169, v185, v15
	v_mul_f32_e32 v170, v186, v15
	v_mul_f32_e32 v171, v187, v15
	v_mul_f32_e32 v172, v188, v15
	v_mul_f32_e32 v173, v189, v15
	v_mul_f32_e32 v174, v190, v15
	v_mul_f32_e32 v175, v191, v15
	v_mul_f32_e32 v160, v160, v36
	v_mul_f32_e32 v161, v161, v37
	v_mul_f32_e32 v162, v162, v38
	v_mul_f32_e32 v163, v163, v39
	v_mul_f32_e32 v164, v164, v40
	v_mul_f32_e32 v165, v165, v41
	v_mul_f32_e32 v166, v166, v42
	v_mul_f32_e32 v167, v167, v43
	v_mul_f32_e32 v168, v168, v44
	v_mul_f32_e32 v169, v169, v45
	v_mul_f32_e32 v170, v170, v46
	v_mul_f32_e32 v171, v171, v47
	v_mul_f32_e32 v172, v172, v48
	v_mul_f32_e32 v173, v173, v49
	v_mul_f32_e32 v174, v174, v50
	v_mul_f32_e32 v175, v175, v51
	v_cvt_pk_bf16_f32 v160, v160, v161
	v_cvt_pk_bf16_f32 v161, v162, v163
	v_cvt_pk_bf16_f32 v164, v164, v165
	v_cvt_pk_bf16_f32 v165, v166, v167
	v_cvt_pk_bf16_f32 v168, v168, v169
	v_cvt_pk_bf16_f32 v169, v170, v171
	v_cvt_pk_bf16_f32 v172, v172, v173
	v_cvt_pk_bf16_f32 v173, v174, v175
	global_store_dwordx2 v2, v[160:161], s[50:51] offset:0
	global_store_dwordx2 v2, v[164:165], s[50:51] offset:512
	global_store_dwordx2 v2, v[168:169], s[50:51] offset:1024
	global_store_dwordx2 v2, v[172:173], s[50:51] offset:1536
	s_add_u32 s53, s16, 0x3000
	s_lshl_b32 s18, s53, 12
	s_lshl_b32 s19, s53, 11
	s_add_u32 s36, s12, s18
	s_addc_u32 s37, s13, 0
	s_add_u32 s38, s6, s19
	s_addc_u32 s39, s7, 0
	s_add_u32 s38, s38, 0x5200000
	s_addc_u32 s39, s39, 0
	s_add_u32 s40, s4, s18
	s_addc_u32 s41, s5, 0
	s_add_u32 s42, s6, s19
	s_addc_u32 s43, s7, 0
	s_add_u32 s42, s42, 0x3100000
	s_addc_u32 s43, s43, 0
	global_load_dwordx2 v[130:131], v2, s[38:39] offset:0
	global_load_dwordx2 v[134:135], v2, s[38:39] offset:512
	global_load_dwordx2 v[138:139], v2, s[38:39] offset:1024
	global_load_dwordx2 v[142:143], v2, s[38:39] offset:1536
	global_load_dwordx4 v[144:147], v1, s[36:37] offset:0
	global_load_dwordx4 v[148:151], v1, s[36:37] offset:1024
	global_load_dwordx4 v[152:155], v1, s[36:37] offset:2048
	global_load_dwordx4 v[156:159], v1, s[36:37] offset:3072
	s_add_u32 s53, s16, 0x3800
	s_lshl_b32 s18, s53, 12
	s_lshl_b32 s19, s53, 11
	s_add_u32 s44, s12, s18
	s_addc_u32 s45, s13, 0
	s_add_u32 s46, s6, s19
	s_addc_u32 s47, s7, 0
	s_add_u32 s46, s46, 0x5200000
	s_addc_u32 s47, s47, 0
	s_add_u32 s48, s4, s18
	s_addc_u32 s49, s5, 0
	s_add_u32 s50, s6, s19
	s_addc_u32 s51, s7, 0
	s_add_u32 s50, s50, 0x3100000
	s_addc_u32 s51, s51, 0
	global_load_dwordx2 v[162:163], v2, s[46:47] offset:0
	global_load_dwordx2 v[166:167], v2, s[46:47] offset:512
	global_load_dwordx2 v[170:171], v2, s[46:47] offset:1024
	global_load_dwordx2 v[174:175], v2, s[46:47] offset:1536
	global_load_dwordx4 v[176:179], v1, s[44:45] offset:0
	global_load_dwordx4 v[180:183], v1, s[44:45] offset:1024
	global_load_dwordx4 v[184:187], v1, s[44:45] offset:2048
	global_load_dwordx4 v[188:191], v1, s[44:45] offset:3072
	s_waitcnt vmcnt(32)
	v_lshlrev_b32_e32 v64, 16, v66
	v_and_b32_e32 v65, 0xffff0000, v66
	v_lshlrev_b32_e32 v66, 16, v67
	v_and_b32_e32 v67, 0xffff0000, v67
	v_lshlrev_b32_e32 v68, 16, v70
	v_and_b32_e32 v69, 0xffff0000, v70
	v_lshlrev_b32_e32 v70, 16, v71
	v_and_b32_e32 v71, 0xffff0000, v71
	v_lshlrev_b32_e32 v72, 16, v74
	v_and_b32_e32 v73, 0xffff0000, v74
	v_lshlrev_b32_e32 v74, 16, v75
	v_and_b32_e32 v75, 0xffff0000, v75
	v_lshlrev_b32_e32 v76, 16, v78
	v_and_b32_e32 v77, 0xffff0000, v78
	v_lshlrev_b32_e32 v78, 16, v79
	v_and_b32_e32 v79, 0xffff0000, v79
	v_lshlrev_b32_e32 v96, 16, v98
	v_and_b32_e32 v97, 0xffff0000, v98
	v_lshlrev_b32_e32 v98, 16, v99
	v_and_b32_e32 v99, 0xffff0000, v99
	v_lshlrev_b32_e32 v100, 16, v102
	v_and_b32_e32 v101, 0xffff0000, v102
	v_lshlrev_b32_e32 v102, 16, v103
	v_and_b32_e32 v103, 0xffff0000, v103
	v_lshlrev_b32_e32 v104, 16, v106
	v_and_b32_e32 v105, 0xffff0000, v106
	v_lshlrev_b32_e32 v106, 16, v107
	v_and_b32_e32 v107, 0xffff0000, v107
	v_lshlrev_b32_e32 v108, 16, v110
	v_and_b32_e32 v109, 0xffff0000, v110
	v_lshlrev_b32_e32 v110, 16, v111
	v_and_b32_e32 v111, 0xffff0000, v111
	v_mul_f32_e32 v10, v64, v64
	v_fmac_f32_e32 v10, v65, v65
	v_fmac_f32_e32 v10, v66, v66
	v_fmac_f32_e32 v10, v67, v67
	v_fmac_f32_e32 v10, v68, v68
	v_fmac_f32_e32 v10, v69, v69
	v_fmac_f32_e32 v10, v70, v70
	v_fmac_f32_e32 v10, v71, v71
	v_fmac_f32_e32 v10, v72, v72
	v_fmac_f32_e32 v10, v73, v73
	v_fmac_f32_e32 v10, v74, v74
	v_fmac_f32_e32 v10, v75, v75
	v_fmac_f32_e32 v10, v76, v76
	v_fmac_f32_e32 v10, v77, v77
	v_fmac_f32_e32 v10, v78, v78
	v_fmac_f32_e32 v10, v79, v79
	v_mul_f32_e32 v11, v96, v96
	v_fmac_f32_e32 v11, v97, v97
	v_fmac_f32_e32 v11, v98, v98
	v_fmac_f32_e32 v11, v99, v99
	v_fmac_f32_e32 v11, v100, v100
	v_fmac_f32_e32 v11, v101, v101
	v_fmac_f32_e32 v11, v102, v102
	v_fmac_f32_e32 v11, v103, v103
	v_fmac_f32_e32 v11, v104, v104
	v_fmac_f32_e32 v11, v105, v105
	v_fmac_f32_e32 v11, v106, v106
	v_fmac_f32_e32 v11, v107, v107
	v_fmac_f32_e32 v11, v108, v108
	v_fmac_f32_e32 v11, v109, v109
	v_fmac_f32_e32 v11, v110, v110
	v_fmac_f32_e32 v11, v111, v111
	ds_bpermute_b32 v12, v4, v10
	ds_bpermute_b32 v13, v4, v11
	s_waitcnt lgkmcnt(0)
	v_add_f32_e32 v10, v10, v12
	v_add_f32_e32 v11, v11, v13
	ds_bpermute_b32 v12, v5, v10
	ds_bpermute_b32 v13, v5, v11
	s_waitcnt lgkmcnt(0)
	v_add_f32_e32 v10, v10, v12
	v_add_f32_e32 v11, v11, v13
	ds_bpermute_b32 v12, v6, v10
	ds_bpermute_b32 v13, v6, v11
	s_waitcnt lgkmcnt(0)
	v_add_f32_e32 v10, v10, v12
	v_add_f32_e32 v11, v11, v13
	ds_bpermute_b32 v12, v7, v10
	ds_bpermute_b32 v13, v7, v11
	s_waitcnt lgkmcnt(0)
	v_add_f32_e32 v10, v10, v12
	v_add_f32_e32 v11, v11, v13
	ds_bpermute_b32 v12, v8, v10
	ds_bpermute_b32 v13, v8, v11
	s_waitcnt lgkmcnt(0)
	v_add_f32_e32 v10, v10, v12
	v_add_f32_e32 v11, v11, v13
	ds_bpermute_b32 v12, v9, v10
	ds_bpermute_b32 v13, v9, v11
	s_waitcnt lgkmcnt(0)
	v_add_f32_e32 v10, v10, v12
	v_add_f32_e32 v11, v11, v13
	v_fma_f32 v14, v10, s17, v3
	v_fma_f32 v15, v11, s17, v3
	v_rsq_f32_e32 v14, v14
	v_rsq_f32_e32 v15, v15
	s_nop 0
	v_mul_f32_e32 v64, v64, v14
	v_mul_f32_e32 v65, v65, v14
	v_mul_f32_e32 v66, v66, v14
	v_mul_f32_e32 v67, v67, v14
	v_mul_f32_e32 v68, v68, v14
	v_mul_f32_e32 v69, v69, v14
	v_mul_f32_e32 v70, v70, v14
	v_mul_f32_e32 v71, v71, v14
	v_mul_f32_e32 v72, v72, v14
	v_mul_f32_e32 v73, v73, v14
	v_mul_f32_e32 v74, v74, v14
	v_mul_f32_e32 v75, v75, v14
	v_mul_f32_e32 v76, v76, v14
	v_mul_f32_e32 v77, v77, v14
	v_mul_f32_e32 v78, v78, v14
	v_mul_f32_e32 v79, v79, v14
	v_fmac_f32_e32 v80, v64, v20
	v_fmac_f32_e32 v81, v65, v21
	v_fmac_f32_e32 v82, v66, v22
	v_fmac_f32_e32 v83, v67, v23
	v_fmac_f32_e32 v84, v68, v24
	v_fmac_f32_e32 v85, v69, v25
	v_fmac_f32_e32 v86, v70, v26
	v_fmac_f32_e32 v87, v71, v27
	v_fmac_f32_e32 v88, v72, v28
	v_fmac_f32_e32 v89, v73, v29
	v_fmac_f32_e32 v90, v74, v30
	v_fmac_f32_e32 v91, v75, v31
	v_fmac_f32_e32 v92, v76, v32
	v_fmac_f32_e32 v93, v77, v33
	v_fmac_f32_e32 v94, v78, v34
	v_fmac_f32_e32 v95, v79, v35
	global_store_dwordx4 v1, v[80:83], s[24:25] offset:0 nt
	global_store_dwordx4 v1, v[84:87], s[24:25] offset:1024 nt
	global_store_dwordx4 v1, v[88:91], s[24:25] offset:2048 nt
	global_store_dwordx4 v1, v[92:95], s[24:25] offset:3072 nt
	v_mul_f32_e32 v96, v96, v15
	v_mul_f32_e32 v97, v97, v15
	v_mul_f32_e32 v98, v98, v15
	v_mul_f32_e32 v99, v99, v15
	v_mul_f32_e32 v100, v100, v15
	v_mul_f32_e32 v101, v101, v15
	v_mul_f32_e32 v102, v102, v15
	v_mul_f32_e32 v103, v103, v15
	v_mul_f32_e32 v104, v104, v15
	v_mul_f32_e32 v105, v105, v15
	v_mul_f32_e32 v106, v106, v15
	v_mul_f32_e32 v107, v107, v15
	v_mul_f32_e32 v108, v108, v15
	v_mul_f32_e32 v109, v109, v15
	v_mul_f32_e32 v110, v110, v15
	v_mul_f32_e32 v111, v111, v15
	v_fmac_f32_e32 v112, v96, v20
	v_fmac_f32_e32 v113, v97, v21
	v_fmac_f32_e32 v114, v98, v22
	v_fmac_f32_e32 v115, v99, v23
	v_fmac_f32_e32 v116, v100, v24
	v_fmac_f32_e32 v117, v101, v25
	v_fmac_f32_e32 v118, v102, v26
	v_fmac_f32_e32 v119, v103, v27
	v_fmac_f32_e32 v120, v104, v28
	v_fmac_f32_e32 v121, v105, v29
	v_fmac_f32_e32 v122, v106, v30
	v_fmac_f32_e32 v123, v107, v31
	v_fmac_f32_e32 v124, v108, v32
	v_fmac_f32_e32 v125, v109, v33
	v_fmac_f32_e32 v126, v110, v34
	v_fmac_f32_e32 v127, v111, v35
	global_store_dwordx4 v1, v[112:115], s[32:33] offset:0 nt
	global_store_dwordx4 v1, v[116:119], s[32:33] offset:1024 nt
	global_store_dwordx4 v1, v[120:123], s[32:33] offset:2048 nt
	global_store_dwordx4 v1, v[124:127], s[32:33] offset:3072 nt
	v_mul_f32_e32 v10, v80, v80
	v_fmac_f32_e32 v10, v81, v81
	v_fmac_f32_e32 v10, v82, v82
	v_fmac_f32_e32 v10, v83, v83
	v_fmac_f32_e32 v10, v84, v84
	v_fmac_f32_e32 v10, v85, v85
	v_fmac_f32_e32 v10, v86, v86
	v_fmac_f32_e32 v10, v87, v87
	v_fmac_f32_e32 v10, v88, v88
	v_fmac_f32_e32 v10, v89, v89
	v_fmac_f32_e32 v10, v90, v90
	v_fmac_f32_e32 v10, v91, v91
	v_fmac_f32_e32 v10, v92, v92
	v_fmac_f32_e32 v10, v93, v93
	v_fmac_f32_e32 v10, v94, v94
	v_fmac_f32_e32 v10, v95, v95
	v_mul_f32_e32 v11, v112, v112
	v_fmac_f32_e32 v11, v113, v113
	v_fmac_f32_e32 v11, v114, v114
	v_fmac_f32_e32 v11, v115, v115
	v_fmac_f32_e32 v11, v116, v116
	v_fmac_f32_e32 v11, v117, v117
	v_fmac_f32_e32 v11, v118, v118
	v_fmac_f32_e32 v11, v119, v119
	v_fmac_f32_e32 v11, v120, v120
	v_fmac_f32_e32 v11, v121, v121
	v_fmac_f32_e32 v11, v122, v122
	v_fmac_f32_e32 v11, v123, v123
	v_fmac_f32_e32 v11, v124, v124
	v_fmac_f32_e32 v11, v125, v125
	v_fmac_f32_e32 v11, v126, v126
	v_fmac_f32_e32 v11, v127, v127
	ds_bpermute_b32 v12, v4, v10
	ds_bpermute_b32 v13, v4, v11
	s_waitcnt lgkmcnt(0)
	v_add_f32_e32 v10, v10, v12
	v_add_f32_e32 v11, v11, v13
	ds_bpermute_b32 v12, v5, v10
	ds_bpermute_b32 v13, v5, v11
	s_waitcnt lgkmcnt(0)
	v_add_f32_e32 v10, v10, v12
	v_add_f32_e32 v11, v11, v13
	ds_bpermute_b32 v12, v6, v10
	ds_bpermute_b32 v13, v6, v11
	s_waitcnt lgkmcnt(0)
	v_add_f32_e32 v10, v10, v12
	v_add_f32_e32 v11, v11, v13
	ds_bpermute_b32 v12, v7, v10
	ds_bpermute_b32 v13, v7, v11
	s_waitcnt lgkmcnt(0)
	v_add_f32_e32 v10, v10, v12
	v_add_f32_e32 v11, v11, v13
	ds_bpermute_b32 v12, v8, v10
	ds_bpermute_b32 v13, v8, v11
	s_waitcnt lgkmcnt(0)
	v_add_f32_e32 v10, v10, v12
	v_add_f32_e32 v11, v11, v13
	ds_bpermute_b32 v12, v9, v10
	ds_bpermute_b32 v13, v9, v11
	s_waitcnt lgkmcnt(0)
	v_add_f32_e32 v10, v10, v12
	v_add_f32_e32 v11, v11, v13
	v_fma_f32 v14, v10, s17, v3
	v_fma_f32 v15, v11, s17, v3
	v_rsq_f32_e32 v14, v14
	v_rsq_f32_e32 v15, v15
	s_nop 0
	v_mul_f32_e32 v64, v80, v14
	v_mul_f32_e32 v65, v81, v14
	v_mul_f32_e32 v66, v82, v14
	v_mul_f32_e32 v67, v83, v14
	v_mul_f32_e32 v68, v84, v14
	v_mul_f32_e32 v69, v85, v14
	v_mul_f32_e32 v70, v86, v14
	v_mul_f32_e32 v71, v87, v14
	v_mul_f32_e32 v72, v88, v14
	v_mul_f32_e32 v73, v89, v14
	v_mul_f32_e32 v74, v90, v14
	v_mul_f32_e32 v75, v91, v14
	v_mul_f32_e32 v76, v92, v14
	v_mul_f32_e32 v77, v93, v14
	v_mul_f32_e32 v78, v94, v14
	v_mul_f32_e32 v79, v95, v14
	v_mul_f32_e32 v64, v64, v36
	v_mul_f32_e32 v65, v65, v37
	v_mul_f32_e32 v66, v66, v38
	v_mul_f32_e32 v67, v67, v39
	v_mul_f32_e32 v68, v68, v40
	v_mul_f32_e32 v69, v69, v41
	v_mul_f32_e32 v70, v70, v42
	v_mul_f32_e32 v71, v71, v43
	v_mul_f32_e32 v72, v72, v44
	v_mul_f32_e32 v73, v73, v45
	v_mul_f32_e32 v74, v74, v46
	v_mul_f32_e32 v75, v75, v47
	v_mul_f32_e32 v76, v76, v48
	v_mul_f32_e32 v77, v77, v49
	v_mul_f32_e32 v78, v78, v50
	v_mul_f32_e32 v79, v79, v51
	v_cvt_pk_bf16_f32 v64, v64, v65
	v_cvt_pk_bf16_f32 v65, v66, v67
	v_cvt_pk_bf16_f32 v68, v68, v69
	v_cvt_pk_bf16_f32 v69, v70, v71
	v_cvt_pk_bf16_f32 v72, v72, v73
	v_cvt_pk_bf16_f32 v73, v74, v75
	v_cvt_pk_bf16_f32 v76, v76, v77
	v_cvt_pk_bf16_f32 v77, v78, v79
	global_store_dwordx2 v2, v[64:65], s[26:27] offset:0
	global_store_dwordx2 v2, v[68:69], s[26:27] offset:512
	global_store_dwordx2 v2, v[72:73], s[26:27] offset:1024
	global_store_dwordx2 v2, v[76:77], s[26:27] offset:1536
	v_mul_f32_e32 v96, v112, v15
	v_mul_f32_e32 v97, v113, v15
	v_mul_f32_e32 v98, v114, v15
	v_mul_f32_e32 v99, v115, v15
	v_mul_f32_e32 v100, v116, v15
	v_mul_f32_e32 v101, v117, v15
	v_mul_f32_e32 v102, v118, v15
	v_mul_f32_e32 v103, v119, v15
	v_mul_f32_e32 v104, v120, v15
	v_mul_f32_e32 v105, v121, v15
	v_mul_f32_e32 v106, v122, v15
	v_mul_f32_e32 v107, v123, v15
	v_mul_f32_e32 v108, v124, v15
	v_mul_f32_e32 v109, v125, v15
	v_mul_f32_e32 v110, v126, v15
	v_mul_f32_e32 v111, v127, v15
	v_mul_f32_e32 v96, v96, v36
	v_mul_f32_e32 v97, v97, v37
	v_mul_f32_e32 v98, v98, v38
	v_mul_f32_e32 v99, v99, v39
	v_mul_f32_e32 v100, v100, v40
	v_mul_f32_e32 v101, v101, v41
	v_mul_f32_e32 v102, v102, v42
	v_mul_f32_e32 v103, v103, v43
	v_mul_f32_e32 v104, v104, v44
	v_mul_f32_e32 v105, v105, v45
	v_mul_f32_e32 v106, v106, v46
	v_mul_f32_e32 v107, v107, v47
	v_mul_f32_e32 v108, v108, v48
	v_mul_f32_e32 v109, v109, v49
	v_mul_f32_e32 v110, v110, v50
	v_mul_f32_e32 v111, v111, v51
	v_cvt_pk_bf16_f32 v96, v96, v97
	v_cvt_pk_bf16_f32 v97, v98, v99
	v_cvt_pk_bf16_f32 v100, v100, v101
	v_cvt_pk_bf16_f32 v101, v102, v103
	v_cvt_pk_bf16_f32 v104, v104, v105
	v_cvt_pk_bf16_f32 v105, v106, v107
	v_cvt_pk_bf16_f32 v108, v108, v109
	v_cvt_pk_bf16_f32 v109, v110, v111
	global_store_dwordx2 v2, v[96:97], s[34:35] offset:0
	global_store_dwordx2 v2, v[100:101], s[34:35] offset:512
	global_store_dwordx2 v2, v[104:105], s[34:35] offset:1024
	global_store_dwordx2 v2, v[108:109], s[34:35] offset:1536
	s_waitcnt vmcnt(16)
	v_lshlrev_b32_e32 v128, 16, v130
	v_and_b32_e32 v129, 0xffff0000, v130
	v_lshlrev_b32_e32 v130, 16, v131
	v_and_b32_e32 v131, 0xffff0000, v131
	v_lshlrev_b32_e32 v132, 16, v134
	v_and_b32_e32 v133, 0xffff0000, v134
	v_lshlrev_b32_e32 v134, 16, v135
	v_and_b32_e32 v135, 0xffff0000, v135
	v_lshlrev_b32_e32 v136, 16, v138
	v_and_b32_e32 v137, 0xffff0000, v138
	v_lshlrev_b32_e32 v138, 16, v139
	v_and_b32_e32 v139, 0xffff0000, v139
	v_lshlrev_b32_e32 v140, 16, v142
	v_and_b32_e32 v141, 0xffff0000, v142
	v_lshlrev_b32_e32 v142, 16, v143
	v_and_b32_e32 v143, 0xffff0000, v143
	v_lshlrev_b32_e32 v160, 16, v162
	v_and_b32_e32 v161, 0xffff0000, v162
	v_lshlrev_b32_e32 v162, 16, v163
	v_and_b32_e32 v163, 0xffff0000, v163
	v_lshlrev_b32_e32 v164, 16, v166
	v_and_b32_e32 v165, 0xffff0000, v166
	v_lshlrev_b32_e32 v166, 16, v167
	v_and_b32_e32 v167, 0xffff0000, v167
	v_lshlrev_b32_e32 v168, 16, v170
	v_and_b32_e32 v169, 0xffff0000, v170
	v_lshlrev_b32_e32 v170, 16, v171
	v_and_b32_e32 v171, 0xffff0000, v171
	v_lshlrev_b32_e32 v172, 16, v174
	v_and_b32_e32 v173, 0xffff0000, v174
	v_lshlrev_b32_e32 v174, 16, v175
	v_and_b32_e32 v175, 0xffff0000, v175
	v_mul_f32_e32 v10, v128, v128
	v_fmac_f32_e32 v10, v129, v129
	v_fmac_f32_e32 v10, v130, v130
	v_fmac_f32_e32 v10, v131, v131
	v_fmac_f32_e32 v10, v132, v132
	v_fmac_f32_e32 v10, v133, v133
	v_fmac_f32_e32 v10, v134, v134
	v_fmac_f32_e32 v10, v135, v135
	v_fmac_f32_e32 v10, v136, v136
	v_fmac_f32_e32 v10, v137, v137
	v_fmac_f32_e32 v10, v138, v138
	v_fmac_f32_e32 v10, v139, v139
	v_fmac_f32_e32 v10, v140, v140
	v_fmac_f32_e32 v10, v141, v141
	v_fmac_f32_e32 v10, v142, v142
	v_fmac_f32_e32 v10, v143, v143
	v_mul_f32_e32 v11, v160, v160
	v_fmac_f32_e32 v11, v161, v161
	v_fmac_f32_e32 v11, v162, v162
	v_fmac_f32_e32 v11, v163, v163
	v_fmac_f32_e32 v11, v164, v164
	v_fmac_f32_e32 v11, v165, v165
	v_fmac_f32_e32 v11, v166, v166
	v_fmac_f32_e32 v11, v167, v167
	v_fmac_f32_e32 v11, v168, v168
	v_fmac_f32_e32 v11, v169, v169
	v_fmac_f32_e32 v11, v170, v170
	v_fmac_f32_e32 v11, v171, v171
	v_fmac_f32_e32 v11, v172, v172
	v_fmac_f32_e32 v11, v173, v173
	v_fmac_f32_e32 v11, v174, v174
	v_fmac_f32_e32 v11, v175, v175
	ds_bpermute_b32 v12, v4, v10
	ds_bpermute_b32 v13, v4, v11
	s_waitcnt lgkmcnt(0)
	v_add_f32_e32 v10, v10, v12
	v_add_f32_e32 v11, v11, v13
	ds_bpermute_b32 v12, v5, v10
	ds_bpermute_b32 v13, v5, v11
	s_waitcnt lgkmcnt(0)
	v_add_f32_e32 v10, v10, v12
	v_add_f32_e32 v11, v11, v13
	ds_bpermute_b32 v12, v6, v10
	ds_bpermute_b32 v13, v6, v11
	s_waitcnt lgkmcnt(0)
	v_add_f32_e32 v10, v10, v12
	v_add_f32_e32 v11, v11, v13
	ds_bpermute_b32 v12, v7, v10
	ds_bpermute_b32 v13, v7, v11
	s_waitcnt lgkmcnt(0)
	v_add_f32_e32 v10, v10, v12
	v_add_f32_e32 v11, v11, v13
	ds_bpermute_b32 v12, v8, v10
	ds_bpermute_b32 v13, v8, v11
	s_waitcnt lgkmcnt(0)
	v_add_f32_e32 v10, v10, v12
	v_add_f32_e32 v11, v11, v13
	ds_bpermute_b32 v12, v9, v10
	ds_bpermute_b32 v13, v9, v11
	s_waitcnt lgkmcnt(0)
	v_add_f32_e32 v10, v10, v12
	v_add_f32_e32 v11, v11, v13
	v_fma_f32 v14, v10, s17, v3
	v_fma_f32 v15, v11, s17, v3
	v_rsq_f32_e32 v14, v14
	v_rsq_f32_e32 v15, v15
	s_nop 0
	v_mul_f32_e32 v128, v128, v14
	v_mul_f32_e32 v129, v129, v14
	v_mul_f32_e32 v130, v130, v14
	v_mul_f32_e32 v131, v131, v14
	v_mul_f32_e32 v132, v132, v14
	v_mul_f32_e32 v133, v133, v14
	v_mul_f32_e32 v134, v134, v14
	v_mul_f32_e32 v135, v135, v14
	v_mul_f32_e32 v136, v136, v14
	v_mul_f32_e32 v137, v137, v14
	v_mul_f32_e32 v138, v138, v14
	v_mul_f32_e32 v139, v139, v14
	v_mul_f32_e32 v140, v140, v14
	v_mul_f32_e32 v141, v141, v14
	v_mul_f32_e32 v142, v142, v14
	v_mul_f32_e32 v143, v143, v14
	v_fmac_f32_e32 v144, v128, v20
	v_fmac_f32_e32 v145, v129, v21
	v_fmac_f32_e32 v146, v130, v22
	v_fmac_f32_e32 v147, v131, v23
	v_fmac_f32_e32 v148, v132, v24
	v_fmac_f32_e32 v149, v133, v25
	v_fmac_f32_e32 v150, v134, v26
	v_fmac_f32_e32 v151, v135, v27
	v_fmac_f32_e32 v152, v136, v28
	v_fmac_f32_e32 v153, v137, v29
	v_fmac_f32_e32 v154, v138, v30
	v_fmac_f32_e32 v155, v139, v31
	v_fmac_f32_e32 v156, v140, v32
	v_fmac_f32_e32 v157, v141, v33
	v_fmac_f32_e32 v158, v142, v34
	v_fmac_f32_e32 v159, v143, v35
	global_store_dwordx4 v1, v[144:147], s[40:41] offset:0 nt
	global_store_dwordx4 v1, v[148:151], s[40:41] offset:1024 nt
	global_store_dwordx4 v1, v[152:155], s[40:41] offset:2048 nt
	global_store_dwordx4 v1, v[156:159], s[40:41] offset:3072 nt
	v_mul_f32_e32 v160, v160, v15
	v_mul_f32_e32 v161, v161, v15
	v_mul_f32_e32 v162, v162, v15
	v_mul_f32_e32 v163, v163, v15
	v_mul_f32_e32 v164, v164, v15
	v_mul_f32_e32 v165, v165, v15
	v_mul_f32_e32 v166, v166, v15
	v_mul_f32_e32 v167, v167, v15
	v_mul_f32_e32 v168, v168, v15
	v_mul_f32_e32 v169, v169, v15
	v_mul_f32_e32 v170, v170, v15
	v_mul_f32_e32 v171, v171, v15
	v_mul_f32_e32 v172, v172, v15
	v_mul_f32_e32 v173, v173, v15
	v_mul_f32_e32 v174, v174, v15
	v_mul_f32_e32 v175, v175, v15
	v_fmac_f32_e32 v176, v160, v20
	v_fmac_f32_e32 v177, v161, v21
	v_fmac_f32_e32 v178, v162, v22
	v_fmac_f32_e32 v179, v163, v23
	v_fmac_f32_e32 v180, v164, v24
	v_fmac_f32_e32 v181, v165, v25
	v_fmac_f32_e32 v182, v166, v26
	v_fmac_f32_e32 v183, v167, v27
	v_fmac_f32_e32 v184, v168, v28
	v_fmac_f32_e32 v185, v169, v29
	v_fmac_f32_e32 v186, v170, v30
	v_fmac_f32_e32 v187, v171, v31
	v_fmac_f32_e32 v188, v172, v32
	v_fmac_f32_e32 v189, v173, v33
	v_fmac_f32_e32 v190, v174, v34
	v_fmac_f32_e32 v191, v175, v35
	global_store_dwordx4 v1, v[176:179], s[48:49] offset:0 nt
	global_store_dwordx4 v1, v[180:183], s[48:49] offset:1024 nt
	global_store_dwordx4 v1, v[184:187], s[48:49] offset:2048 nt
	global_store_dwordx4 v1, v[188:191], s[48:49] offset:3072 nt
	v_mul_f32_e32 v10, v144, v144
	v_fmac_f32_e32 v10, v145, v145
	v_fmac_f32_e32 v10, v146, v146
	v_fmac_f32_e32 v10, v147, v147
	v_fmac_f32_e32 v10, v148, v148
	v_fmac_f32_e32 v10, v149, v149
	v_fmac_f32_e32 v10, v150, v150
	v_fmac_f32_e32 v10, v151, v151
	v_fmac_f32_e32 v10, v152, v152
	v_fmac_f32_e32 v10, v153, v153
	v_fmac_f32_e32 v10, v154, v154
	v_fmac_f32_e32 v10, v155, v155
	v_fmac_f32_e32 v10, v156, v156
	v_fmac_f32_e32 v10, v157, v157
	v_fmac_f32_e32 v10, v158, v158
	v_fmac_f32_e32 v10, v159, v159
	v_mul_f32_e32 v11, v176, v176
	v_fmac_f32_e32 v11, v177, v177
	v_fmac_f32_e32 v11, v178, v178
	v_fmac_f32_e32 v11, v179, v179
	v_fmac_f32_e32 v11, v180, v180
	v_fmac_f32_e32 v11, v181, v181
	v_fmac_f32_e32 v11, v182, v182
	v_fmac_f32_e32 v11, v183, v183
	v_fmac_f32_e32 v11, v184, v184
	v_fmac_f32_e32 v11, v185, v185
	v_fmac_f32_e32 v11, v186, v186
	v_fmac_f32_e32 v11, v187, v187
	v_fmac_f32_e32 v11, v188, v188
	v_fmac_f32_e32 v11, v189, v189
	v_fmac_f32_e32 v11, v190, v190
	v_fmac_f32_e32 v11, v191, v191
	ds_bpermute_b32 v12, v4, v10
	ds_bpermute_b32 v13, v4, v11
	s_waitcnt lgkmcnt(0)
	v_add_f32_e32 v10, v10, v12
	v_add_f32_e32 v11, v11, v13
	ds_bpermute_b32 v12, v5, v10
	ds_bpermute_b32 v13, v5, v11
	s_waitcnt lgkmcnt(0)
	v_add_f32_e32 v10, v10, v12
	v_add_f32_e32 v11, v11, v13
	ds_bpermute_b32 v12, v6, v10
	ds_bpermute_b32 v13, v6, v11
	s_waitcnt lgkmcnt(0)
	v_add_f32_e32 v10, v10, v12
	v_add_f32_e32 v11, v11, v13
	ds_bpermute_b32 v12, v7, v10
	ds_bpermute_b32 v13, v7, v11
	s_waitcnt lgkmcnt(0)
	v_add_f32_e32 v10, v10, v12
	v_add_f32_e32 v11, v11, v13
	ds_bpermute_b32 v12, v8, v10
	ds_bpermute_b32 v13, v8, v11
	s_waitcnt lgkmcnt(0)
	v_add_f32_e32 v10, v10, v12
	v_add_f32_e32 v11, v11, v13
	ds_bpermute_b32 v12, v9, v10
	ds_bpermute_b32 v13, v9, v11
	s_waitcnt lgkmcnt(0)
	v_add_f32_e32 v10, v10, v12
	v_add_f32_e32 v11, v11, v13
	v_fma_f32 v14, v10, s17, v3
	v_fma_f32 v15, v11, s17, v3
	v_rsq_f32_e32 v14, v14
	v_rsq_f32_e32 v15, v15
	s_nop 0
	v_mul_f32_e32 v128, v144, v14
	v_mul_f32_e32 v129, v145, v14
	v_mul_f32_e32 v130, v146, v14
	v_mul_f32_e32 v131, v147, v14
	v_mul_f32_e32 v132, v148, v14
	v_mul_f32_e32 v133, v149, v14
	v_mul_f32_e32 v134, v150, v14
	v_mul_f32_e32 v135, v151, v14
	v_mul_f32_e32 v136, v152, v14
	v_mul_f32_e32 v137, v153, v14
	v_mul_f32_e32 v138, v154, v14
	v_mul_f32_e32 v139, v155, v14
	v_mul_f32_e32 v140, v156, v14
	v_mul_f32_e32 v141, v157, v14
	v_mul_f32_e32 v142, v158, v14
	v_mul_f32_e32 v143, v159, v14
	v_mul_f32_e32 v128, v128, v36
	v_mul_f32_e32 v129, v129, v37
	v_mul_f32_e32 v130, v130, v38
	v_mul_f32_e32 v131, v131, v39
	v_mul_f32_e32 v132, v132, v40
	v_mul_f32_e32 v133, v133, v41
	v_mul_f32_e32 v134, v134, v42
	v_mul_f32_e32 v135, v135, v43
	v_mul_f32_e32 v136, v136, v44
	v_mul_f32_e32 v137, v137, v45
	v_mul_f32_e32 v138, v138, v46
	v_mul_f32_e32 v139, v139, v47
	v_mul_f32_e32 v140, v140, v48
	v_mul_f32_e32 v141, v141, v49
	v_mul_f32_e32 v142, v142, v50
	v_mul_f32_e32 v143, v143, v51
	v_cvt_pk_bf16_f32 v128, v128, v129
	v_cvt_pk_bf16_f32 v129, v130, v131
	v_cvt_pk_bf16_f32 v132, v132, v133
	v_cvt_pk_bf16_f32 v133, v134, v135
	v_cvt_pk_bf16_f32 v136, v136, v137
	v_cvt_pk_bf16_f32 v137, v138, v139
	v_cvt_pk_bf16_f32 v140, v140, v141
	v_cvt_pk_bf16_f32 v141, v142, v143
	global_store_dwordx2 v2, v[128:129], s[42:43] offset:0
	global_store_dwordx2 v2, v[132:133], s[42:43] offset:512
	global_store_dwordx2 v2, v[136:137], s[42:43] offset:1024
	global_store_dwordx2 v2, v[140:141], s[42:43] offset:1536
	v_mul_f32_e32 v160, v176, v15
	v_mul_f32_e32 v161, v177, v15
	v_mul_f32_e32 v162, v178, v15
	v_mul_f32_e32 v163, v179, v15
	v_mul_f32_e32 v164, v180, v15
	v_mul_f32_e32 v165, v181, v15
	v_mul_f32_e32 v166, v182, v15
	v_mul_f32_e32 v167, v183, v15
	v_mul_f32_e32 v168, v184, v15
	v_mul_f32_e32 v169, v185, v15
	v_mul_f32_e32 v170, v186, v15
	v_mul_f32_e32 v171, v187, v15
	v_mul_f32_e32 v172, v188, v15
	v_mul_f32_e32 v173, v189, v15
	v_mul_f32_e32 v174, v190, v15
	v_mul_f32_e32 v175, v191, v15
	v_mul_f32_e32 v160, v160, v36
	v_mul_f32_e32 v161, v161, v37
	v_mul_f32_e32 v162, v162, v38
	v_mul_f32_e32 v163, v163, v39
	v_mul_f32_e32 v164, v164, v40
	v_mul_f32_e32 v165, v165, v41
	v_mul_f32_e32 v166, v166, v42
	v_mul_f32_e32 v167, v167, v43
	v_mul_f32_e32 v168, v168, v44
	v_mul_f32_e32 v169, v169, v45
	v_mul_f32_e32 v170, v170, v46
	v_mul_f32_e32 v171, v171, v47
	v_mul_f32_e32 v172, v172, v48
	v_mul_f32_e32 v173, v173, v49
	v_mul_f32_e32 v174, v174, v50
	v_mul_f32_e32 v175, v175, v51
	v_cvt_pk_bf16_f32 v160, v160, v161
	v_cvt_pk_bf16_f32 v161, v162, v163
	v_cvt_pk_bf16_f32 v164, v164, v165
	v_cvt_pk_bf16_f32 v165, v166, v167
	v_cvt_pk_bf16_f32 v168, v168, v169
	v_cvt_pk_bf16_f32 v169, v170, v171
	v_cvt_pk_bf16_f32 v172, v172, v173
	v_cvt_pk_bf16_f32 v173, v174, v175
	global_store_dwordx2 v2, v[160:161], s[50:51] offset:0
	global_store_dwordx2 v2, v[164:165], s[50:51] offset:512
	global_store_dwordx2 v2, v[168:169], s[50:51] offset:1024
	global_store_dwordx2 v2, v[172:173], s[50:51] offset:1536
	v_add_f32_e32 v208, v208, v212
	v_add_f32_e32 v209, v209, v213
	v_add_f32_e32 v210, v210, v214
	v_add_f32_e32 v211, v211, v215
	v_readfirstlane_b32 s18, v0
	s_lshr_b32 s18, s18, 6
	s_lshl_b32 s19, s18, 2
	s_and_b32 s52, s18, 4
	s_lshl_b32 s52, s52, 2
	v_mov_b32_e32 v16, s19
	v_mov_b32_e32 v17, s52
	v_mul_f32_e32 v10, v208, v208
	v_fmac_f32_e32 v10, v209, v209
	v_fmac_f32_e32 v10, v210, v210
	v_fmac_f32_e32 v10, v211, v211
	ds_bpermute_b32 v11, v4, v10
	s_waitcnt lgkmcnt(0)
	v_add_f32_e32 v10, v10, v11
	ds_bpermute_b32 v11, v5, v10
	s_waitcnt lgkmcnt(0)
	v_add_f32_e32 v10, v10, v11
	ds_bpermute_b32 v11, v6, v10
	s_waitcnt lgkmcnt(0)
	v_add_f32_e32 v10, v10, v11
	ds_bpermute_b32 v11, v7, v10
	s_waitcnt lgkmcnt(0)
	v_add_f32_e32 v10, v10, v11
	ds_bpermute_b32 v11, v8, v10
	s_waitcnt lgkmcnt(0)
	v_add_f32_e32 v10, v10, v11
	ds_bpermute_b32 v11, v9, v10
	s_waitcnt lgkmcnt(0)
	v_add_f32_e32 v10, v10, v11
	ds_write_b32 v16, v10 offset:0
	s_waitcnt lgkmcnt(0)
	s_barrier
	ds_read_b128 v[12:15], v17 offset:0
	s_waitcnt lgkmcnt(0)
	v_add_f32_e32 v12, v12, v13
	v_add_f32_e32 v14, v14, v15
	v_add_f32_e32 v10, v12, v14
	v_fma_f32 v11, v10, s17, v3
	v_rsq_f32_e32 v11, v11
	s_nop 0
	v_mul_f32_e32 v208, v208, v11
	v_mul_f32_e32 v209, v209, v11
	v_mul_f32_e32 v210, v210, v11
	v_mul_f32_e32 v211, v211, v11
	v_fmac_f32_e32 v240, v208, v244
	v_fmac_f32_e32 v241, v209, v245
	v_fmac_f32_e32 v242, v210, v246
	v_fmac_f32_e32 v243, v211, v247
	s_lshl_b32 s18, s54, 12
	s_add_u32 s18, s18, s55
	s_add_u32 s56, s4, s18
	s_addc_u32 s57, s5, 0
	s_add_u32 s56, s56, 0x4000000
	s_addc_u32 s57, s57, 0
	global_store_dwordx4 v1, v[240:243], s[56:57]
	v_mul_f32_e32 v10, v240, v240
	v_fmac_f32_e32 v10, v241, v241
	v_fmac_f32_e32 v10, v242, v242
	v_fmac_f32_e32 v10, v243, v243
	ds_bpermute_b32 v11, v4, v10
	s_waitcnt lgkmcnt(0)
	v_add_f32_e32 v10, v10, v11
	ds_bpermute_b32 v11, v5, v10
	s_waitcnt lgkmcnt(0)
	v_add_f32_e32 v10, v10, v11
	ds_bpermute_b32 v11, v6, v10
	s_waitcnt lgkmcnt(0)
	v_add_f32_e32 v10, v10, v11
	ds_bpermute_b32 v11, v7, v10
	s_waitcnt lgkmcnt(0)
	v_add_f32_e32 v10, v10, v11
	ds_bpermute_b32 v11, v8, v10
	s_waitcnt lgkmcnt(0)
	v_add_f32_e32 v10, v10, v11
	ds_bpermute_b32 v11, v9, v10
	s_waitcnt lgkmcnt(0)
	v_add_f32_e32 v10, v10, v11
	ds_write_b32 v16, v10 offset:64
	s_waitcnt lgkmcnt(0)
	s_barrier
	ds_read_b128 v[12:15], v17 offset:64
	s_waitcnt lgkmcnt(0)
	v_add_f32_e32 v12, v12, v13
	v_add_f32_e32 v14, v14, v15
	v_add_f32_e32 v10, v12, v14
	v_fma_f32 v11, v10, s17, v3
	v_rsq_f32_e32 v11, v11
	s_nop 0
	v_mul_f32_e32 v208, v240, v11
	v_mul_f32_e32 v209, v241, v11
	v_mul_f32_e32 v210, v242, v11
	v_mul_f32_e32 v211, v243, v11
	v_mul_f32_e32 v208, v208, v248
	v_mul_f32_e32 v209, v209, v249
	v_mul_f32_e32 v210, v210, v250
	v_mul_f32_e32 v211, v211, v251
	v_cvt_pk_bf16_f32 v208, v208, v209
	v_cvt_pk_bf16_f32 v209, v210, v211
	s_lshl_b32 s18, s54, 11
	s_lshr_b32 s19, s55, 1
	s_add_u32 s18, s18, s19
	s_add_u32 s56, s6, s18
	s_addc_u32 s57, s7, 0
	s_add_u32 s56, s56, 0x5100000
	s_addc_u32 s57, s57, 0
	global_store_dwordx2 v2, v[208:209], s[56:57]

_Z10fwd_kernelILi7ELi8EEv4Args:
	s_load_dword s3, s[0:1], 0xe8
	s_load_dwordx4 s[4:7], s[0:1], 0xd0
	s_load_dwordx2 s[8:9], s[0:1], 0xb8
	s_load_dwordx2 s[10:11], s[0:1], 0xa0
	s_waitcnt lgkmcnt(0)
	s_cmp_lg_u32 s3, 0x100
	s_cbranch_scc1 .Lrows7_orig
	s_add_u32 s10, s10, 0x1000
	s_addc_u32 s11, s11, 0
	v_readfirstlane_b32 s16, v0
	s_lshr_b32 s16, s16, 6
	s_lshl_b32 s18, s2, 3
	s_add_u32 s16, s16, s18
	s_mov_b32 s17, 0x3a800000
	v_mov_b32_e32 v3, 0x358637bd
	v_and_b32_e32 v10, 63, v0
	v_lshlrev_b32_e32 v1, 4, v10
	v_lshlrev_b32_e32 v2, 3, v10
	v_xor_b32_e32 v4, 1, v10
	v_xor_b32_e32 v5, 2, v10
	v_xor_b32_e32 v6, 4, v10
	v_xor_b32_e32 v7, 8, v10
	v_xor_b32_e32 v8, 16, v10
	v_xor_b32_e32 v9, 32, v10
	v_lshlrev_b32_e32 v4, 2, v4
	v_lshlrev_b32_e32 v5, 2, v5
	v_lshlrev_b32_e32 v6, 2, v6
	v_lshlrev_b32_e32 v7, 2, v7
	v_lshlrev_b32_e32 v8, 2, v8
	v_lshlrev_b32_e32 v9, 2, v9
	global_load_dwordx4 v[20:23], v1, s[8:9] offset:0
	global_load_dwordx4 v[24:27], v1, s[8:9] offset:1024
	global_load_dwordx4 v[28:31], v1, s[8:9] offset:2048
	global_load_dwordx4 v[32:35], v1, s[8:9] offset:3072
	global_load_dwordx4 v[36:39], v1, s[10:11] offset:0
	global_load_dwordx4 v[40:43], v1, s[10:11] offset:1024
	global_load_dwordx4 v[44:47], v1, s[10:11] offset:2048
	global_load_dwordx4 v[48:51], v1, s[10:11] offset:3072
	s_lshr_b32 s54, s16, 2
	s_and_b32 s55, s16, 3
	s_lshl_b32 s55, s55, 10
	s_lshl_b32 s18, s54, 12
	s_add_u32 s18, s18, s55
	s_add_u32 s56, s6, s18
	s_addc_u32 s57, s7, 0
	s_add_u32 s56, s56, 0x100000
	s_addc_u32 s57, s57, 0
	global_load_dwordx4 v[208:211], v1, s[56:57]
	s_add_u32 s56, s56, 0x200000
	s_addc_u32 s57, s57, 0
	global_load_dwordx4 v[212:215], v1, s[56:57]
	s_add_u32 s56, s56, 0x200000
	s_addc_u32 s57, s57, 0
	global_load_dwordx4 v[216:219], v1, s[56:57]
	s_add_u32 s56, s56, 0x200000
	s_addc_u32 s57, s57, 0
	global_load_dwordx4 v[220:223], v1, s[56:57]
	s_add_u32 s56, s56, 0x200000
	s_addc_u32 s57, s57, 0
	global_load_dwordx4 v[224:227], v1, s[56:57]
	s_add_u32 s56, s56, 0x200000
	s_addc_u32 s57, s57, 0
	global_load_dwordx4 v[228:231], v1, s[56:57]
	s_add_u32 s56, s56, 0x200000
	s_addc_u32 s57, s57, 0
	global_load_dwordx4 v[232:235], v1, s[56:57]
	s_add_u32 s56, s56, 0x200000
	s_addc_u32 s57, s57, 0
	global_load_dwordx4 v[236:239], v1, s[56:57]
	s_add_u32 s56, s4, s18
	s_addc_u32 s57, s5, 0
	s_add_u32 s56, s56, 0x4000000
	s_addc_u32 s57, s57, 0
	global_load_dwordx4 v[240:243], v1, s[56:57]
	s_add_u32 s56, s8, s55
	s_addc_u32 s57, s9, 0
	global_load_dwordx4 v[244:247], v1, s[56:57]
	s_add_u32 s56, s10, s55
	s_addc_u32 s57, s11, 0
	global_load_dwordx4 v[248:251], v1, s[56:57]
	s_add_u32 s53, s16, 0x0
	s_lshl_b32 s18, s53, 12
	s_lshl_b32 s19, s53, 11
	s_add_u32 s20, s4, s18
	s_addc_u32 s21, s5, 0
	s_add_u32 s22, s6, s19
	s_addc_u32 s23, s7, 0
	s_add_u32 s22, s22, 0x5200000
	s_addc_u32 s23, s23, 0
	s_add_u32 s24, s4, s18
	s_addc_u32 s25, s5, 0
	s_add_u32 s26, s6, s19
	s_addc_u32 s27, s7, 0
	s_add_u32 s26, s26, 0x3100000
	s_addc_u32 s27, s27, 0
	global_load_dwordx2 v[66:67], v2, s[22:23] offset:0
	global_load_dwordx2 v[70:71], v2, s[22:23] offset:512
	global_load_dwordx2 v[74:75], v2, s[22:23] offset:1024
	global_load_dwordx2 v[78:79], v2, s[22:23] offset:1536
	global_load_dwordx4 v[80:83], v1, s[20:21] offset:0
	global_load_dwordx4 v[84:87], v1, s[20:21] offset:1024
	global_load_dwordx4 v[88:91], v1, s[20:21] offset:2048
	global_load_dwordx4 v[92:95], v1, s[20:21] offset:3072
	s_add_u32 s53, s16, 0x800
	s_lshl_b32 s18, s53, 12
	s_lshl_b32 s19, s53, 11
	s_add_u32 s28, s4, s18
	s_addc_u32 s29, s5, 0
	s_add_u32 s30, s6, s19
	s_addc_u32 s31, s7, 0
	s_add_u32 s30, s30, 0x5200000
	s_addc_u32 s31, s31, 0
	s_add_u32 s32, s4, s18
	s_addc_u32 s33, s5, 0
	s_add_u32 s34, s6, s19
	s_addc_u32 s35, s7, 0
	s_add_u32 s34, s34, 0x3100000
	s_addc_u32 s35, s35, 0
	global_load_dwordx2 v[98:99], v2, s[30:31] offset:0
	global_load_dwordx2 v[102:103], v2, s[30:31] offset:512
	global_load_dwordx2 v[106:107], v2, s[30:31] offset:1024
	global_load_dwordx2 v[110:111], v2, s[30:31] offset:1536
	global_load_dwordx4 v[112:115], v1, s[28:29] offset:0
	global_load_dwordx4 v[116:119], v1, s[28:29] offset:1024
	global_load_dwordx4 v[120:123], v1, s[28:29] offset:2048
	global_load_dwordx4 v[124:127], v1, s[28:29] offset:3072
	s_add_u32 s53, s16, 0x1000
	s_lshl_b32 s18, s53, 12
	s_lshl_b32 s19, s53, 11
	s_add_u32 s36, s4, s18
	s_addc_u32 s37, s5, 0
	s_add_u32 s38, s6, s19
	s_addc_u32 s39, s7, 0
	s_add_u32 s38, s38, 0x5200000
	s_addc_u32 s39, s39, 0
	s_add_u32 s40, s4, s18
	s_addc_u32 s41, s5, 0
	s_add_u32 s42, s6, s19
	s_addc_u32 s43, s7, 0
	s_add_u32 s42, s42, 0x3100000
	s_addc_u32 s43, s43, 0
	global_load_dwordx2 v[130:131], v2, s[38:39] offset:0
	global_load_dwordx2 v[134:135], v2, s[38:39] offset:512
	global_load_dwordx2 v[138:139], v2, s[38:39] offset:1024
	global_load_dwordx2 v[142:143], v2, s[38:39] offset:1536
	global_load_dwordx4 v[144:147], v1, s[36:37] offset:0
	global_load_dwordx4 v[148:151], v1, s[36:37] offset:1024
	global_load_dwordx4 v[152:155], v1, s[36:37] offset:2048
	global_load_dwordx4 v[156:159], v1, s[36:37] offset:3072
	s_add_u32 s53, s16, 0x1800
	s_lshl_b32 s18, s53, 12
	s_lshl_b32 s19, s53, 11
	s_add_u32 s44, s4, s18
	s_addc_u32 s45, s5, 0
	s_add_u32 s46, s6, s19
	s_addc_u32 s47, s7, 0
	s_add_u32 s46, s46, 0x5200000
	s_addc_u32 s47, s47, 0
	s_add_u32 s48, s4, s18
	s_addc_u32 s49, s5, 0
	s_add_u32 s50, s6, s19
	s_addc_u32 s51, s7, 0
	s_add_u32 s50, s50, 0x3100000
	s_addc_u32 s51, s51, 0
	global_load_dwordx2 v[162:163], v2, s[46:47] offset:0
	global_load_dwordx2 v[166:167], v2, s[46:47] offset:512
	global_load_dwordx2 v[170:171], v2, s[46:47] offset:1024
	global_load_dwordx2 v[174:175], v2, s[46:47] offset:1536
	global_load_dwordx4 v[176:179], v1, s[44:45] offset:0
	global_load_dwordx4 v[180:183], v1, s[44:45] offset:1024
	global_load_dwordx4 v[184:187], v1, s[44:45] offset:2048
	global_load_dwordx4 v[188:191], v1, s[44:45] offset:3072
	s_waitcnt vmcnt(16)
	v_lshlrev_b32_e32 v64, 16, v66
	v_and_b32_e32 v65, 0xffff0000, v66
	v_lshlrev_b32_e32 v66, 16, v67
	v_and_b32_e32 v67, 0xffff0000, v67
	v_lshlrev_b32_e32 v68, 16, v70
	v_and_b32_e32 v69, 0xffff0000, v70
	v_lshlrev_b32_e32 v70, 16, v71
	v_and_b32_e32 v71, 0xffff0000, v71
	v_lshlrev_b32_e32 v72, 16, v74
	v_and_b32_e32 v73, 0xffff0000, v74
	v_lshlrev_b32_e32 v74, 16, v75
	v_and_b32_e32 v75, 0xffff0000, v75
	v_lshlrev_b32_e32 v76, 16, v78
	v_and_b32_e32 v77, 0xffff0000, v78
	v_lshlrev_b32_e32 v78, 16, v79
	v_and_b32_e32 v79, 0xffff0000, v79
	v_lshlrev_b32_e32 v96, 16, v98
	v_and_b32_e32 v97, 0xffff0000, v98
	v_lshlrev_b32_e32 v98, 16, v99
	v_and_b32_e32 v99, 0xffff0000, v99
	v_lshlrev_b32_e32 v100, 16, v102
	v_and_b32_e32 v101, 0xffff0000, v102
	v_lshlrev_b32_e32 v102, 16, v103
	v_and_b32_e32 v103, 0xffff0000, v103
	v_lshlrev_b32_e32 v104, 16, v106
	v_and_b32_e32 v105, 0xffff0000, v106
	v_lshlrev_b32_e32 v106, 16, v107
	v_and_b32_e32 v107, 0xffff0000, v107
	v_lshlrev_b32_e32 v108, 16, v110
	v_and_b32_e32 v109, 0xffff0000, v110
	v_lshlrev_b32_e32 v110, 16, v111
	v_and_b32_e32 v111, 0xffff0000, v111
	v_mul_f32_e32 v10, v64, v64
	v_fmac_f32_e32 v10, v65, v65
	v_fmac_f32_e32 v10, v66, v66
	v_fmac_f32_e32 v10, v67, v67
	v_fmac_f32_e32 v10, v68, v68
	v_fmac_f32_e32 v10, v69, v69
	v_fmac_f32_e32 v10, v70, v70
	v_fmac_f32_e32 v10, v71, v71
	v_fmac_f32_e32 v10, v72, v72
	v_fmac_f32_e32 v10, v73, v73
	v_fmac_f32_e32 v10, v74, v74
	v_fmac_f32_e32 v10, v75, v75
	v_fmac_f32_e32 v10, v76, v76
	v_fmac_f32_e32 v10, v77, v77
	v_fmac_f32_e32 v10, v78, v78
	v_fmac_f32_e32 v10, v79, v79
	v_mul_f32_e32 v11, v96, v96
	v_fmac_f32_e32 v11, v97, v97
	v_fmac_f32_e32 v11, v98, v98
	v_fmac_f32_e32 v11, v99, v99
	v_fmac_f32_e32 v11, v100, v100
	v_fmac_f32_e32 v11, v101, v101
	v_fmac_f32_e32 v11, v102, v102
	v_fmac_f32_e32 v11, v103, v103
	v_fmac_f32_e32 v11, v104, v104
	v_fmac_f32_e32 v11, v105, v105
	v_fmac_f32_e32 v11, v106, v106
	v_fmac_f32_e32 v11, v107, v107
	v_fmac_f32_e32 v11, v108, v108
	v_fmac_f32_e32 v11, v109, v109
	v_fmac_f32_e32 v11, v110, v110
	v_fmac_f32_e32 v11, v111, v111
	ds_bpermute_b32 v12, v4, v10
	ds_bpermute_b32 v13, v4, v11
	s_waitcnt lgkmcnt(0)
	v_add_f32_e32 v10, v10, v12
	v_add_f32_e32 v11, v11, v13
	ds_bpermute_b32 v12, v5, v10
	ds_bpermute_b32 v13, v5, v11
	s_waitcnt lgkmcnt(0)
	v_add_f32_e32 v10, v10, v12
	v_add_f32_e32 v11, v11, v13
	ds_bpermute_b32 v12, v6, v10
	ds_bpermute_b32 v13, v6, v11
	s_waitcnt lgkmcnt(0)
	v_add_f32_e32 v10, v10, v12
	v_add_f32_e32 v11, v11, v13
	ds_bpermute_b32 v12, v7, v10
	ds_bpermute_b32 v13, v7, v11
	s_waitcnt lgkmcnt(0)
	v_add_f32_e32 v10, v10, v12
	v_add_f32_e32 v11, v11, v13
	ds_bpermute_b32 v12, v8, v10
	ds_bpermute_b32 v13, v8, v11
	s_waitcnt lgkmcnt(0)
	v_add_f32_e32 v10, v10, v12
	v_add_f32_e32 v11, v11, v13
	ds_bpermute_b32 v12, v9, v10
	ds_bpermute_b32 v13, v9, v11
	s_waitcnt lgkmcnt(0)
	v_add_f32_e32 v10, v10, v12
	v_add_f32_e32 v11, v11, v13
	v_fma_f32 v14, v10, s17, v3
	v_fma_f32 v15, v11, s17, v3
	v_rsq_f32_e32 v14, v14
	v_rsq_f32_e32 v15, v15
	s_nop 0
	v_mul_f32_e32 v64, v64, v14
	v_mul_f32_e32 v65, v65, v14
	v_mul_f32_e32 v66, v66, v14
	v_mul_f32_e32 v67, v67, v14
	v_mul_f32_e32 v68, v68, v14
	v_mul_f32_e32 v69, v69, v14
	v_mul_f32_e32 v70, v70, v14
	v_mul_f32_e32 v71, v71, v14
	v_mul_f32_e32 v72, v72, v14
	v_mul_f32_e32 v73, v73, v14
	v_mul_f32_e32 v74, v74, v14
	v_mul_f32_e32 v75, v75, v14
	v_mul_f32_e32 v76, v76, v14
	v_mul_f32_e32 v77, v77, v14
	v_mul_f32_e32 v78, v78, v14
	v_mul_f32_e32 v79, v79, v14
	v_fmac_f32_e32 v80, v64, v20
	v_fmac_f32_e32 v81, v65, v21
	v_fmac_f32_e32 v82, v66, v22
	v_fmac_f32_e32 v83, v67, v23
	v_fmac_f32_e32 v84, v68, v24
	v_fmac_f32_e32 v85, v69, v25
	v_fmac_f32_e32 v86, v70, v26
	v_fmac_f32_e32 v87, v71, v27
	v_fmac_f32_e32 v88, v72, v28
	v_fmac_f32_e32 v89, v73, v29
	v_fmac_f32_e32 v90, v74, v30
	v_fmac_f32_e32 v91, v75, v31
	v_fmac_f32_e32 v92, v76, v32
	v_fmac_f32_e32 v93, v77, v33
	v_fmac_f32_e32 v94, v78, v34
	v_fmac_f32_e32 v95, v79, v35
	global_store_dwordx4 v1, v[80:83], s[24:25] offset:0 nt
	global_store_dwordx4 v1, v[84:87], s[24:25] offset:1024 nt
	global_store_dwordx4 v1, v[88:91], s[24:25] offset:2048 nt
	global_store_dwordx4 v1, v[92:95], s[24:25] offset:3072 nt
	v_mul_f32_e32 v96, v96, v15
	v_mul_f32_e32 v97, v97, v15
	v_mul_f32_e32 v98, v98, v15
	v_mul_f32_e32 v99, v99, v15
	v_mul_f32_e32 v100, v100, v15
	v_mul_f32_e32 v101, v101, v15
	v_mul_f32_e32 v102, v102, v15
	v_mul_f32_e32 v103, v103, v15
	v_mul_f32_e32 v104, v104, v15
	v_mul_f32_e32 v105, v105, v15
	v_mul_f32_e32 v106, v106, v15
	v_mul_f32_e32 v107, v107, v15
	v_mul_f32_e32 v108, v108, v15
	v_mul_f32_e32 v109, v109, v15
	v_mul_f32_e32 v110, v110, v15
	v_mul_f32_e32 v111, v111, v15
	v_fmac_f32_e32 v112, v96, v20
	v_fmac_f32_e32 v113, v97, v21
	v_fmac_f32_e32 v114, v98, v22
	v_fmac_f32_e32 v115, v99, v23
	v_fmac_f32_e32 v116, v100, v24
	v_fmac_f32_e32 v117, v101, v25
	v_fmac_f32_e32 v118, v102, v26
	v_fmac_f32_e32 v119, v103, v27
	v_fmac_f32_e32 v120, v104, v28
	v_fmac_f32_e32 v121, v105, v29
	v_fmac_f32_e32 v122, v106, v30
	v_fmac_f32_e32 v123, v107, v31
	v_fmac_f32_e32 v124, v108, v32
	v_fmac_f32_e32 v125, v109, v33
	v_fmac_f32_e32 v126, v110, v34
	v_fmac_f32_e32 v127, v111, v35
	global_store_dwordx4 v1, v[112:115], s[32:33] offset:0 nt
	global_store_dwordx4 v1, v[116:119], s[32:33] offset:1024 nt
	global_store_dwordx4 v1, v[120:123], s[32:33] offset:2048 nt
	global_store_dwordx4 v1, v[124:127], s[32:33] offset:3072 nt
	v_mul_f32_e32 v10, v80, v80
	v_fmac_f32_e32 v10, v81, v81
	v_fmac_f32_e32 v10, v82, v82
	v_fmac_f32_e32 v10, v83, v83
	v_fmac_f32_e32 v10, v84, v84
	v_fmac_f32_e32 v10, v85, v85
	v_fmac_f32_e32 v10, v86, v86
	v_fmac_f32_e32 v10, v87, v87
	v_fmac_f32_e32 v10, v88, v88
	v_fmac_f32_e32 v10, v89, v89
	v_fmac_f32_e32 v10, v90, v90
	v_fmac_f32_e32 v10, v91, v91
	v_fmac_f32_e32 v10, v92, v92
	v_fmac_f32_e32 v10, v93, v93
	v_fmac_f32_e32 v10, v94, v94
	v_fmac_f32_e32 v10, v95, v95
	v_mul_f32_e32 v11, v112, v112
	v_fmac_f32_e32 v11, v113, v113
	v_fmac_f32_e32 v11, v114, v114
	v_fmac_f32_e32 v11, v115, v115
	v_fmac_f32_e32 v11, v116, v116
	v_fmac_f32_e32 v11, v117, v117
	v_fmac_f32_e32 v11, v118, v118
	v_fmac_f32_e32 v11, v119, v119
	v_fmac_f32_e32 v11, v120, v120
	v_fmac_f32_e32 v11, v121, v121
	v_fmac_f32_e32 v11, v122, v122
	v_fmac_f32_e32 v11, v123, v123
	v_fmac_f32_e32 v11, v124, v124
	v_fmac_f32_e32 v11, v125, v125
	v_fmac_f32_e32 v11, v126, v126
	v_fmac_f32_e32 v11, v127, v127
	ds_bpermute_b32 v12, v4, v10
	ds_bpermute_b32 v13, v4, v11
	s_waitcnt lgkmcnt(0)
	v_add_f32_e32 v10, v10, v12
	v_add_f32_e32 v11, v11, v13
	ds_bpermute_b32 v12, v5, v10
	ds_bpermute_b32 v13, v5, v11
	s_waitcnt lgkmcnt(0)
	v_add_f32_e32 v10, v10, v12
	v_add_f32_e32 v11, v11, v13
	ds_bpermute_b32 v12, v6, v10
	ds_bpermute_b32 v13, v6, v11
	s_waitcnt lgkmcnt(0)
	v_add_f32_e32 v10, v10, v12
	v_add_f32_e32 v11, v11, v13
	ds_bpermute_b32 v12, v7, v10
	ds_bpermute_b32 v13, v7, v11
	s_waitcnt lgkmcnt(0)
	v_add_f32_e32 v10, v10, v12
	v_add_f32_e32 v11, v11, v13
	ds_bpermute_b32 v12, v8, v10
	ds_bpermute_b32 v13, v8, v11
	s_waitcnt lgkmcnt(0)
	v_add_f32_e32 v10, v10, v12
	v_add_f32_e32 v11, v11, v13
	ds_bpermute_b32 v12, v9, v10
	ds_bpermute_b32 v13, v9, v11
	s_waitcnt lgkmcnt(0)
	v_add_f32_e32 v10, v10, v12
	v_add_f32_e32 v11, v11, v13
	v_fma_f32 v14, v10, s17, v3
	v_fma_f32 v15, v11, s17, v3
	v_rsq_f32_e32 v14, v14
	v_rsq_f32_e32 v15, v15
	s_nop 0
	v_mul_f32_e32 v64, v80, v14
	v_mul_f32_e32 v65, v81, v14
	v_mul_f32_e32 v66, v82, v14
	v_mul_f32_e32 v67, v83, v14
	v_mul_f32_e32 v68, v84, v14
	v_mul_f32_e32 v69, v85, v14
	v_mul_f32_e32 v70, v86, v14
	v_mul_f32_e32 v71, v87, v14
	v_mul_f32_e32 v72, v88, v14
	v_mul_f32_e32 v73, v89, v14
	v_mul_f32_e32 v74, v90, v14
	v_mul_f32_e32 v75, v91, v14
	v_mul_f32_e32 v76, v92, v14
	v_mul_f32_e32 v77, v93, v14
	v_mul_f32_e32 v78, v94, v14
	v_mul_f32_e32 v79, v95, v14
	v_mul_f32_e32 v64, v64, v36
	v_mul_f32_e32 v65, v65, v37
	v_mul_f32_e32 v66, v66, v38
	v_mul_f32_e32 v67, v67, v39
	v_mul_f32_e32 v68, v68, v40
	v_mul_f32_e32 v69, v69, v41
	v_mul_f32_e32 v70, v70, v42
	v_mul_f32_e32 v71, v71, v43
	v_mul_f32_e32 v72, v72, v44
	v_mul_f32_e32 v73, v73, v45
	v_mul_f32_e32 v74, v74, v46
	v_mul_f32_e32 v75, v75, v47
	v_mul_f32_e32 v76, v76, v48
	v_mul_f32_e32 v77, v77, v49
	v_mul_f32_e32 v78, v78, v50
	v_mul_f32_e32 v79, v79, v51
	v_cvt_pk_bf16_f32 v64, v64, v65
	v_cvt_pk_bf16_f32 v65, v66, v67
	v_cvt_pk_bf16_f32 v68, v68, v69
	v_cvt_pk_bf16_f32 v69, v70, v71
	v_cvt_pk_bf16_f32 v72, v72, v73
	v_cvt_pk_bf16_f32 v73, v74, v75
	v_cvt_pk_bf16_f32 v76, v76, v77
	v_cvt_pk_bf16_f32 v77, v78, v79
	global_store_dwordx2 v2, v[64:65], s[26:27] offset:0
	global_store_dwordx2 v2, v[68:69], s[26:27] offset:512
	global_store_dwordx2 v2, v[72:73], s[26:27] offset:1024
	global_store_dwordx2 v2, v[76:77], s[26:27] offset:1536
	v_mul_f32_e32 v96, v112, v15
	v_mul_f32_e32 v97, v113, v15
	v_mul_f32_e32 v98, v114, v15
	v_mul_f32_e32 v99, v115, v15
	v_mul_f32_e32 v100, v116, v15
	v_mul_f32_e32 v101, v117, v15
	v_mul_f32_e32 v102, v118, v15
	v_mul_f32_e32 v103, v119, v15
	v_mul_f32_e32 v104, v120, v15
	v_mul_f32_e32 v105, v121, v15
	v_mul_f32_e32 v106, v122, v15
	v_mul_f32_e32 v107, v123, v15
	v_mul_f32_e32 v108, v124, v15
	v_mul_f32_e32 v109, v125, v15
	v_mul_f32_e32 v110, v126, v15
	v_mul_f32_e32 v111, v127, v15
	v_mul_f32_e32 v96, v96, v36
	v_mul_f32_e32 v97, v97, v37
	v_mul_f32_e32 v98, v98, v38
	v_mul_f32_e32 v99, v99, v39
	v_mul_f32_e32 v100, v100, v40
	v_mul_f32_e32 v101, v101, v41
	v_mul_f32_e32 v102, v102, v42
	v_mul_f32_e32 v103, v103, v43
	v_mul_f32_e32 v104, v104, v44
	v_mul_f32_e32 v105, v105, v45
	v_mul_f32_e32 v106, v106, v46
	v_mul_f32_e32 v107, v107, v47
	v_mul_f32_e32 v108, v108, v48
	v_mul_f32_e32 v109, v109, v49
	v_mul_f32_e32 v110, v110, v50
	v_mul_f32_e32 v111, v111, v51
	v_cvt_pk_bf16_f32 v96, v96, v97
	v_cvt_pk_bf16_f32 v97, v98, v99
	v_cvt_pk_bf16_f32 v100, v100, v101
	v_cvt_pk_bf16_f32 v101, v102, v103
	v_cvt_pk_bf16_f32 v104, v104, v105
	v_cvt_pk_bf16_f32 v105, v106, v107
	v_cvt_pk_bf16_f32 v108, v108, v109
	v_cvt_pk_bf16_f32 v109, v110, v111
	global_store_dwordx2 v2, v[96:97], s[34:35] offset:0
	global_store_dwordx2 v2, v[100:101], s[34:35] offset:512
	global_store_dwordx2 v2, v[104:105], s[34:35] offset:1024
	global_store_dwordx2 v2, v[108:109], s[34:35] offset:1536
	s_add_u32 s53, s16, 0x2000
	s_lshl_b32 s18, s53, 12
	s_lshl_b32 s19, s53, 11
	s_add_u32 s20, s4, s18
	s_addc_u32 s21, s5, 0
	s_add_u32 s22, s6, s19
	s_addc_u32 s23, s7, 0
	s_add_u32 s22, s22, 0x5200000
	s_addc_u32 s23, s23, 0
	s_add_u32 s24, s4, s18
	s_addc_u32 s25, s5, 0
	s_add_u32 s26, s6, s19
	s_addc_u32 s27, s7, 0
	s_add_u32 s26, s26, 0x3100000
	s_addc_u32 s27, s27, 0
	global_load_dwordx2 v[66:67], v2, s[22:23] offset:0
	global_load_dwordx2 v[70:71], v2, s[22:23] offset:512
	global_load_dwordx2 v[74:75], v2, s[22:23] offset:1024
	global_load_dwordx2 v[78:79], v2, s[22:23] offset:1536
	global_load_dwordx4 v[80:83], v1, s[20:21] offset:0
	global_load_dwordx4 v[84:87], v1, s[20:21] offset:1024
	global_load_dwordx4 v[88:91], v1, s[20:21] offset:2048
	global_load_dwordx4 v[92:95], v1, s[20:21] offset:3072
	s_add_u32 s53, s16, 0x2800
	s_lshl_b32 s18, s53, 12
	s_lshl_b32 s19, s53, 11
	s_add_u32 s28, s4, s18
	s_addc_u32 s29, s5, 0
	s_add_u32 s30, s6, s19
	s_addc_u32 s31, s7, 0
	s_add_u32 s30, s30, 0x5200000
	s_addc_u32 s31, s31, 0
	s_add_u32 s32, s4, s18
	s_addc_u32 s33, s5, 0
	s_add_u32 s34, s6, s19
	s_addc_u32 s35, s7, 0
	s_add_u32 s34, s34, 0x3100000
	s_addc_u32 s35, s35, 0
	global_load_dwordx2 v[98:99], v2, s[30:31] offset:0
	global_load_dwordx2 v[102:103], v2, s[30:31] offset:512
	global_load_dwordx2 v[106:107], v2, s[30:31] offset:1024
	global_load_dwordx2 v[110:111], v2, s[30:31] offset:1536
	global_load_dwordx4 v[112:115], v1, s[28:29] offset:0
	global_load_dwordx4 v[116:119], v1, s[28:29] offset:1024
	global_load_dwordx4 v[120:123], v1, s[28:29] offset:2048
	global_load_dwordx4 v[124:127], v1, s[28:29] offset:3072
	s_waitcnt vmcnt(32)
	v_lshlrev_b32_e32 v128, 16, v130
	v_and_b32_e32 v129, 0xffff0000, v130
	v_lshlrev_b32_e32 v130, 16, v131
	v_and_b32_e32 v131, 0xffff0000, v131
	v_lshlrev_b32_e32 v132, 16, v134
	v_and_b32_e32 v133, 0xffff0000, v134
	v_lshlrev_b32_e32 v134, 16, v135
	v_and_b32_e32 v135, 0xffff0000, v135
	v_lshlrev_b32_e32 v136, 16, v138
	v_and_b32_e32 v137, 0xffff0000, v138
	v_lshlrev_b32_e32 v138, 16, v139
	v_and_b32_e32 v139, 0xffff0000, v139
	v_lshlrev_b32_e32 v140, 16, v142
	v_and_b32_e32 v141, 0xffff0000, v142
	v_lshlrev_b32_e32 v142, 16, v143
	v_and_b32_e32 v143, 0xffff0000, v143
	v_lshlrev_b32_e32 v160, 16, v162
	v_and_b32_e32 v161, 0xffff0000, v162
	v_lshlrev_b32_e32 v162, 16, v163
	v_and_b32_e32 v163, 0xffff0000, v163
	v_lshlrev_b32_e32 v164, 16, v166
	v_and_b32_e32 v165, 0xffff0000, v166
	v_lshlrev_b32_e32 v166, 16, v167
	v_and_b32_e32 v167, 0xffff0000, v167
	v_lshlrev_b32_e32 v168, 16, v170
	v_and_b32_e32 v169, 0xffff0000, v170
	v_lshlrev_b32_e32 v170, 16, v171
	v_and_b32_e32 v171, 0xffff0000, v171
	v_lshlrev_b32_e32 v172, 16, v174
	v_and_b32_e32 v173, 0xffff0000, v174
	v_lshlrev_b32_e32 v174, 16, v175
	v_and_b32_e32 v175, 0xffff0000, v175
	v_mul_f32_e32 v10, v128, v128
	v_fmac_f32_e32 v10, v129, v129
	v_fmac_f32_e32 v10, v130, v130
	v_fmac_f32_e32 v10, v131, v131
	v_fmac_f32_e32 v10, v132, v132
	v_fmac_f32_e32 v10, v133, v133
	v_fmac_f32_e32 v10, v134, v134
	v_fmac_f32_e32 v10, v135, v135
	v_fmac_f32_e32 v10, v136, v136
	v_fmac_f32_e32 v10, v137, v137
	v_fmac_f32_e32 v10, v138, v138
	v_fmac_f32_e32 v10, v139, v139
	v_fmac_f32_e32 v10, v140, v140
	v_fmac_f32_e32 v10, v141, v141
	v_fmac_f32_e32 v10, v142, v142
	v_fmac_f32_e32 v10, v143, v143
	v_mul_f32_e32 v11, v160, v160
	v_fmac_f32_e32 v11, v161, v161
	v_fmac_f32_e32 v11, v162, v162
	v_fmac_f32_e32 v11, v163, v163
	v_fmac_f32_e32 v11, v164, v164
	v_fmac_f32_e32 v11, v165, v165
	v_fmac_f32_e32 v11, v166, v166
	v_fmac_f32_e32 v11, v167, v167
	v_fmac_f32_e32 v11, v168, v168
	v_fmac_f32_e32 v11, v169, v169
	v_fmac_f32_e32 v11, v170, v170
	v_fmac_f32_e32 v11, v171, v171
	v_fmac_f32_e32 v11, v172, v172
	v_fmac_f32_e32 v11, v173, v173
	v_fmac_f32_e32 v11, v174, v174
	v_fmac_f32_e32 v11, v175, v175
	ds_bpermute_b32 v12, v4, v10
	ds_bpermute_b32 v13, v4, v11
	s_waitcnt lgkmcnt(0)
	v_add_f32_e32 v10, v10, v12
	v_add_f32_e32 v11, v11, v13
	ds_bpermute_b32 v12, v5, v10
	ds_bpermute_b32 v13, v5, v11
	s_waitcnt lgkmcnt(0)
	v_add_f32_e32 v10, v10, v12
	v_add_f32_e32 v11, v11, v13
	ds_bpermute_b32 v12, v6, v10
	ds_bpermute_b32 v13, v6, v11
	s_waitcnt lgkmcnt(0)
	v_add_f32_e32 v10, v10, v12
	v_add_f32_e32 v11, v11, v13
	ds_bpermute_b32 v12, v7, v10
	ds_bpermute_b32 v13, v7, v11
	s_waitcnt lgkmcnt(0)
	v_add_f32_e32 v10, v10, v12
	v_add_f32_e32 v11, v11, v13
	ds_bpermute_b32 v12, v8, v10
	ds_bpermute_b32 v13, v8, v11
	s_waitcnt lgkmcnt(0)
	v_add_f32_e32 v10, v10, v12
	v_add_f32_e32 v11, v11, v13
	ds_bpermute_b32 v12, v9, v10
	ds_bpermute_b32 v13, v9, v11
	s_waitcnt lgkmcnt(0)
	v_add_f32_e32 v10, v10, v12
	v_add_f32_e32 v11, v11, v13
	v_fma_f32 v14, v10, s17, v3
	v_fma_f32 v15, v11, s17, v3
	v_rsq_f32_e32 v14, v14
	v_rsq_f32_e32 v15, v15
	s_nop 0
	v_mul_f32_e32 v128, v128, v14
	v_mul_f32_e32 v129, v129, v14
	v_mul_f32_e32 v130, v130, v14
	v_mul_f32_e32 v131, v131, v14
	v_mul_f32_e32 v132, v132, v14
	v_mul_f32_e32 v133, v133, v14
	v_mul_f32_e32 v134, v134, v14
	v_mul_f32_e32 v135, v135, v14
	v_mul_f32_e32 v136, v136, v14
	v_mul_f32_e32 v137, v137, v14
	v_mul_f32_e32 v138, v138, v14
	v_mul_f32_e32 v139, v139, v14
	v_mul_f32_e32 v140, v140, v14
	v_mul_f32_e32 v141, v141, v14
	v_mul_f32_e32 v142, v142, v14
	v_mul_f32_e32 v143, v143, v14
	v_fmac_f32_e32 v144, v128, v20
	v_fmac_f32_e32 v145, v129, v21
	v_fmac_f32_e32 v146, v130, v22
	v_fmac_f32_e32 v147, v131, v23
	v_fmac_f32_e32 v148, v132, v24
	v_fmac_f32_e32 v149, v133, v25
	v_fmac_f32_e32 v150, v134, v26
	v_fmac_f32_e32 v151, v135, v27
	v_fmac_f32_e32 v152, v136, v28
	v_fmac_f32_e32 v153, v137, v29
	v_fmac_f32_e32 v154, v138, v30
	v_fmac_f32_e32 v155, v139, v31
	v_fmac_f32_e32 v156, v140, v32
	v_fmac_f32_e32 v157, v141, v33
	v_fmac_f32_e32 v158, v142, v34
	v_fmac_f32_e32 v159, v143, v35
	global_store_dwordx4 v1, v[144:147], s[40:41] offset:0 nt
	global_store_dwordx4 v1, v[148:151], s[40:41] offset:1024 nt
	global_store_dwordx4 v1, v[152:155], s[40:41] offset:2048 nt
	global_store_dwordx4 v1, v[156:159], s[40:41] offset:3072 nt
	v_mul_f32_e32 v160, v160, v15
	v_mul_f32_e32 v161, v161, v15
	v_mul_f32_e32 v162, v162, v15
	v_mul_f32_e32 v163, v163, v15
	v_mul_f32_e32 v164, v164, v15
	v_mul_f32_e32 v165, v165, v15
	v_mul_f32_e32 v166, v166, v15
	v_mul_f32_e32 v167, v167, v15
	v_mul_f32_e32 v168, v168, v15
	v_mul_f32_e32 v169, v169, v15
	v_mul_f32_e32 v170, v170, v15
	v_mul_f32_e32 v171, v171, v15
	v_mul_f32_e32 v172, v172, v15
	v_mul_f32_e32 v173, v173, v15
	v_mul_f32_e32 v174, v174, v15
	v_mul_f32_e32 v175, v175, v15
	v_fmac_f32_e32 v176, v160, v20
	v_fmac_f32_e32 v177, v161, v21
	v_fmac_f32_e32 v178, v162, v22
	v_fmac_f32_e32 v179, v163, v23
	v_fmac_f32_e32 v180, v164, v24
	v_fmac_f32_e32 v181, v165, v25
	v_fmac_f32_e32 v182, v166, v26
	v_fmac_f32_e32 v183, v167, v27
	v_fmac_f32_e32 v184, v168, v28
	v_fmac_f32_e32 v185, v169, v29
	v_fmac_f32_e32 v186, v170, v30
	v_fmac_f32_e32 v187, v171, v31
	v_fmac_f32_e32 v188, v172, v32
	v_fmac_f32_e32 v189, v173, v33
	v_fmac_f32_e32 v190, v174, v34
	v_fmac_f32_e32 v191, v175, v35
	global_store_dwordx4 v1, v[176:179], s[48:49] offset:0 nt
	global_store_dwordx4 v1, v[180:183], s[48:49] offset:1024 nt
	global_store_dwordx4 v1, v[184:187], s[48:49] offset:2048 nt
	global_store_dwordx4 v1, v[188:191], s[48:49] offset:3072 nt
	v_mul_f32_e32 v10, v144, v144
	v_fmac_f32_e32 v10, v145, v145
	v_fmac_f32_e32 v10, v146, v146
	v_fmac_f32_e32 v10, v147, v147
	v_fmac_f32_e32 v10, v148, v148
	v_fmac_f32_e32 v10, v149, v149
	v_fmac_f32_e32 v10, v150, v150
	v_fmac_f32_e32 v10, v151, v151
	v_fmac_f32_e32 v10, v152, v152
	v_fmac_f32_e32 v10, v153, v153
	v_fmac_f32_e32 v10, v154, v154
	v_fmac_f32_e32 v10, v155, v155
	v_fmac_f32_e32 v10, v156, v156
	v_fmac_f32_e32 v10, v157, v157
	v_fmac_f32_e32 v10, v158, v158
	v_fmac_f32_e32 v10, v159, v159
	v_mul_f32_e32 v11, v176, v176
	v_fmac_f32_e32 v11, v177, v177
	v_fmac_f32_e32 v11, v178, v178
	v_fmac_f32_e32 v11, v179, v179
	v_fmac_f32_e32 v11, v180, v180
	v_fmac_f32_e32 v11, v181, v181
	v_fmac_f32_e32 v11, v182, v182
	v_fmac_f32_e32 v11, v183, v183
	v_fmac_f32_e32 v11, v184, v184
	v_fmac_f32_e32 v11, v185, v185
	v_fmac_f32_e32 v11, v186, v186
	v_fmac_f32_e32 v11, v187, v187
	v_fmac_f32_e32 v11, v188, v188
	v_fmac_f32_e32 v11, v189, v189
	v_fmac_f32_e32 v11, v190, v190
	v_fmac_f32_e32 v11, v191, v191
	ds_bpermute_b32 v12, v4, v10
	ds_bpermute_b32 v13, v4, v11
	s_waitcnt lgkmcnt(0)
	v_add_f32_e32 v10, v10, v12
	v_add_f32_e32 v11, v11, v13
	ds_bpermute_b32 v12, v5, v10
	ds_bpermute_b32 v13, v5, v11
	s_waitcnt lgkmcnt(0)
	v_add_f32_e32 v10, v10, v12
	v_add_f32_e32 v11, v11, v13
	ds_bpermute_b32 v12, v6, v10
	ds_bpermute_b32 v13, v6, v11
	s_waitcnt lgkmcnt(0)
	v_add_f32_e32 v10, v10, v12
	v_add_f32_e32 v11, v11, v13
	ds_bpermute_b32 v12, v7, v10
	ds_bpermute_b32 v13, v7, v11
	s_waitcnt lgkmcnt(0)
	v_add_f32_e32 v10, v10, v12
	v_add_f32_e32 v11, v11, v13
	ds_bpermute_b32 v12, v8, v10
	ds_bpermute_b32 v13, v8, v11
	s_waitcnt lgkmcnt(0)
	v_add_f32_e32 v10, v10, v12
	v_add_f32_e32 v11, v11, v13
	ds_bpermute_b32 v12, v9, v10
	ds_bpermute_b32 v13, v9, v11
	s_waitcnt lgkmcnt(0)
	v_add_f32_e32 v10, v10, v12
	v_add_f32_e32 v11, v11, v13
	v_fma_f32 v14, v10, s17, v3
	v_fma_f32 v15, v11, s17, v3
	v_rsq_f32_e32 v14, v14
	v_rsq_f32_e32 v15, v15
	s_nop 0
	v_mul_f32_e32 v128, v144, v14
	v_mul_f32_e32 v129, v145, v14
	v_mul_f32_e32 v130, v146, v14
	v_mul_f32_e32 v131, v147, v14
	v_mul_f32_e32 v132, v148, v14
	v_mul_f32_e32 v133, v149, v14
	v_mul_f32_e32 v134, v150, v14
	v_mul_f32_e32 v135, v151, v14
	v_mul_f32_e32 v136, v152, v14
	v_mul_f32_e32 v137, v153, v14
	v_mul_f32_e32 v138, v154, v14
	v_mul_f32_e32 v139, v155, v14
	v_mul_f32_e32 v140, v156, v14
	v_mul_f32_e32 v141, v157, v14
	v_mul_f32_e32 v142, v158, v14
	v_mul_f32_e32 v143, v159, v14
	v_mul_f32_e32 v128, v128, v36
	v_mul_f32_e32 v129, v129, v37
	v_mul_f32_e32 v130, v130, v38
	v_mul_f32_e32 v131, v131, v39
	v_mul_f32_e32 v132, v132, v40
	v_mul_f32_e32 v133, v133, v41
	v_mul_f32_e32 v134, v134, v42
	v_mul_f32_e32 v135, v135, v43
	v_mul_f32_e32 v136, v136, v44
	v_mul_f32_e32 v137, v137, v45
	v_mul_f32_e32 v138, v138, v46
	v_mul_f32_e32 v139, v139, v47
	v_mul_f32_e32 v140, v140, v48
	v_mul_f32_e32 v141, v141, v49
	v_mul_f32_e32 v142, v142, v50
	v_mul_f32_e32 v143, v143, v51
	v_cvt_pk_bf16_f32 v128, v128, v129
	v_cvt_pk_bf16_f32 v129, v130, v131
	v_cvt_pk_bf16_f32 v132, v132, v133
	v_cvt_pk_bf16_f32 v133, v134, v135
	v_cvt_pk_bf16_f32 v136, v136, v137
	v_cvt_pk_bf16_f32 v137, v138, v139
	v_cvt_pk_bf16_f32 v140, v140, v141
	v_cvt_pk_bf16_f32 v141, v142, v143
	global_store_dwordx2 v2, v[128:129], s[42:43] offset:0
	global_store_dwordx2 v2, v[132:133], s[42:43] offset:512
	global_store_dwordx2 v2, v[136:137], s[42:43] offset:1024
	global_store_dwordx2 v2, v[140:141], s[42:43] offset:1536
	v_mul_f32_e32 v160, v176, v15
	v_mul_f32_e32 v161, v177, v15
	v_mul_f32_e32 v162, v178, v15
	v_mul_f32_e32 v163, v179, v15
	v_mul_f32_e32 v164, v180, v15
	v_mul_f32_e32 v165, v181, v15
	v_mul_f32_e32 v166, v182, v15
	v_mul_f32_e32 v167, v183, v15
	v_mul_f32_e32 v168, v184, v15
	v_mul_f32_e32 v169, v185, v15
	v_mul_f32_e32 v170, v186, v15
	v_mul_f32_e32 v171, v187, v15
	v_mul_f32_e32 v172, v188, v15
	v_mul_f32_e32 v173, v189, v15
	v_mul_f32_e32 v174, v190, v15
	v_mul_f32_e32 v175, v191, v15
	v_mul_f32_e32 v160, v160, v36
	v_mul_f32_e32 v161, v161, v37
	v_mul_f32_e32 v162, v162, v38
	v_mul_f32_e32 v163, v163, v39
	v_mul_f32_e32 v164, v164, v40
	v_mul_f32_e32 v165, v165, v41
	v_mul_f32_e32 v166, v166, v42
	v_mul_f32_e32 v167, v167, v43
	v_mul_f32_e32 v168, v168, v44
	v_mul_f32_e32 v169, v169, v45
	v_mul_f32_e32 v170, v170, v46
	v_mul_f32_e32 v171, v171, v47
	v_mul_f32_e32 v172, v172, v48
	v_mul_f32_e32 v173, v173, v49
	v_mul_f32_e32 v174, v174, v50
	v_mul_f32_e32 v175, v175, v51
	v_cvt_pk_bf16_f32 v160, v160, v161
	v_cvt_pk_bf16_f32 v161, v162, v163
	v_cvt_pk_bf16_f32 v164, v164, v165
	v_cvt_pk_bf16_f32 v165, v166, v167
	v_cvt_pk_bf16_f32 v168, v168, v169
	v_cvt_pk_bf16_f32 v169, v170, v171
	v_cvt_pk_bf16_f32 v172, v172, v173
	v_cvt_pk_bf16_f32 v173, v174, v175
	global_store_dwordx2 v2, v[160:161], s[50:51] offset:0
	global_store_dwordx2 v2, v[164:165], s[50:51] offset:512
	global_store_dwordx2 v2, v[168:169], s[50:51] offset:1024
	global_store_dwordx2 v2, v[172:173], s[50:51] offset:1536
	s_add_u32 s53, s16, 0x3000
	s_lshl_b32 s18, s53, 12
	s_lshl_b32 s19, s53, 11
	s_add_u32 s36, s4, s18
	s_addc_u32 s37, s5, 0
	s_add_u32 s38, s6, s19
	s_addc_u32 s39, s7, 0
	s_add_u32 s38, s38, 0x5200000
	s_addc_u32 s39, s39, 0
	s_add_u32 s40, s4, s18
	s_addc_u32 s41, s5, 0
	s_add_u32 s42, s6, s19
	s_addc_u32 s43, s7, 0
	s_add_u32 s42, s42, 0x3100000
	s_addc_u32 s43, s43, 0
	global_load_dwordx2 v[130:131], v2, s[38:39] offset:0
	global_load_dwordx2 v[134:135], v2, s[38:39] offset:512
	global_load_dwordx2 v[138:139], v2, s[38:39] offset:1024
	global_load_dwordx2 v[142:143], v2, s[38:39] offset:1536
	global_load_dwordx4 v[144:147], v1, s[36:37] offset:0
	global_load_dwordx4 v[148:151], v1, s[36:37] offset:1024
	global_load_dwordx4 v[152:155], v1, s[36:37] offset:2048
	global_load_dwordx4 v[156:159], v1, s[36:37] offset:3072
	s_add_u32 s53, s16, 0x3800
	s_lshl_b32 s18, s53, 12
	s_lshl_b32 s19, s53, 11
	s_add_u32 s44, s4, s18
	s_addc_u32 s45, s5, 0
	s_add_u32 s46, s6, s19
	s_addc_u32 s47, s7, 0
	s_add_u32 s46, s46, 0x5200000
	s_addc_u32 s47, s47, 0
	s_add_u32 s48, s4, s18
	s_addc_u32 s49, s5, 0
	s_add_u32 s50, s6, s19
	s_addc_u32 s51, s7, 0
	s_add_u32 s50, s50, 0x3100000
	s_addc_u32 s51, s51, 0
	global_load_dwordx2 v[162:163], v2, s[46:47] offset:0
	global_load_dwordx2 v[166:167], v2, s[46:47] offset:512
	global_load_dwordx2 v[170:171], v2, s[46:47] offset:1024
	global_load_dwordx2 v[174:175], v2, s[46:47] offset:1536
	global_load_dwordx4 v[176:179], v1, s[44:45] offset:0
	global_load_dwordx4 v[180:183], v1, s[44:45] offset:1024
	global_load_dwordx4 v[184:187], v1, s[44:45] offset:2048
	global_load_dwordx4 v[188:191], v1, s[44:45] offset:3072
	s_waitcnt vmcnt(32)
	v_lshlrev_b32_e32 v64, 16, v66
	v_and_b32_e32 v65, 0xffff0000, v66
	v_lshlrev_b32_e32 v66, 16, v67
	v_and_b32_e32 v67, 0xffff0000, v67
	v_lshlrev_b32_e32 v68, 16, v70
	v_and_b32_e32 v69, 0xffff0000, v70
	v_lshlrev_b32_e32 v70, 16, v71
	v_and_b32_e32 v71, 0xffff0000, v71
	v_lshlrev_b32_e32 v72, 16, v74
	v_and_b32_e32 v73, 0xffff0000, v74
	v_lshlrev_b32_e32 v74, 16, v75
	v_and_b32_e32 v75, 0xffff0000, v75
	v_lshlrev_b32_e32 v76, 16, v78
	v_and_b32_e32 v77, 0xffff0000, v78
	v_lshlrev_b32_e32 v78, 16, v79
	v_and_b32_e32 v79, 0xffff0000, v79
	v_lshlrev_b32_e32 v96, 16, v98
	v_and_b32_e32 v97, 0xffff0000, v98
	v_lshlrev_b32_e32 v98, 16, v99
	v_and_b32_e32 v99, 0xffff0000, v99
	v_lshlrev_b32_e32 v100, 16, v102
	v_and_b32_e32 v101, 0xffff0000, v102
	v_lshlrev_b32_e32 v102, 16, v103
	v_and_b32_e32 v103, 0xffff0000, v103
	v_lshlrev_b32_e32 v104, 16, v106
	v_and_b32_e32 v105, 0xffff0000, v106
	v_lshlrev_b32_e32 v106, 16, v107
	v_and_b32_e32 v107, 0xffff0000, v107
	v_lshlrev_b32_e32 v108, 16, v110
	v_and_b32_e32 v109, 0xffff0000, v110
	v_lshlrev_b32_e32 v110, 16, v111
	v_and_b32_e32 v111, 0xffff0000, v111
	v_mul_f32_e32 v10, v64, v64
	v_fmac_f32_e32 v10, v65, v65
	v_fmac_f32_e32 v10, v66, v66
	v_fmac_f32_e32 v10, v67, v67
	v_fmac_f32_e32 v10, v68, v68
	v_fmac_f32_e32 v10, v69, v69
	v_fmac_f32_e32 v10, v70, v70
	v_fmac_f32_e32 v10, v71, v71
	v_fmac_f32_e32 v10, v72, v72
	v_fmac_f32_e32 v10, v73, v73
	v_fmac_f32_e32 v10, v74, v74
	v_fmac_f32_e32 v10, v75, v75
	v_fmac_f32_e32 v10, v76, v76
	v_fmac_f32_e32 v10, v77, v77
	v_fmac_f32_e32 v10, v78, v78
	v_fmac_f32_e32 v10, v79, v79
	v_mul_f32_e32 v11, v96, v96
	v_fmac_f32_e32 v11, v97, v97
	v_fmac_f32_e32 v11, v98, v98
	v_fmac_f32_e32 v11, v99, v99
	v_fmac_f32_e32 v11, v100, v100
	v_fmac_f32_e32 v11, v101, v101
	v_fmac_f32_e32 v11, v102, v102
	v_fmac_f32_e32 v11, v103, v103
	v_fmac_f32_e32 v11, v104, v104
	v_fmac_f32_e32 v11, v105, v105
	v_fmac_f32_e32 v11, v106, v106
	v_fmac_f32_e32 v11, v107, v107
	v_fmac_f32_e32 v11, v108, v108
	v_fmac_f32_e32 v11, v109, v109
	v_fmac_f32_e32 v11, v110, v110
	v_fmac_f32_e32 v11, v111, v111
	ds_bpermute_b32 v12, v4, v10
	ds_bpermute_b32 v13, v4, v11
	s_waitcnt lgkmcnt(0)
	v_add_f32_e32 v10, v10, v12
	v_add_f32_e32 v11, v11, v13
	ds_bpermute_b32 v12, v5, v10
	ds_bpermute_b32 v13, v5, v11
	s_waitcnt lgkmcnt(0)
	v_add_f32_e32 v10, v10, v12
	v_add_f32_e32 v11, v11, v13
	ds_bpermute_b32 v12, v6, v10
	ds_bpermute_b32 v13, v6, v11
	s_waitcnt lgkmcnt(0)
	v_add_f32_e32 v10, v10, v12
	v_add_f32_e32 v11, v11, v13
	ds_bpermute_b32 v12, v7, v10
	ds_bpermute_b32 v13, v7, v11
	s_waitcnt lgkmcnt(0)
	v_add_f32_e32 v10, v10, v12
	v_add_f32_e32 v11, v11, v13
	ds_bpermute_b32 v12, v8, v10
	ds_bpermute_b32 v13, v8, v11
	s_waitcnt lgkmcnt(0)
	v_add_f32_e32 v10, v10, v12
	v_add_f32_e32 v11, v11, v13
	ds_bpermute_b32 v12, v9, v10
	ds_bpermute_b32 v13, v9, v11
	s_waitcnt lgkmcnt(0)
	v_add_f32_e32 v10, v10, v12
	v_add_f32_e32 v11, v11, v13
	v_fma_f32 v14, v10, s17, v3
	v_fma_f32 v15, v11, s17, v3
	v_rsq_f32_e32 v14, v14
	v_rsq_f32_e32 v15, v15
	s_nop 0
	v_mul_f32_e32 v64, v64, v14
	v_mul_f32_e32 v65, v65, v14
	v_mul_f32_e32 v66, v66, v14
	v_mul_f32_e32 v67, v67, v14
	v_mul_f32_e32 v68, v68, v14
	v_mul_f32_e32 v69, v69, v14
	v_mul_f32_e32 v70, v70, v14
	v_mul_f32_e32 v71, v71, v14
	v_mul_f32_e32 v72, v72, v14
	v_mul_f32_e32 v73, v73, v14
	v_mul_f32_e32 v74, v74, v14
	v_mul_f32_e32 v75, v75, v14
	v_mul_f32_e32 v76, v76, v14
	v_mul_f32_e32 v77, v77, v14
	v_mul_f32_e32 v78, v78, v14
	v_mul_f32_e32 v79, v79, v14
	v_fmac_f32_e32 v80, v64, v20
	v_fmac_f32_e32 v81, v65, v21
	v_fmac_f32_e32 v82, v66, v22
	v_fmac_f32_e32 v83, v67, v23
	v_fmac_f32_e32 v84, v68, v24
	v_fmac_f32_e32 v85, v69, v25
	v_fmac_f32_e32 v86, v70, v26
	v_fmac_f32_e32 v87, v71, v27
	v_fmac_f32_e32 v88, v72, v28
	v_fmac_f32_e32 v89, v73, v29
	v_fmac_f32_e32 v90, v74, v30
	v_fmac_f32_e32 v91, v75, v31
	v_fmac_f32_e32 v92, v76, v32
	v_fmac_f32_e32 v93, v77, v33
	v_fmac_f32_e32 v94, v78, v34
	v_fmac_f32_e32 v95, v79, v35
	global_store_dwordx4 v1, v[80:83], s[24:25] offset:0 nt
	global_store_dwordx4 v1, v[84:87], s[24:25] offset:1024 nt
	global_store_dwordx4 v1, v[88:91], s[24:25] offset:2048 nt
	global_store_dwordx4 v1, v[92:95], s[24:25] offset:3072 nt
	v_mul_f32_e32 v96, v96, v15
	v_mul_f32_e32 v97, v97, v15
	v_mul_f32_e32 v98, v98, v15
	v_mul_f32_e32 v99, v99, v15
	v_mul_f32_e32 v100, v100, v15
	v_mul_f32_e32 v101, v101, v15
	v_mul_f32_e32 v102, v102, v15
	v_mul_f32_e32 v103, v103, v15
	v_mul_f32_e32 v104, v104, v15
	v_mul_f32_e32 v105, v105, v15
	v_mul_f32_e32 v106, v106, v15
	v_mul_f32_e32 v107, v107, v15
	v_mul_f32_e32 v108, v108, v15
	v_mul_f32_e32 v109, v109, v15
	v_mul_f32_e32 v110, v110, v15
	v_mul_f32_e32 v111, v111, v15
	v_fmac_f32_e32 v112, v96, v20
	v_fmac_f32_e32 v113, v97, v21
	v_fmac_f32_e32 v114, v98, v22
	v_fmac_f32_e32 v115, v99, v23
	v_fmac_f32_e32 v116, v100, v24
	v_fmac_f32_e32 v117, v101, v25
	v_fmac_f32_e32 v118, v102, v26
	v_fmac_f32_e32 v119, v103, v27
	v_fmac_f32_e32 v120, v104, v28
	v_fmac_f32_e32 v121, v105, v29
	v_fmac_f32_e32 v122, v106, v30
	v_fmac_f32_e32 v123, v107, v31
	v_fmac_f32_e32 v124, v108, v32
	v_fmac_f32_e32 v125, v109, v33
	v_fmac_f32_e32 v126, v110, v34
	v_fmac_f32_e32 v127, v111, v35
	global_store_dwordx4 v1, v[112:115], s[32:33] offset:0 nt
	global_store_dwordx4 v1, v[116:119], s[32:33] offset:1024 nt
	global_store_dwordx4 v1, v[120:123], s[32:33] offset:2048 nt
	global_store_dwordx4 v1, v[124:127], s[32:33] offset:3072 nt
	v_mul_f32_e32 v10, v80, v80
	v_fmac_f32_e32 v10, v81, v81
	v_fmac_f32_e32 v10, v82, v82
	v_fmac_f32_e32 v10, v83, v83
	v_fmac_f32_e32 v10, v84, v84
	v_fmac_f32_e32 v10, v85, v85
	v_fmac_f32_e32 v10, v86, v86
	v_fmac_f32_e32 v10, v87, v87
	v_fmac_f32_e32 v10, v88, v88
	v_fmac_f32_e32 v10, v89, v89
	v_fmac_f32_e32 v10, v90, v90
	v_fmac_f32_e32 v10, v91, v91
	v_fmac_f32_e32 v10, v92, v92
	v_fmac_f32_e32 v10, v93, v93
	v_fmac_f32_e32 v10, v94, v94
	v_fmac_f32_e32 v10, v95, v95
	v_mul_f32_e32 v11, v112, v112
	v_fmac_f32_e32 v11, v113, v113
	v_fmac_f32_e32 v11, v114, v114
	v_fmac_f32_e32 v11, v115, v115
	v_fmac_f32_e32 v11, v116, v116
	v_fmac_f32_e32 v11, v117, v117
	v_fmac_f32_e32 v11, v118, v118
	v_fmac_f32_e32 v11, v119, v119
	v_fmac_f32_e32 v11, v120, v120
	v_fmac_f32_e32 v11, v121, v121
	v_fmac_f32_e32 v11, v122, v122
	v_fmac_f32_e32 v11, v123, v123
	v_fmac_f32_e32 v11, v124, v124
	v_fmac_f32_e32 v11, v125, v125
	v_fmac_f32_e32 v11, v126, v126
	v_fmac_f32_e32 v11, v127, v127
	ds_bpermute_b32 v12, v4, v10
	ds_bpermute_b32 v13, v4, v11
	s_waitcnt lgkmcnt(0)
	v_add_f32_e32 v10, v10, v12
	v_add_f32_e32 v11, v11, v13
	ds_bpermute_b32 v12, v5, v10
	ds_bpermute_b32 v13, v5, v11
	s_waitcnt lgkmcnt(0)
	v_add_f32_e32 v10, v10, v12
	v_add_f32_e32 v11, v11, v13
	ds_bpermute_b32 v12, v6, v10
	ds_bpermute_b32 v13, v6, v11
	s_waitcnt lgkmcnt(0)
	v_add_f32_e32 v10, v10, v12
	v_add_f32_e32 v11, v11, v13
	ds_bpermute_b32 v12, v7, v10
	ds_bpermute_b32 v13, v7, v11
	s_waitcnt lgkmcnt(0)
	v_add_f32_e32 v10, v10, v12
	v_add_f32_e32 v11, v11, v13
	ds_bpermute_b32 v12, v8, v10
	ds_bpermute_b32 v13, v8, v11
	s_waitcnt lgkmcnt(0)
	v_add_f32_e32 v10, v10, v12
	v_add_f32_e32 v11, v11, v13
	ds_bpermute_b32 v12, v9, v10
	ds_bpermute_b32 v13, v9, v11
	s_waitcnt lgkmcnt(0)
	v_add_f32_e32 v10, v10, v12
	v_add_f32_e32 v11, v11, v13
	v_fma_f32 v14, v10, s17, v3
	v_fma_f32 v15, v11, s17, v3
	v_rsq_f32_e32 v14, v14
	v_rsq_f32_e32 v15, v15
	s_nop 0
	v_mul_f32_e32 v64, v80, v14
	v_mul_f32_e32 v65, v81, v14
	v_mul_f32_e32 v66, v82, v14
	v_mul_f32_e32 v67, v83, v14
	v_mul_f32_e32 v68, v84, v14
	v_mul_f32_e32 v69, v85, v14
	v_mul_f32_e32 v70, v86, v14
	v_mul_f32_e32 v71, v87, v14
	v_mul_f32_e32 v72, v88, v14
	v_mul_f32_e32 v73, v89, v14
	v_mul_f32_e32 v74, v90, v14
	v_mul_f32_e32 v75, v91, v14
	v_mul_f32_e32 v76, v92, v14
	v_mul_f32_e32 v77, v93, v14
	v_mul_f32_e32 v78, v94, v14
	v_mul_f32_e32 v79, v95, v14
	v_mul_f32_e32 v64, v64, v36
	v_mul_f32_e32 v65, v65, v37
	v_mul_f32_e32 v66, v66, v38
	v_mul_f32_e32 v67, v67, v39
	v_mul_f32_e32 v68, v68, v40
	v_mul_f32_e32 v69, v69, v41
	v_mul_f32_e32 v70, v70, v42
	v_mul_f32_e32 v71, v71, v43
	v_mul_f32_e32 v72, v72, v44
	v_mul_f32_e32 v73, v73, v45
	v_mul_f32_e32 v74, v74, v46
	v_mul_f32_e32 v75, v75, v47
	v_mul_f32_e32 v76, v76, v48
	v_mul_f32_e32 v77, v77, v49
	v_mul_f32_e32 v78, v78, v50
	v_mul_f32_e32 v79, v79, v51
	v_cvt_pk_bf16_f32 v64, v64, v65
	v_cvt_pk_bf16_f32 v65, v66, v67
	v_cvt_pk_bf16_f32 v68, v68, v69
	v_cvt_pk_bf16_f32 v69, v70, v71
	v_cvt_pk_bf16_f32 v72, v72, v73
	v_cvt_pk_bf16_f32 v73, v74, v75
	v_cvt_pk_bf16_f32 v76, v76, v77
	v_cvt_pk_bf16_f32 v77, v78, v79
	global_store_dwordx2 v2, v[64:65], s[26:27] offset:0
	global_store_dwordx2 v2, v[68:69], s[26:27] offset:512
	global_store_dwordx2 v2, v[72:73], s[26:27] offset:1024
	global_store_dwordx2 v2, v[76:77], s[26:27] offset:1536
	v_mul_f32_e32 v96, v112, v15
	v_mul_f32_e32 v97, v113, v15
	v_mul_f32_e32 v98, v114, v15
	v_mul_f32_e32 v99, v115, v15
	v_mul_f32_e32 v100, v116, v15
	v_mul_f32_e32 v101, v117, v15
	v_mul_f32_e32 v102, v118, v15
	v_mul_f32_e32 v103, v119, v15
	v_mul_f32_e32 v104, v120, v15
	v_mul_f32_e32 v105, v121, v15
	v_mul_f32_e32 v106, v122, v15
	v_mul_f32_e32 v107, v123, v15
	v_mul_f32_e32 v108, v124, v15
	v_mul_f32_e32 v109, v125, v15
	v_mul_f32_e32 v110, v126, v15
	v_mul_f32_e32 v111, v127, v15
	v_mul_f32_e32 v96, v96, v36
	v_mul_f32_e32 v97, v97, v37
	v_mul_f32_e32 v98, v98, v38
	v_mul_f32_e32 v99, v99, v39
	v_mul_f32_e32 v100, v100, v40
	v_mul_f32_e32 v101, v101, v41
	v_mul_f32_e32 v102, v102, v42
	v_mul_f32_e32 v103, v103, v43
	v_mul_f32_e32 v104, v104, v44
	v_mul_f32_e32 v105, v105, v45
	v_mul_f32_e32 v106, v106, v46
	v_mul_f32_e32 v107, v107, v47
	v_mul_f32_e32 v108, v108, v48
	v_mul_f32_e32 v109, v109, v49
	v_mul_f32_e32 v110, v110, v50
	v_mul_f32_e32 v111, v111, v51
	v_cvt_pk_bf16_f32 v96, v96, v97
	v_cvt_pk_bf16_f32 v97, v98, v99
	v_cvt_pk_bf16_f32 v100, v100, v101
	v_cvt_pk_bf16_f32 v101, v102, v103
	v_cvt_pk_bf16_f32 v104, v104, v105
	v_cvt_pk_bf16_f32 v105, v106, v107
	v_cvt_pk_bf16_f32 v108, v108, v109
	v_cvt_pk_bf16_f32 v109, v110, v111
	global_store_dwordx2 v2, v[96:97], s[34:35] offset:0
	global_store_dwordx2 v2, v[100:101], s[34:35] offset:512
	global_store_dwordx2 v2, v[104:105], s[34:35] offset:1024
	global_store_dwordx2 v2, v[108:109], s[34:35] offset:1536
	s_waitcnt vmcnt(16)
	v_lshlrev_b32_e32 v128, 16, v130
	v_and_b32_e32 v129, 0xffff0000, v130
	v_lshlrev_b32_e32 v130, 16, v131
	v_and_b32_e32 v131, 0xffff0000, v131
	v_lshlrev_b32_e32 v132, 16, v134
	v_and_b32_e32 v133, 0xffff0000, v134
	v_lshlrev_b32_e32 v134, 16, v135
	v_and_b32_e32 v135, 0xffff0000, v135
	v_lshlrev_b32_e32 v136, 16, v138
	v_and_b32_e32 v137, 0xffff0000, v138
	v_lshlrev_b32_e32 v138, 16, v139
	v_and_b32_e32 v139, 0xffff0000, v139
	v_lshlrev_b32_e32 v140, 16, v142
	v_and_b32_e32 v141, 0xffff0000, v142
	v_lshlrev_b32_e32 v142, 16, v143
	v_and_b32_e32 v143, 0xffff0000, v143
	v_lshlrev_b32_e32 v160, 16, v162
	v_and_b32_e32 v161, 0xffff0000, v162
	v_lshlrev_b32_e32 v162, 16, v163
	v_and_b32_e32 v163, 0xffff0000, v163
	v_lshlrev_b32_e32 v164, 16, v166
	v_and_b32_e32 v165, 0xffff0000, v166
	v_lshlrev_b32_e32 v166, 16, v167
	v_and_b32_e32 v167, 0xffff0000, v167
	v_lshlrev_b32_e32 v168, 16, v170
	v_and_b32_e32 v169, 0xffff0000, v170
	v_lshlrev_b32_e32 v170, 16, v171
	v_and_b32_e32 v171, 0xffff0000, v171
	v_lshlrev_b32_e32 v172, 16, v174
	v_and_b32_e32 v173, 0xffff0000, v174
	v_lshlrev_b32_e32 v174, 16, v175
	v_and_b32_e32 v175, 0xffff0000, v175
	v_mul_f32_e32 v10, v128, v128
	v_fmac_f32_e32 v10, v129, v129
	v_fmac_f32_e32 v10, v130, v130
	v_fmac_f32_e32 v10, v131, v131
	v_fmac_f32_e32 v10, v132, v132
	v_fmac_f32_e32 v10, v133, v133
	v_fmac_f32_e32 v10, v134, v134
	v_fmac_f32_e32 v10, v135, v135
	v_fmac_f32_e32 v10, v136, v136
	v_fmac_f32_e32 v10, v137, v137
	v_fmac_f32_e32 v10, v138, v138
	v_fmac_f32_e32 v10, v139, v139
	v_fmac_f32_e32 v10, v140, v140
	v_fmac_f32_e32 v10, v141, v141
	v_fmac_f32_e32 v10, v142, v142
	v_fmac_f32_e32 v10, v143, v143
	v_mul_f32_e32 v11, v160, v160
	v_fmac_f32_e32 v11, v161, v161
	v_fmac_f32_e32 v11, v162, v162
	v_fmac_f32_e32 v11, v163, v163
	v_fmac_f32_e32 v11, v164, v164
	v_fmac_f32_e32 v11, v165, v165
	v_fmac_f32_e32 v11, v166, v166
	v_fmac_f32_e32 v11, v167, v167
	v_fmac_f32_e32 v11, v168, v168
	v_fmac_f32_e32 v11, v169, v169
	v_fmac_f32_e32 v11, v170, v170
	v_fmac_f32_e32 v11, v171, v171
	v_fmac_f32_e32 v11, v172, v172
	v_fmac_f32_e32 v11, v173, v173
	v_fmac_f32_e32 v11, v174, v174
	v_fmac_f32_e32 v11, v175, v175
	ds_bpermute_b32 v12, v4, v10
	ds_bpermute_b32 v13, v4, v11
	s_waitcnt lgkmcnt(0)
	v_add_f32_e32 v10, v10, v12
	v_add_f32_e32 v11, v11, v13
	ds_bpermute_b32 v12, v5, v10
	ds_bpermute_b32 v13, v5, v11
	s_waitcnt lgkmcnt(0)
	v_add_f32_e32 v10, v10, v12
	v_add_f32_e32 v11, v11, v13
	ds_bpermute_b32 v12, v6, v10
	ds_bpermute_b32 v13, v6, v11
	s_waitcnt lgkmcnt(0)
	v_add_f32_e32 v10, v10, v12
	v_add_f32_e32 v11, v11, v13
	ds_bpermute_b32 v12, v7, v10
	ds_bpermute_b32 v13, v7, v11
	s_waitcnt lgkmcnt(0)
	v_add_f32_e32 v10, v10, v12
	v_add_f32_e32 v11, v11, v13
	ds_bpermute_b32 v12, v8, v10
	ds_bpermute_b32 v13, v8, v11
	s_waitcnt lgkmcnt(0)
	v_add_f32_e32 v10, v10, v12
	v_add_f32_e32 v11, v11, v13
	ds_bpermute_b32 v12, v9, v10
	ds_bpermute_b32 v13, v9, v11
	s_waitcnt lgkmcnt(0)
	v_add_f32_e32 v10, v10, v12
	v_add_f32_e32 v11, v11, v13
	v_fma_f32 v14, v10, s17, v3
	v_fma_f32 v15, v11, s17, v3
	v_rsq_f32_e32 v14, v14
	v_rsq_f32_e32 v15, v15
	s_nop 0
	v_mul_f32_e32 v128, v128, v14
	v_mul_f32_e32 v129, v129, v14
	v_mul_f32_e32 v130, v130, v14
	v_mul_f32_e32 v131, v131, v14
	v_mul_f32_e32 v132, v132, v14
	v_mul_f32_e32 v133, v133, v14
	v_mul_f32_e32 v134, v134, v14
	v_mul_f32_e32 v135, v135, v14
	v_mul_f32_e32 v136, v136, v14
	v_mul_f32_e32 v137, v137, v14
	v_mul_f32_e32 v138, v138, v14
	v_mul_f32_e32 v139, v139, v14
	v_mul_f32_e32 v140, v140, v14
	v_mul_f32_e32 v141, v141, v14
	v_mul_f32_e32 v142, v142, v14
	v_mul_f32_e32 v143, v143, v14
	v_fmac_f32_e32 v144, v128, v20
	v_fmac_f32_e32 v145, v129, v21
	v_fmac_f32_e32 v146, v130, v22
	v_fmac_f32_e32 v147, v131, v23
	v_fmac_f32_e32 v148, v132, v24
	v_fmac_f32_e32 v149, v133, v25
	v_fmac_f32_e32 v150, v134, v26
	v_fmac_f32_e32 v151, v135, v27
	v_fmac_f32_e32 v152, v136, v28
	v_fmac_f32_e32 v153, v137, v29
	v_fmac_f32_e32 v154, v138, v30
	v_fmac_f32_e32 v155, v139, v31
	v_fmac_f32_e32 v156, v140, v32
	v_fmac_f32_e32 v157, v141, v33
	v_fmac_f32_e32 v158, v142, v34
	v_fmac_f32_e32 v159, v143, v35
	global_store_dwordx4 v1, v[144:147], s[40:41] offset:0 nt
	global_store_dwordx4 v1, v[148:151], s[40:41] offset:1024 nt
	global_store_dwordx4 v1, v[152:155], s[40:41] offset:2048 nt
	global_store_dwordx4 v1, v[156:159], s[40:41] offset:3072 nt
	v_mul_f32_e32 v160, v160, v15
	v_mul_f32_e32 v161, v161, v15
	v_mul_f32_e32 v162, v162, v15
	v_mul_f32_e32 v163, v163, v15
	v_mul_f32_e32 v164, v164, v15
	v_mul_f32_e32 v165, v165, v15
	v_mul_f32_e32 v166, v166, v15
	v_mul_f32_e32 v167, v167, v15
	v_mul_f32_e32 v168, v168, v15
	v_mul_f32_e32 v169, v169, v15
	v_mul_f32_e32 v170, v170, v15
	v_mul_f32_e32 v171, v171, v15
	v_mul_f32_e32 v172, v172, v15
	v_mul_f32_e32 v173, v173, v15
	v_mul_f32_e32 v174, v174, v15
	v_mul_f32_e32 v175, v175, v15
	v_fmac_f32_e32 v176, v160, v20
	v_fmac_f32_e32 v177, v161, v21
	v_fmac_f32_e32 v178, v162, v22
	v_fmac_f32_e32 v179, v163, v23
	v_fmac_f32_e32 v180, v164, v24
	v_fmac_f32_e32 v181, v165, v25
	v_fmac_f32_e32 v182, v166, v26
	v_fmac_f32_e32 v183, v167, v27
	v_fmac_f32_e32 v184, v168, v28
	v_fmac_f32_e32 v185, v169, v29
	v_fmac_f32_e32 v186, v170, v30
	v_fmac_f32_e32 v187, v171, v31
	v_fmac_f32_e32 v188, v172, v32
	v_fmac_f32_e32 v189, v173, v33
	v_fmac_f32_e32 v190, v174, v34
	v_fmac_f32_e32 v191, v175, v35
	global_store_dwordx4 v1, v[176:179], s[48:49] offset:0 nt
	global_store_dwordx4 v1, v[180:183], s[48:49] offset:1024 nt
	global_store_dwordx4 v1, v[184:187], s[48:49] offset:2048 nt
	global_store_dwordx4 v1, v[188:191], s[48:49] offset:3072 nt
	v_mul_f32_e32 v10, v144, v144
	v_fmac_f32_e32 v10, v145, v145
	v_fmac_f32_e32 v10, v146, v146
	v_fmac_f32_e32 v10, v147, v147
	v_fmac_f32_e32 v10, v148, v148
	v_fmac_f32_e32 v10, v149, v149
	v_fmac_f32_e32 v10, v150, v150
	v_fmac_f32_e32 v10, v151, v151
	v_fmac_f32_e32 v10, v152, v152
	v_fmac_f32_e32 v10, v153, v153
	v_fmac_f32_e32 v10, v154, v154
	v_fmac_f32_e32 v10, v155, v155
	v_fmac_f32_e32 v10, v156, v156
	v_fmac_f32_e32 v10, v157, v157
	v_fmac_f32_e32 v10, v158, v158
	v_fmac_f32_e32 v10, v159, v159
	v_mul_f32_e32 v11, v176, v176
	v_fmac_f32_e32 v11, v177, v177
	v_fmac_f32_e32 v11, v178, v178
	v_fmac_f32_e32 v11, v179, v179
	v_fmac_f32_e32 v11, v180, v180
	v_fmac_f32_e32 v11, v181, v181
	v_fmac_f32_e32 v11, v182, v182
	v_fmac_f32_e32 v11, v183, v183
	v_fmac_f32_e32 v11, v184, v184
	v_fmac_f32_e32 v11, v185, v185
	v_fmac_f32_e32 v11, v186, v186
	v_fmac_f32_e32 v11, v187, v187
	v_fmac_f32_e32 v11, v188, v188
	v_fmac_f32_e32 v11, v189, v189
	v_fmac_f32_e32 v11, v190, v190
	v_fmac_f32_e32 v11, v191, v191
	ds_bpermute_b32 v12, v4, v10
	ds_bpermute_b32 v13, v4, v11
	s_waitcnt lgkmcnt(0)
	v_add_f32_e32 v10, v10, v12
	v_add_f32_e32 v11, v11, v13
	ds_bpermute_b32 v12, v5, v10
	ds_bpermute_b32 v13, v5, v11
	s_waitcnt lgkmcnt(0)
	v_add_f32_e32 v10, v10, v12
	v_add_f32_e32 v11, v11, v13
	ds_bpermute_b32 v12, v6, v10
	ds_bpermute_b32 v13, v6, v11
	s_waitcnt lgkmcnt(0)
	v_add_f32_e32 v10, v10, v12
	v_add_f32_e32 v11, v11, v13
	ds_bpermute_b32 v12, v7, v10
	ds_bpermute_b32 v13, v7, v11
	s_waitcnt lgkmcnt(0)
	v_add_f32_e32 v10, v10, v12
	v_add_f32_e32 v11, v11, v13
	ds_bpermute_b32 v12, v8, v10
	ds_bpermute_b32 v13, v8, v11
	s_waitcnt lgkmcnt(0)
	v_add_f32_e32 v10, v10, v12
	v_add_f32_e32 v11, v11, v13
	ds_bpermute_b32 v12, v9, v10
	ds_bpermute_b32 v13, v9, v11
	s_waitcnt lgkmcnt(0)
	v_add_f32_e32 v10, v10, v12
	v_add_f32_e32 v11, v11, v13
	v_fma_f32 v14, v10, s17, v3
	v_fma_f32 v15, v11, s17, v3
	v_rsq_f32_e32 v14, v14
	v_rsq_f32_e32 v15, v15
	s_nop 0
	v_mul_f32_e32 v128, v144, v14
	v_mul_f32_e32 v129, v145, v14
	v_mul_f32_e32 v130, v146, v14
	v_mul_f32_e32 v131, v147, v14
	v_mul_f32_e32 v132, v148, v14
	v_mul_f32_e32 v133, v149, v14
	v_mul_f32_e32 v134, v150, v14
	v_mul_f32_e32 v135, v151, v14
	v_mul_f32_e32 v136, v152, v14
	v_mul_f32_e32 v137, v153, v14
	v_mul_f32_e32 v138, v154, v14
	v_mul_f32_e32 v139, v155, v14
	v_mul_f32_e32 v140, v156, v14
	v_mul_f32_e32 v141, v157, v14
	v_mul_f32_e32 v142, v158, v14
	v_mul_f32_e32 v143, v159, v14
	v_mul_f32_e32 v128, v128, v36
	v_mul_f32_e32 v129, v129, v37
	v_mul_f32_e32 v130, v130, v38
	v_mul_f32_e32 v131, v131, v39
	v_mul_f32_e32 v132, v132, v40
	v_mul_f32_e32 v133, v133, v41
	v_mul_f32_e32 v134, v134, v42
	v_mul_f32_e32 v135, v135, v43
	v_mul_f32_e32 v136, v136, v44
	v_mul_f32_e32 v137, v137, v45
	v_mul_f32_e32 v138, v138, v46
	v_mul_f32_e32 v139, v139, v47
	v_mul_f32_e32 v140, v140, v48
	v_mul_f32_e32 v141, v141, v49
	v_mul_f32_e32 v142, v142, v50
	v_mul_f32_e32 v143, v143, v51
	v_cvt_pk_bf16_f32 v128, v128, v129
	v_cvt_pk_bf16_f32 v129, v130, v131
	v_cvt_pk_bf16_f32 v132, v132, v133
	v_cvt_pk_bf16_f32 v133, v134, v135
	v_cvt_pk_bf16_f32 v136, v136, v137
	v_cvt_pk_bf16_f32 v137, v138, v139
	v_cvt_pk_bf16_f32 v140, v140, v141
	v_cvt_pk_bf16_f32 v141, v142, v143
	global_store_dwordx2 v2, v[128:129], s[42:43] offset:0
	global_store_dwordx2 v2, v[132:133], s[42:43] offset:512
	global_store_dwordx2 v2, v[136:137], s[42:43] offset:1024
	global_store_dwordx2 v2, v[140:141], s[42:43] offset:1536
	v_mul_f32_e32 v160, v176, v15
	v_mul_f32_e32 v161, v177, v15
	v_mul_f32_e32 v162, v178, v15
	v_mul_f32_e32 v163, v179, v15
	v_mul_f32_e32 v164, v180, v15
	v_mul_f32_e32 v165, v181, v15
	v_mul_f32_e32 v166, v182, v15
	v_mul_f32_e32 v167, v183, v15
	v_mul_f32_e32 v168, v184, v15
	v_mul_f32_e32 v169, v185, v15
	v_mul_f32_e32 v170, v186, v15
	v_mul_f32_e32 v171, v187, v15
	v_mul_f32_e32 v172, v188, v15
	v_mul_f32_e32 v173, v189, v15
	v_mul_f32_e32 v174, v190, v15
	v_mul_f32_e32 v175, v191, v15
	v_mul_f32_e32 v160, v160, v36
	v_mul_f32_e32 v161, v161, v37
	v_mul_f32_e32 v162, v162, v38
	v_mul_f32_e32 v163, v163, v39
	v_mul_f32_e32 v164, v164, v40
	v_mul_f32_e32 v165, v165, v41
	v_mul_f32_e32 v166, v166, v42
	v_mul_f32_e32 v167, v167, v43
	v_mul_f32_e32 v168, v168, v44
	v_mul_f32_e32 v169, v169, v45
	v_mul_f32_e32 v170, v170, v46
	v_mul_f32_e32 v171, v171, v47
	v_mul_f32_e32 v172, v172, v48
	v_mul_f32_e32 v173, v173, v49
	v_mul_f32_e32 v174, v174, v50
	v_mul_f32_e32 v175, v175, v51
	v_cvt_pk_bf16_f32 v160, v160, v161
	v_cvt_pk_bf16_f32 v161, v162, v163
	v_cvt_pk_bf16_f32 v164, v164, v165
	v_cvt_pk_bf16_f32 v165, v166, v167
	v_cvt_pk_bf16_f32 v168, v168, v169
	v_cvt_pk_bf16_f32 v169, v170, v171
	v_cvt_pk_bf16_f32 v172, v172, v173
	v_cvt_pk_bf16_f32 v173, v174, v175
	global_store_dwordx2 v2, v[160:161], s[50:51] offset:0
	global_store_dwordx2 v2, v[164:165], s[50:51] offset:512
	global_store_dwordx2 v2, v[168:169], s[50:51] offset:1024
	global_store_dwordx2 v2, v[172:173], s[50:51] offset:1536
	v_add_f32_e32 v208, v208, v212
	v_add_f32_e32 v209, v209, v213
	v_add_f32_e32 v210, v210, v214
	v_add_f32_e32 v211, v211, v215
	v_add_f32_e32 v216, v216, v220
	v_add_f32_e32 v217, v217, v221
	v_add_f32_e32 v218, v218, v222
	v_add_f32_e32 v219, v219, v223
	v_add_f32_e32 v224, v224, v228
	v_add_f32_e32 v225, v225, v229
	v_add_f32_e32 v226, v226, v230
	v_add_f32_e32 v227, v227, v231
	v_add_f32_e32 v232, v232, v236
	v_add_f32_e32 v233, v233, v237
	v_add_f32_e32 v234, v234, v238
	v_add_f32_e32 v235, v235, v239
	v_add_f32_e32 v208, v208, v216
	v_add_f32_e32 v209, v209, v217
	v_add_f32_e32 v210, v210, v218
	v_add_f32_e32 v211, v211, v219
	v_add_f32_e32 v224, v224, v232
	v_add_f32_e32 v225, v225, v233
	v_add_f32_e32 v226, v226, v234
	v_add_f32_e32 v227, v227, v235
	v_add_f32_e32 v208, v208, v224
	v_add_f32_e32 v209, v209, v225
	v_add_f32_e32 v210, v210, v226
	v_add_f32_e32 v211, v211, v227
	v_readfirstlane_b32 s18, v0
	s_lshr_b32 s18, s18, 6
	s_lshl_b32 s19, s18, 2
	s_and_b32 s52, s18, 4
	s_lshl_b32 s52, s52, 2
	v_mov_b32_e32 v16, s19
	v_mov_b32_e32 v17, s52
	v_mul_f32_e32 v10, v208, v208
	v_fmac_f32_e32 v10, v209, v209
	v_fmac_f32_e32 v10, v210, v210
	v_fmac_f32_e32 v10, v211, v211
	ds_bpermute_b32 v11, v4, v10
	s_waitcnt lgkmcnt(0)
	v_add_f32_e32 v10, v10, v11
	ds_bpermute_b32 v11, v5, v10
	s_waitcnt lgkmcnt(0)
	v_add_f32_e32 v10, v10, v11
	ds_bpermute_b32 v11, v6, v10
	s_waitcnt lgkmcnt(0)
	v_add_f32_e32 v10, v10, v11
	ds_bpermute_b32 v11, v7, v10
	s_waitcnt lgkmcnt(0)
	v_add_f32_e32 v10, v10, v11
	ds_bpermute_b32 v11, v8, v10
	s_waitcnt lgkmcnt(0)
	v_add_f32_e32 v10, v10, v11
	ds_bpermute_b32 v11, v9, v10
	s_waitcnt lgkmcnt(0)
	v_add_f32_e32 v10, v10, v11
	ds_write_b32 v16, v10 offset:0
	s_waitcnt lgkmcnt(0)
	s_barrier
	ds_read_b128 v[12:15], v17 offset:0
	s_waitcnt lgkmcnt(0)
	v_add_f32_e32 v12, v12, v13
	v_add_f32_e32 v14, v14, v15
	v_add_f32_e32 v10, v12, v14
	v_fma_f32 v11, v10, s17, v3
	v_rsq_f32_e32 v11, v11
	s_nop 0
	v_mul_f32_e32 v208, v208, v11
	v_mul_f32_e32 v209, v209, v11
	v_mul_f32_e32 v210, v210, v11
	v_mul_f32_e32 v211, v211, v11
	v_fmac_f32_e32 v240, v208, v244
	v_fmac_f32_e32 v241, v209, v245
	v_fmac_f32_e32 v242, v210, v246
	v_fmac_f32_e32 v243, v211, v247
	s_lshl_b32 s18, s54, 12
	s_add_u32 s18, s18, s55
	s_add_u32 s56, s4, s18
	s_addc_u32 s57, s5, 0
	s_add_u32 s56, s56, 0x4000000
	s_addc_u32 s57, s57, 0
	global_store_dwordx4 v1, v[240:243], s[56:57]
	v_mul_f32_e32 v10, v240, v240
	v_fmac_f32_e32 v10, v241, v241
	v_fmac_f32_e32 v10, v242, v242
	v_fmac_f32_e32 v10, v243, v243
	ds_bpermute_b32 v11, v4, v10
	s_waitcnt lgkmcnt(0)
	v_add_f32_e32 v10, v10, v11
	ds_bpermute_b32 v11, v5, v10
	s_waitcnt lgkmcnt(0)
	v_add_f32_e32 v10, v10, v11
	ds_bpermute_b32 v11, v6, v10
	s_waitcnt lgkmcnt(0)
	v_add_f32_e32 v10, v10, v11
	ds_bpermute_b32 v11, v7, v10
	s_waitcnt lgkmcnt(0)
	v_add_f32_e32 v10, v10, v11
	ds_bpermute_b32 v11, v8, v10
	s_waitcnt lgkmcnt(0)
	v_add_f32_e32 v10, v10, v11
	ds_bpermute_b32 v11, v9, v10
	s_waitcnt lgkmcnt(0)
	v_add_f32_e32 v10, v10, v11
	ds_write_b32 v16, v10 offset:64
	s_waitcnt lgkmcnt(0)
	s_barrier
	ds_read_b128 v[12:15], v17 offset:64
	s_waitcnt lgkmcnt(0)
	v_add_f32_e32 v12, v12, v13
	v_add_f32_e32 v14, v14, v15
	v_add_f32_e32 v10, v12, v14
	v_fma_f32 v11, v10, s17, v3
	v_rsq_f32_e32 v11, v11
	s_nop 0
	v_mul_f32_e32 v208, v240, v11
	v_mul_f32_e32 v209, v241, v11
	v_mul_f32_e32 v210, v242, v11
	v_mul_f32_e32 v211, v243, v11
	v_mul_f32_e32 v208, v208, v248
	v_mul_f32_e32 v209, v209, v249
	v_mul_f32_e32 v210, v210, v250
	v_mul_f32_e32 v211, v211, v251
	v_cvt_pk_bf16_f32 v208, v208, v209
	v_cvt_pk_bf16_f32 v209, v210, v211
	s_lshl_b32 s18, s54, 11
	s_lshr_b32 s19, s55, 1
	s_add_u32 s18, s18, s19
	s_add_u32 s56, s6, s18
	s_addc_u32 s57, s7, 0
	s_add_u32 s56, s56, 0x5100000
	s_addc_u32 s57, s57, 0
	global_store_dwordx2 v2, v[208:209], s[56:57]

_Z10fwd_kernelILi11ELi12EEv4Args:
	s_load_dword s3, s[0:1], 0xe8
	s_load_dwordx4 s[4:7], s[0:1], 0xd0
	s_load_dwordx2 s[8:9], s[0:1], 0xa8
	s_load_dwordx2 s[10:11], s[0:1], 0xb0
	s_waitcnt lgkmcnt(0)
	s_cmp_lg_u32 s3, 0x100
	s_cbranch_scc1 .Lrows11_orig
	s_add_u32 s8, s8, 0x1000
	s_addc_u32 s9, s9, 0
	s_add_u32 s10, s10, 0x1000
	s_addc_u32 s11, s11, 0
	v_readfirstlane_b32 s16, v0
	s_lshr_b32 s16, s16, 6
	s_lshl_b32 s18, s2, 3
	s_add_u32 s16, s16, s18
	s_mov_b32 s17, 0x3a800000
	v_mov_b32_e32 v3, 0x358637bd
	v_and_b32_e32 v10, 63, v0
	v_lshlrev_b32_e32 v1, 4, v10
	v_lshlrev_b32_e32 v2, 3, v10
	v_xor_b32_e32 v4, 1, v10
	v_xor_b32_e32 v5, 2, v10
	v_xor_b32_e32 v6, 4, v10
	v_xor_b32_e32 v7, 8, v10
	v_xor_b32_e32 v8, 16, v10
	v_xor_b32_e32 v9, 32, v10
	v_lshlrev_b32_e32 v4, 2, v4
	v_lshlrev_b32_e32 v5, 2, v5
	v_lshlrev_b32_e32 v6, 2, v6
	v_lshlrev_b32_e32 v7, 2, v7
	v_lshlrev_b32_e32 v8, 2, v8
	v_lshlrev_b32_e32 v9, 2, v9
	global_load_dwordx4 v[20:23], v1, s[8:9] offset:0
	global_load_dwordx4 v[24:27], v1, s[8:9] offset:1024
	global_load_dwordx4 v[28:31], v1, s[8:9] offset:2048
	global_load_dwordx4 v[32:35], v1, s[8:9] offset:3072
	global_load_dwordx4 v[36:39], v1, s[10:11] offset:0
	global_load_dwordx4 v[40:43], v1, s[10:11] offset:1024
	global_load_dwordx4 v[44:47], v1, s[10:11] offset:2048
	global_load_dwordx4 v[48:51], v1, s[10:11] offset:3072
	s_lshr_b32 s54, s16, 2
	s_and_b32 s55, s16, 3
	s_lshl_b32 s55, s55, 10
	s_lshl_b32 s18, s54, 12
	s_add_u32 s18, s18, s55
	s_add_u32 s56, s6, s18
	s_addc_u32 s57, s7, 0
	s_add_u32 s56, s56, 0x7400000
	s_addc_u32 s57, s57, 0
	global_load_dwordx4 v[208:211], v1, s[56:57]
	s_add_u32 s56, s56, 0x200000
	s_addc_u32 s57, s57, 0
	global_load_dwordx4 v[212:215], v1, s[56:57]
	s_add_u32 s56, s4, s18
	s_addc_u32 s57, s5, 0
	s_add_u32 s56, s56, 0x4000000
	s_addc_u32 s57, s57, 0
	global_load_dwordx4 v[240:243], v1, s[56:57]
	s_add_u32 s56, s8, s55
	s_addc_u32 s57, s9, 0
	global_load_dwordx4 v[244:247], v1, s[56:57]
	s_add_u32 s56, s10, s55
	s_addc_u32 s57, s11, 0
	global_load_dwordx4 v[248:251], v1, s[56:57]
	s_add_u32 s53, s16, 0x0
	s_lshl_b32 s18, s53, 12
	s_lshl_b32 s19, s53, 11
	s_add_u32 s20, s4, s18
	s_addc_u32 s21, s5, 0
	s_add_u32 s22, s6, s19
	s_addc_u32 s23, s7, 0
	s_add_u32 s22, s22, 0x5200000
	s_addc_u32 s23, s23, 0
	s_add_u32 s24, s4, s18
	s_addc_u32 s25, s5, 0
	s_add_u32 s26, s6, s19
	s_addc_u32 s27, s7, 0
	s_add_u32 s26, s26, 0x3100000
	s_addc_u32 s27, s27, 0
	global_load_dwordx2 v[66:67], v2, s[22:23] offset:0
	global_load_dwordx2 v[70:71], v2, s[22:23] offset:512
	global_load_dwordx2 v[74:75], v2, s[22:23] offset:1024
	global_load_dwordx2 v[78:79], v2, s[22:23] offset:1536
	global_load_dwordx4 v[80:83], v1, s[20:21] offset:0
	global_load_dwordx4 v[84:87], v1, s[20:21] offset:1024
	global_load_dwordx4 v[88:91], v1, s[20:21] offset:2048
	global_load_dwordx4 v[92:95], v1, s[20:21] offset:3072
	s_add_u32 s53, s16, 0x800
	s_lshl_b32 s18, s53, 12
	s_lshl_b32 s19, s53, 11
	s_add_u32 s28, s4, s18
	s_addc_u32 s29, s5, 0
	s_add_u32 s30, s6, s19
	s_addc_u32 s31, s7, 0
	s_add_u32 s30, s30, 0x5200000
	s_addc_u32 s31, s31, 0
	s_add_u32 s32, s4, s18
	s_addc_u32 s33, s5, 0
	s_add_u32 s34, s6, s19
	s_addc_u32 s35, s7, 0
	s_add_u32 s34, s34, 0x3100000
	s_addc_u32 s35, s35, 0
	global_load_dwordx2 v[98:99], v2, s[30:31] offset:0
	global_load_dwordx2 v[102:103], v2, s[30:31] offset:512
	global_load_dwordx2 v[106:107], v2, s[30:31] offset:1024
	global_load_dwordx2 v[110:111], v2, s[30:31] offset:1536
	global_load_dwordx4 v[112:115], v1, s[28:29] offset:0
	global_load_dwordx4 v[116:119], v1, s[28:29] offset:1024
	global_load_dwordx4 v[120:123], v1, s[28:29] offset:2048
	global_load_dwordx4 v[124:127], v1, s[28:29] offset:3072
	s_add_u32 s53, s16, 0x1000
	s_lshl_b32 s18, s53, 12
	s_lshl_b32 s19, s53, 11
	s_add_u32 s36, s4, s18
	s_addc_u32 s37, s5, 0
	s_add_u32 s38, s6, s19
	s_addc_u32 s39, s7, 0
	s_add_u32 s38, s38, 0x5200000
	s_addc_u32 s39, s39, 0
	s_add_u32 s40, s4, s18
	s_addc_u32 s41, s5, 0
	s_add_u32 s42, s6, s19
	s_addc_u32 s43, s7, 0
	s_add_u32 s42, s42, 0x3100000
	s_addc_u32 s43, s43, 0
	global_load_dwordx2 v[130:131], v2, s[38:39] offset:0
	global_load_dwordx2 v[134:135], v2, s[38:39] offset:512
	global_load_dwordx2 v[138:139], v2, s[38:39] offset:1024
	global_load_dwordx2 v[142:143], v2, s[38:39] offset:1536
	global_load_dwordx4 v[144:147], v1, s[36:37] offset:0
	global_load_dwordx4 v[148:151], v1, s[36:37] offset:1024
	global_load_dwordx4 v[152:155], v1, s[36:37] offset:2048
	global_load_dwordx4 v[156:159], v1, s[36:37] offset:3072
	s_add_u32 s53, s16, 0x1800
	s_lshl_b32 s18, s53, 12
	s_lshl_b32 s19, s53, 11
	s_add_u32 s44, s4, s18
	s_addc_u32 s45, s5, 0
	s_add_u32 s46, s6, s19
	s_addc_u32 s47, s7, 0
	s_add_u32 s46, s46, 0x5200000
	s_addc_u32 s47, s47, 0
	s_add_u32 s48, s4, s18
	s_addc_u32 s49, s5, 0
	s_add_u32 s50, s6, s19
	s_addc_u32 s51, s7, 0
	s_add_u32 s50, s50, 0x3100000
	s_addc_u32 s51, s51, 0
	global_load_dwordx2 v[162:163], v2, s[46:47] offset:0
	global_load_dwordx2 v[166:167], v2, s[46:47] offset:512
	global_load_dwordx2 v[170:171], v2, s[46:47] offset:1024
	global_load_dwordx2 v[174:175], v2, s[46:47] offset:1536
	global_load_dwordx4 v[176:179], v1, s[44:45] offset:0
	global_load_dwordx4 v[180:183], v1, s[44:45] offset:1024
	global_load_dwordx4 v[184:187], v1, s[44:45] offset:2048
	global_load_dwordx4 v[188:191], v1, s[44:45] offset:3072
	s_waitcnt vmcnt(16)
	v_lshlrev_b32_e32 v64, 16, v66
	v_and_b32_e32 v65, 0xffff0000, v66
	v_lshlrev_b32_e32 v66, 16, v67
	v_and_b32_e32 v67, 0xffff0000, v67
	v_lshlrev_b32_e32 v68, 16, v70
	v_and_b32_e32 v69, 0xffff0000, v70
	v_lshlrev_b32_e32 v70, 16, v71
	v_and_b32_e32 v71, 0xffff0000, v71
	v_lshlrev_b32_e32 v72, 16, v74
	v_and_b32_e32 v73, 0xffff0000, v74
	v_lshlrev_b32_e32 v74, 16, v75
	v_and_b32_e32 v75, 0xffff0000, v75
	v_lshlrev_b32_e32 v76, 16, v78
	v_and_b32_e32 v77, 0xffff0000, v78
	v_lshlrev_b32_e32 v78, 16, v79
	v_and_b32_e32 v79, 0xffff0000, v79
	v_lshlrev_b32_e32 v96, 16, v98
	v_and_b32_e32 v97, 0xffff0000, v98
	v_lshlrev_b32_e32 v98, 16, v99
	v_and_b32_e32 v99, 0xffff0000, v99
	v_lshlrev_b32_e32 v100, 16, v102
	v_and_b32_e32 v101, 0xffff0000, v102
	v_lshlrev_b32_e32 v102, 16, v103
	v_and_b32_e32 v103, 0xffff0000, v103
	v_lshlrev_b32_e32 v104, 16, v106
	v_and_b32_e32 v105, 0xffff0000, v106
	v_lshlrev_b32_e32 v106, 16, v107
	v_and_b32_e32 v107, 0xffff0000, v107
	v_lshlrev_b32_e32 v108, 16, v110
	v_and_b32_e32 v109, 0xffff0000, v110
	v_lshlrev_b32_e32 v110, 16, v111
	v_and_b32_e32 v111, 0xffff0000, v111
	v_mul_f32_e32 v10, v64, v64
	v_fmac_f32_e32 v10, v65, v65
	v_fmac_f32_e32 v10, v66, v66
	v_fmac_f32_e32 v10, v67, v67
	v_fmac_f32_e32 v10, v68, v68
	v_fmac_f32_e32 v10, v69, v69
	v_fmac_f32_e32 v10, v70, v70
	v_fmac_f32_e32 v10, v71, v71
	v_fmac_f32_e32 v10, v72, v72
	v_fmac_f32_e32 v10, v73, v73
	v_fmac_f32_e32 v10, v74, v74
	v_fmac_f32_e32 v10, v75, v75
	v_fmac_f32_e32 v10, v76, v76
	v_fmac_f32_e32 v10, v77, v77
	v_fmac_f32_e32 v10, v78, v78
	v_fmac_f32_e32 v10, v79, v79
	v_mul_f32_e32 v11, v96, v96
	v_fmac_f32_e32 v11, v97, v97
	v_fmac_f32_e32 v11, v98, v98
	v_fmac_f32_e32 v11, v99, v99
	v_fmac_f32_e32 v11, v100, v100
	v_fmac_f32_e32 v11, v101, v101
	v_fmac_f32_e32 v11, v102, v102
	v_fmac_f32_e32 v11, v103, v103
	v_fmac_f32_e32 v11, v104, v104
	v_fmac_f32_e32 v11, v105, v105
	v_fmac_f32_e32 v11, v106, v106
	v_fmac_f32_e32 v11, v107, v107
	v_fmac_f32_e32 v11, v108, v108
	v_fmac_f32_e32 v11, v109, v109
	v_fmac_f32_e32 v11, v110, v110
	v_fmac_f32_e32 v11, v111, v111
	ds_bpermute_b32 v12, v4, v10
	ds_bpermute_b32 v13, v4, v11
	s_waitcnt lgkmcnt(0)
	v_add_f32_e32 v10, v10, v12
	v_add_f32_e32 v11, v11, v13
	ds_bpermute_b32 v12, v5, v10
	ds_bpermute_b32 v13, v5, v11
	s_waitcnt lgkmcnt(0)
	v_add_f32_e32 v10, v10, v12
	v_add_f32_e32 v11, v11, v13
	ds_bpermute_b32 v12, v6, v10
	ds_bpermute_b32 v13, v6, v11
	s_waitcnt lgkmcnt(0)
	v_add_f32_e32 v10, v10, v12
	v_add_f32_e32 v11, v11, v13
	ds_bpermute_b32 v12, v7, v10
	ds_bpermute_b32 v13, v7, v11
	s_waitcnt lgkmcnt(0)
	v_add_f32_e32 v10, v10, v12
	v_add_f32_e32 v11, v11, v13
	ds_bpermute_b32 v12, v8, v10
	ds_bpermute_b32 v13, v8, v11
	s_waitcnt lgkmcnt(0)
	v_add_f32_e32 v10, v10, v12
	v_add_f32_e32 v11, v11, v13
	ds_bpermute_b32 v12, v9, v10
	ds_bpermute_b32 v13, v9, v11
	s_waitcnt lgkmcnt(0)
	v_add_f32_e32 v10, v10, v12
	v_add_f32_e32 v11, v11, v13
	v_fma_f32 v14, v10, s17, v3
	v_fma_f32 v15, v11, s17, v3
	v_rsq_f32_e32 v14, v14
	v_rsq_f32_e32 v15, v15
	s_nop 0
	v_mul_f32_e32 v64, v64, v14
	v_mul_f32_e32 v65, v65, v14
	v_mul_f32_e32 v66, v66, v14
	v_mul_f32_e32 v67, v67, v14
	v_mul_f32_e32 v68, v68, v14
	v_mul_f32_e32 v69, v69, v14
	v_mul_f32_e32 v70, v70, v14
	v_mul_f32_e32 v71, v71, v14
	v_mul_f32_e32 v72, v72, v14
	v_mul_f32_e32 v73, v73, v14
	v_mul_f32_e32 v74, v74, v14
	v_mul_f32_e32 v75, v75, v14
	v_mul_f32_e32 v76, v76, v14
	v_mul_f32_e32 v77, v77, v14
	v_mul_f32_e32 v78, v78, v14
	v_mul_f32_e32 v79, v79, v14
	v_fmac_f32_e32 v80, v64, v20
	v_fmac_f32_e32 v81, v65, v21
	v_fmac_f32_e32 v82, v66, v22
	v_fmac_f32_e32 v83, v67, v23
	v_fmac_f32_e32 v84, v68, v24
	v_fmac_f32_e32 v85, v69, v25
	v_fmac_f32_e32 v86, v70, v26
	v_fmac_f32_e32 v87, v71, v27
	v_fmac_f32_e32 v88, v72, v28
	v_fmac_f32_e32 v89, v73, v29
	v_fmac_f32_e32 v90, v74, v30
	v_fmac_f32_e32 v91, v75, v31
	v_fmac_f32_e32 v92, v76, v32
	v_fmac_f32_e32 v93, v77, v33
	v_fmac_f32_e32 v94, v78, v34
	v_fmac_f32_e32 v95, v79, v35
	global_store_dwordx4 v1, v[80:83], s[24:25] offset:0 nt
	global_store_dwordx4 v1, v[84:87], s[24:25] offset:1024 nt
	global_store_dwordx4 v1, v[88:91], s[24:25] offset:2048 nt
	global_store_dwordx4 v1, v[92:95], s[24:25] offset:3072 nt
	v_mul_f32_e32 v96, v96, v15
	v_mul_f32_e32 v97, v97, v15
	v_mul_f32_e32 v98, v98, v15
	v_mul_f32_e32 v99, v99, v15
	v_mul_f32_e32 v100, v100, v15
	v_mul_f32_e32 v101, v101, v15
	v_mul_f32_e32 v102, v102, v15
	v_mul_f32_e32 v103, v103, v15
	v_mul_f32_e32 v104, v104, v15
	v_mul_f32_e32 v105, v105, v15
	v_mul_f32_e32 v106, v106, v15
	v_mul_f32_e32 v107, v107, v15
	v_mul_f32_e32 v108, v108, v15
	v_mul_f32_e32 v109, v109, v15
	v_mul_f32_e32 v110, v110, v15
	v_mul_f32_e32 v111, v111, v15
	v_fmac_f32_e32 v112, v96, v20
	v_fmac_f32_e32 v113, v97, v21
	v_fmac_f32_e32 v114, v98, v22
	v_fmac_f32_e32 v115, v99, v23
	v_fmac_f32_e32 v116, v100, v24
	v_fmac_f32_e32 v117, v101, v25
	v_fmac_f32_e32 v118, v102, v26
	v_fmac_f32_e32 v119, v103, v27
	v_fmac_f32_e32 v120, v104, v28
	v_fmac_f32_e32 v121, v105, v29
	v_fmac_f32_e32 v122, v106, v30
	v_fmac_f32_e32 v123, v107, v31
	v_fmac_f32_e32 v124, v108, v32
	v_fmac_f32_e32 v125, v109, v33
	v_fmac_f32_e32 v126, v110, v34
	v_fmac_f32_e32 v127, v111, v35
	global_store_dwordx4 v1, v[112:115], s[32:33] offset:0 nt
	global_store_dwordx4 v1, v[116:119], s[32:33] offset:1024 nt
	global_store_dwordx4 v1, v[120:123], s[32:33] offset:2048 nt
	global_store_dwordx4 v1, v[124:127], s[32:33] offset:3072 nt
	v_mul_f32_e32 v10, v80, v80
	v_fmac_f32_e32 v10, v81, v81
	v_fmac_f32_e32 v10, v82, v82
	v_fmac_f32_e32 v10, v83, v83
	v_fmac_f32_e32 v10, v84, v84
	v_fmac_f32_e32 v10, v85, v85
	v_fmac_f32_e32 v10, v86, v86
	v_fmac_f32_e32 v10, v87, v87
	v_fmac_f32_e32 v10, v88, v88
	v_fmac_f32_e32 v10, v89, v89
	v_fmac_f32_e32 v10, v90, v90
	v_fmac_f32_e32 v10, v91, v91
	v_fmac_f32_e32 v10, v92, v92
	v_fmac_f32_e32 v10, v93, v93
	v_fmac_f32_e32 v10, v94, v94
	v_fmac_f32_e32 v10, v95, v95
	v_mul_f32_e32 v11, v112, v112
	v_fmac_f32_e32 v11, v113, v113
	v_fmac_f32_e32 v11, v114, v114
	v_fmac_f32_e32 v11, v115, v115
	v_fmac_f32_e32 v11, v116, v116
	v_fmac_f32_e32 v11, v117, v117
	v_fmac_f32_e32 v11, v118, v118
	v_fmac_f32_e32 v11, v119, v119
	v_fmac_f32_e32 v11, v120, v120
	v_fmac_f32_e32 v11, v121, v121
	v_fmac_f32_e32 v11, v122, v122
	v_fmac_f32_e32 v11, v123, v123
	v_fmac_f32_e32 v11, v124, v124
	v_fmac_f32_e32 v11, v125, v125
	v_fmac_f32_e32 v11, v126, v126
	v_fmac_f32_e32 v11, v127, v127
	ds_bpermute_b32 v12, v4, v10
	ds_bpermute_b32 v13, v4, v11
	s_waitcnt lgkmcnt(0)
	v_add_f32_e32 v10, v10, v12
	v_add_f32_e32 v11, v11, v13
	ds_bpermute_b32 v12, v5, v10
	ds_bpermute_b32 v13, v5, v11
	s_waitcnt lgkmcnt(0)
	v_add_f32_e32 v10, v10, v12
	v_add_f32_e32 v11, v11, v13
	ds_bpermute_b32 v12, v6, v10
	ds_bpermute_b32 v13, v6, v11
	s_waitcnt lgkmcnt(0)
	v_add_f32_e32 v10, v10, v12
	v_add_f32_e32 v11, v11, v13
	ds_bpermute_b32 v12, v7, v10
	ds_bpermute_b32 v13, v7, v11
	s_waitcnt lgkmcnt(0)
	v_add_f32_e32 v10, v10, v12
	v_add_f32_e32 v11, v11, v13
	ds_bpermute_b32 v12, v8, v10
	ds_bpermute_b32 v13, v8, v11
	s_waitcnt lgkmcnt(0)
	v_add_f32_e32 v10, v10, v12
	v_add_f32_e32 v11, v11, v13
	ds_bpermute_b32 v12, v9, v10
	ds_bpermute_b32 v13, v9, v11
	s_waitcnt lgkmcnt(0)
	v_add_f32_e32 v10, v10, v12
	v_add_f32_e32 v11, v11, v13
	v_fma_f32 v14, v10, s17, v3
	v_fma_f32 v15, v11, s17, v3
	v_rsq_f32_e32 v14, v14
	v_rsq_f32_e32 v15, v15
	s_nop 0
	v_mul_f32_e32 v64, v80, v14
	v_mul_f32_e32 v65, v81, v14
	v_mul_f32_e32 v66, v82, v14
	v_mul_f32_e32 v67, v83, v14
	v_mul_f32_e32 v68, v84, v14
	v_mul_f32_e32 v69, v85, v14
	v_mul_f32_e32 v70, v86, v14
	v_mul_f32_e32 v71, v87, v14
	v_mul_f32_e32 v72, v88, v14
	v_mul_f32_e32 v73, v89, v14
	v_mul_f32_e32 v74, v90, v14
	v_mul_f32_e32 v75, v91, v14
	v_mul_f32_e32 v76, v92, v14
	v_mul_f32_e32 v77, v93, v14
	v_mul_f32_e32 v78, v94, v14
	v_mul_f32_e32 v79, v95, v14
	v_mul_f32_e32 v64, v64, v36
	v_mul_f32_e32 v65, v65, v37
	v_mul_f32_e32 v66, v66, v38
	v_mul_f32_e32 v67, v67, v39
	v_mul_f32_e32 v68, v68, v40
	v_mul_f32_e32 v69, v69, v41
	v_mul_f32_e32 v70, v70, v42
	v_mul_f32_e32 v71, v71, v43
	v_mul_f32_e32 v72, v72, v44
	v_mul_f32_e32 v73, v73, v45
	v_mul_f32_e32 v74, v74, v46
	v_mul_f32_e32 v75, v75, v47
	v_mul_f32_e32 v76, v76, v48
	v_mul_f32_e32 v77, v77, v49
	v_mul_f32_e32 v78, v78, v50
	v_mul_f32_e32 v79, v79, v51
	v_cvt_pk_bf16_f32 v64, v64, v65
	v_cvt_pk_bf16_f32 v65, v66, v67
	v_cvt_pk_bf16_f32 v68, v68, v69
	v_cvt_pk_bf16_f32 v69, v70, v71
	v_cvt_pk_bf16_f32 v72, v72, v73
	v_cvt_pk_bf16_f32 v73, v74, v75
	v_cvt_pk_bf16_f32 v76, v76, v77
	v_cvt_pk_bf16_f32 v77, v78, v79
	global_store_dwordx2 v2, v[64:65], s[26:27] offset:0
	global_store_dwordx2 v2, v[68:69], s[26:27] offset:512
	global_store_dwordx2 v2, v[72:73], s[26:27] offset:1024
	global_store_dwordx2 v2, v[76:77], s[26:27] offset:1536
	v_mul_f32_e32 v96, v112, v15
	v_mul_f32_e32 v97, v113, v15
	v_mul_f32_e32 v98, v114, v15
	v_mul_f32_e32 v99, v115, v15
	v_mul_f32_e32 v100, v116, v15
	v_mul_f32_e32 v101, v117, v15
	v_mul_f32_e32 v102, v118, v15
	v_mul_f32_e32 v103, v119, v15
	v_mul_f32_e32 v104, v120, v15
	v_mul_f32_e32 v105, v121, v15
	v_mul_f32_e32 v106, v122, v15
	v_mul_f32_e32 v107, v123, v15
	v_mul_f32_e32 v108, v124, v15
	v_mul_f32_e32 v109, v125, v15
	v_mul_f32_e32 v110, v126, v15
	v_mul_f32_e32 v111, v127, v15
	v_mul_f32_e32 v96, v96, v36
	v_mul_f32_e32 v97, v97, v37
	v_mul_f32_e32 v98, v98, v38
	v_mul_f32_e32 v99, v99, v39
	v_mul_f32_e32 v100, v100, v40
	v_mul_f32_e32 v101, v101, v41
	v_mul_f32_e32 v102, v102, v42
	v_mul_f32_e32 v103, v103, v43
	v_mul_f32_e32 v104, v104, v44
	v_mul_f32_e32 v105, v105, v45
	v_mul_f32_e32 v106, v106, v46
	v_mul_f32_e32 v107, v107, v47
	v_mul_f32_e32 v108, v108, v48
	v_mul_f32_e32 v109, v109, v49
	v_mul_f32_e32 v110, v110, v50
	v_mul_f32_e32 v111, v111, v51
	v_cvt_pk_bf16_f32 v96, v96, v97
	v_cvt_pk_bf16_f32 v97, v98, v99
	v_cvt_pk_bf16_f32 v100, v100, v101
	v_cvt_pk_bf16_f32 v101, v102, v103
	v_cvt_pk_bf16_f32 v104, v104, v105
	v_cvt_pk_bf16_f32 v105, v106, v107
	v_cvt_pk_bf16_f32 v108, v108, v109
	v_cvt_pk_bf16_f32 v109, v110, v111
	global_store_dwordx2 v2, v[96:97], s[34:35] offset:0
	global_store_dwordx2 v2, v[100:101], s[34:35] offset:512
	global_store_dwordx2 v2, v[104:105], s[34:35] offset:1024
	global_store_dwordx2 v2, v[108:109], s[34:35] offset:1536
	s_add_u32 s53, s16, 0x2000
	s_lshl_b32 s18, s53, 12
	s_lshl_b32 s19, s53, 11
	s_add_u32 s20, s4, s18
	s_addc_u32 s21, s5, 0
	s_add_u32 s22, s6, s19
	s_addc_u32 s23, s7, 0
	s_add_u32 s22, s22, 0x5200000
	s_addc_u32 s23, s23, 0
	s_add_u32 s24, s4, s18
	s_addc_u32 s25, s5, 0
	s_add_u32 s26, s6, s19
	s_addc_u32 s27, s7, 0
	s_add_u32 s26, s26, 0x3100000
	s_addc_u32 s27, s27, 0
	global_load_dwordx2 v[66:67], v2, s[22:23] offset:0
	global_load_dwordx2 v[70:71], v2, s[22:23] offset:512
	global_load_dwordx2 v[74:75], v2, s[22:23] offset:1024
	global_load_dwordx2 v[78:79], v2, s[22:23] offset:1536
	global_load_dwordx4 v[80:83], v1, s[20:21] offset:0
	global_load_dwordx4 v[84:87], v1, s[20:21] offset:1024
	global_load_dwordx4 v[88:91], v1, s[20:21] offset:2048
	global_load_dwordx4 v[92:95], v1, s[20:21] offset:3072
	s_add_u32 s53, s16, 0x2800
	s_lshl_b32 s18, s53, 12
	s_lshl_b32 s19, s53, 11
	s_add_u32 s28, s4, s18
	s_addc_u32 s29, s5, 0
	s_add_u32 s30, s6, s19
	s_addc_u32 s31, s7, 0
	s_add_u32 s30, s30, 0x5200000
	s_addc_u32 s31, s31, 0
	s_add_u32 s32, s4, s18
	s_addc_u32 s33, s5, 0
	s_add_u32 s34, s6, s19
	s_addc_u32 s35, s7, 0
	s_add_u32 s34, s34, 0x3100000
	s_addc_u32 s35, s35, 0
	global_load_dwordx2 v[98:99], v2, s[30:31] offset:0
	global_load_dwordx2 v[102:103], v2, s[30:31] offset:512
	global_load_dwordx2 v[106:107], v2, s[30:31] offset:1024
	global_load_dwordx2 v[110:111], v2, s[30:31] offset:1536
	global_load_dwordx4 v[112:115], v1, s[28:29] offset:0
	global_load_dwordx4 v[116:119], v1, s[28:29] offset:1024
	global_load_dwordx4 v[120:123], v1, s[28:29] offset:2048
	global_load_dwordx4 v[124:127], v1, s[28:29] offset:3072
	s_waitcnt vmcnt(32)
	v_lshlrev_b32_e32 v128, 16, v130
	v_and_b32_e32 v129, 0xffff0000, v130
	v_lshlrev_b32_e32 v130, 16, v131
	v_and_b32_e32 v131, 0xffff0000, v131
	v_lshlrev_b32_e32 v132, 16, v134
	v_and_b32_e32 v133, 0xffff0000, v134
	v_lshlrev_b32_e32 v134, 16, v135
	v_and_b32_e32 v135, 0xffff0000, v135
	v_lshlrev_b32_e32 v136, 16, v138
	v_and_b32_e32 v137, 0xffff0000, v138
	v_lshlrev_b32_e32 v138, 16, v139
	v_and_b32_e32 v139, 0xffff0000, v139
	v_lshlrev_b32_e32 v140, 16, v142
	v_and_b32_e32 v141, 0xffff0000, v142
	v_lshlrev_b32_e32 v142, 16, v143
	v_and_b32_e32 v143, 0xffff0000, v143
	v_lshlrev_b32_e32 v160, 16, v162
	v_and_b32_e32 v161, 0xffff0000, v162
	v_lshlrev_b32_e32 v162, 16, v163
	v_and_b32_e32 v163, 0xffff0000, v163
	v_lshlrev_b32_e32 v164, 16, v166
	v_and_b32_e32 v165, 0xffff0000, v166
	v_lshlrev_b32_e32 v166, 16, v167
	v_and_b32_e32 v167, 0xffff0000, v167
	v_lshlrev_b32_e32 v168, 16, v170
	v_and_b32_e32 v169, 0xffff0000, v170
	v_lshlrev_b32_e32 v170, 16, v171
	v_and_b32_e32 v171, 0xffff0000, v171
	v_lshlrev_b32_e32 v172, 16, v174
	v_and_b32_e32 v173, 0xffff0000, v174
	v_lshlrev_b32_e32 v174, 16, v175
	v_and_b32_e32 v175, 0xffff0000, v175
	v_mul_f32_e32 v10, v128, v128
	v_fmac_f32_e32 v10, v129, v129
	v_fmac_f32_e32 v10, v130, v130
	v_fmac_f32_e32 v10, v131, v131
	v_fmac_f32_e32 v10, v132, v132
	v_fmac_f32_e32 v10, v133, v133
	v_fmac_f32_e32 v10, v134, v134
	v_fmac_f32_e32 v10, v135, v135
	v_fmac_f32_e32 v10, v136, v136
	v_fmac_f32_e32 v10, v137, v137
	v_fmac_f32_e32 v10, v138, v138
	v_fmac_f32_e32 v10, v139, v139
	v_fmac_f32_e32 v10, v140, v140
	v_fmac_f32_e32 v10, v141, v141
	v_fmac_f32_e32 v10, v142, v142
	v_fmac_f32_e32 v10, v143, v143
	v_mul_f32_e32 v11, v160, v160
	v_fmac_f32_e32 v11, v161, v161
	v_fmac_f32_e32 v11, v162, v162
	v_fmac_f32_e32 v11, v163, v163
	v_fmac_f32_e32 v11, v164, v164
	v_fmac_f32_e32 v11, v165, v165
	v_fmac_f32_e32 v11, v166, v166
	v_fmac_f32_e32 v11, v167, v167
	v_fmac_f32_e32 v11, v168, v168
	v_fmac_f32_e32 v11, v169, v169
	v_fmac_f32_e32 v11, v170, v170
	v_fmac_f32_e32 v11, v171, v171
	v_fmac_f32_e32 v11, v172, v172
	v_fmac_f32_e32 v11, v173, v173
	v_fmac_f32_e32 v11, v174, v174
	v_fmac_f32_e32 v11, v175, v175
	ds_bpermute_b32 v12, v4, v10
	ds_bpermute_b32 v13, v4, v11
	s_waitcnt lgkmcnt(0)
	v_add_f32_e32 v10, v10, v12
	v_add_f32_e32 v11, v11, v13
	ds_bpermute_b32 v12, v5, v10
	ds_bpermute_b32 v13, v5, v11
	s_waitcnt lgkmcnt(0)
	v_add_f32_e32 v10, v10, v12
	v_add_f32_e32 v11, v11, v13
	ds_bpermute_b32 v12, v6, v10
	ds_bpermute_b32 v13, v6, v11
	s_waitcnt lgkmcnt(0)
	v_add_f32_e32 v10, v10, v12
	v_add_f32_e32 v11, v11, v13
	ds_bpermute_b32 v12, v7, v10
	ds_bpermute_b32 v13, v7, v11
	s_waitcnt lgkmcnt(0)
	v_add_f32_e32 v10, v10, v12
	v_add_f32_e32 v11, v11, v13
	ds_bpermute_b32 v12, v8, v10
	ds_bpermute_b32 v13, v8, v11
	s_waitcnt lgkmcnt(0)
	v_add_f32_e32 v10, v10, v12
	v_add_f32_e32 v11, v11, v13
	ds_bpermute_b32 v12, v9, v10
	ds_bpermute_b32 v13, v9, v11
	s_waitcnt lgkmcnt(0)
	v_add_f32_e32 v10, v10, v12
	v_add_f32_e32 v11, v11, v13
	v_fma_f32 v14, v10, s17, v3
	v_fma_f32 v15, v11, s17, v3
	v_rsq_f32_e32 v14, v14
	v_rsq_f32_e32 v15, v15
	s_nop 0
	v_mul_f32_e32 v128, v128, v14
	v_mul_f32_e32 v129, v129, v14
	v_mul_f32_e32 v130, v130, v14
	v_mul_f32_e32 v131, v131, v14
	v_mul_f32_e32 v132, v132, v14
	v_mul_f32_e32 v133, v133, v14
	v_mul_f32_e32 v134, v134, v14
	v_mul_f32_e32 v135, v135, v14
	v_mul_f32_e32 v136, v136, v14
	v_mul_f32_e32 v137, v137, v14
	v_mul_f32_e32 v138, v138, v14
	v_mul_f32_e32 v139, v139, v14
	v_mul_f32_e32 v140, v140, v14
	v_mul_f32_e32 v141, v141, v14
	v_mul_f32_e32 v142, v142, v14
	v_mul_f32_e32 v143, v143, v14
	v_fmac_f32_e32 v144, v128, v20
	v_fmac_f32_e32 v145, v129, v21
	v_fmac_f32_e32 v146, v130, v22
	v_fmac_f32_e32 v147, v131, v23
	v_fmac_f32_e32 v148, v132, v24
	v_fmac_f32_e32 v149, v133, v25
	v_fmac_f32_e32 v150, v134, v26
	v_fmac_f32_e32 v151, v135, v27
	v_fmac_f32_e32 v152, v136, v28
	v_fmac_f32_e32 v153, v137, v29
	v_fmac_f32_e32 v154, v138, v30
	v_fmac_f32_e32 v155, v139, v31
	v_fmac_f32_e32 v156, v140, v32
	v_fmac_f32_e32 v157, v141, v33
	v_fmac_f32_e32 v158, v142, v34
	v_fmac_f32_e32 v159, v143, v35
	global_store_dwordx4 v1, v[144:147], s[40:41] offset:0 nt
	global_store_dwordx4 v1, v[148:151], s[40:41] offset:1024 nt
	global_store_dwordx4 v1, v[152:155], s[40:41] offset:2048 nt
	global_store_dwordx4 v1, v[156:159], s[40:41] offset:3072 nt
	v_mul_f32_e32 v160, v160, v15
	v_mul_f32_e32 v161, v161, v15
	v_mul_f32_e32 v162, v162, v15
	v_mul_f32_e32 v163, v163, v15
	v_mul_f32_e32 v164, v164, v15
	v_mul_f32_e32 v165, v165, v15
	v_mul_f32_e32 v166, v166, v15
	v_mul_f32_e32 v167, v167, v15
	v_mul_f32_e32 v168, v168, v15
	v_mul_f32_e32 v169, v169, v15
	v_mul_f32_e32 v170, v170, v15
	v_mul_f32_e32 v171, v171, v15
	v_mul_f32_e32 v172, v172, v15
	v_mul_f32_e32 v173, v173, v15
	v_mul_f32_e32 v174, v174, v15
	v_mul_f32_e32 v175, v175, v15
	v_fmac_f32_e32 v176, v160, v20
	v_fmac_f32_e32 v177, v161, v21
	v_fmac_f32_e32 v178, v162, v22
	v_fmac_f32_e32 v179, v163, v23
	v_fmac_f32_e32 v180, v164, v24
	v_fmac_f32_e32 v181, v165, v25
	v_fmac_f32_e32 v182, v166, v26
	v_fmac_f32_e32 v183, v167, v27
	v_fmac_f32_e32 v184, v168, v28
	v_fmac_f32_e32 v185, v169, v29
	v_fmac_f32_e32 v186, v170, v30
	v_fmac_f32_e32 v187, v171, v31
	v_fmac_f32_e32 v188, v172, v32
	v_fmac_f32_e32 v189, v173, v33
	v_fmac_f32_e32 v190, v174, v34
	v_fmac_f32_e32 v191, v175, v35
	global_store_dwordx4 v1, v[176:179], s[48:49] offset:0 nt
	global_store_dwordx4 v1, v[180:183], s[48:49] offset:1024 nt
	global_store_dwordx4 v1, v[184:187], s[48:49] offset:2048 nt
	global_store_dwordx4 v1, v[188:191], s[48:49] offset:3072 nt
	v_mul_f32_e32 v10, v144, v144
	v_fmac_f32_e32 v10, v145, v145
	v_fmac_f32_e32 v10, v146, v146
	v_fmac_f32_e32 v10, v147, v147
	v_fmac_f32_e32 v10, v148, v148
	v_fmac_f32_e32 v10, v149, v149
	v_fmac_f32_e32 v10, v150, v150
	v_fmac_f32_e32 v10, v151, v151
	v_fmac_f32_e32 v10, v152, v152
	v_fmac_f32_e32 v10, v153, v153
	v_fmac_f32_e32 v10, v154, v154
	v_fmac_f32_e32 v10, v155, v155
	v_fmac_f32_e32 v10, v156, v156
	v_fmac_f32_e32 v10, v157, v157
	v_fmac_f32_e32 v10, v158, v158
	v_fmac_f32_e32 v10, v159, v159
	v_mul_f32_e32 v11, v176, v176
	v_fmac_f32_e32 v11, v177, v177
	v_fmac_f32_e32 v11, v178, v178
	v_fmac_f32_e32 v11, v179, v179
	v_fmac_f32_e32 v11, v180, v180
	v_fmac_f32_e32 v11, v181, v181
	v_fmac_f32_e32 v11, v182, v182
	v_fmac_f32_e32 v11, v183, v183
	v_fmac_f32_e32 v11, v184, v184
	v_fmac_f32_e32 v11, v185, v185
	v_fmac_f32_e32 v11, v186, v186
	v_fmac_f32_e32 v11, v187, v187
	v_fmac_f32_e32 v11, v188, v188
	v_fmac_f32_e32 v11, v189, v189
	v_fmac_f32_e32 v11, v190, v190
	v_fmac_f32_e32 v11, v191, v191
	ds_bpermute_b32 v12, v4, v10
	ds_bpermute_b32 v13, v4, v11
	s_waitcnt lgkmcnt(0)
	v_add_f32_e32 v10, v10, v12
	v_add_f32_e32 v11, v11, v13
	ds_bpermute_b32 v12, v5, v10
	ds_bpermute_b32 v13, v5, v11
	s_waitcnt lgkmcnt(0)
	v_add_f32_e32 v10, v10, v12
	v_add_f32_e32 v11, v11, v13
	ds_bpermute_b32 v12, v6, v10
	ds_bpermute_b32 v13, v6, v11
	s_waitcnt lgkmcnt(0)
	v_add_f32_e32 v10, v10, v12
	v_add_f32_e32 v11, v11, v13
	ds_bpermute_b32 v12, v7, v10
	ds_bpermute_b32 v13, v7, v11
	s_waitcnt lgkmcnt(0)
	v_add_f32_e32 v10, v10, v12
	v_add_f32_e32 v11, v11, v13
	ds_bpermute_b32 v12, v8, v10
	ds_bpermute_b32 v13, v8, v11
	s_waitcnt lgkmcnt(0)
	v_add_f32_e32 v10, v10, v12
	v_add_f32_e32 v11, v11, v13
	ds_bpermute_b32 v12, v9, v10
	ds_bpermute_b32 v13, v9, v11
	s_waitcnt lgkmcnt(0)
	v_add_f32_e32 v10, v10, v12
	v_add_f32_e32 v11, v11, v13
	v_fma_f32 v14, v10, s17, v3
	v_fma_f32 v15, v11, s17, v3
	v_rsq_f32_e32 v14, v14
	v_rsq_f32_e32 v15, v15
	s_nop 0
	v_mul_f32_e32 v128, v144, v14
	v_mul_f32_e32 v129, v145, v14
	v_mul_f32_e32 v130, v146, v14
	v_mul_f32_e32 v131, v147, v14
	v_mul_f32_e32 v132, v148, v14
	v_mul_f32_e32 v133, v149, v14
	v_mul_f32_e32 v134, v150, v14
	v_mul_f32_e32 v135, v151, v14
	v_mul_f32_e32 v136, v152, v14
	v_mul_f32_e32 v137, v153, v14
	v_mul_f32_e32 v138, v154, v14
	v_mul_f32_e32 v139, v155, v14
	v_mul_f32_e32 v140, v156, v14
	v_mul_f32_e32 v141, v157, v14
	v_mul_f32_e32 v142, v158, v14
	v_mul_f32_e32 v143, v159, v14
	v_mul_f32_e32 v128, v128, v36
	v_mul_f32_e32 v129, v129, v37
	v_mul_f32_e32 v130, v130, v38
	v_mul_f32_e32 v131, v131, v39
	v_mul_f32_e32 v132, v132, v40
	v_mul_f32_e32 v133, v133, v41
	v_mul_f32_e32 v134, v134, v42
	v_mul_f32_e32 v135, v135, v43
	v_mul_f32_e32 v136, v136, v44
	v_mul_f32_e32 v137, v137, v45
	v_mul_f32_e32 v138, v138, v46
	v_mul_f32_e32 v139, v139, v47
	v_mul_f32_e32 v140, v140, v48
	v_mul_f32_e32 v141, v141, v49
	v_mul_f32_e32 v142, v142, v50
	v_mul_f32_e32 v143, v143, v51
	v_cvt_pk_bf16_f32 v128, v128, v129
	v_cvt_pk_bf16_f32 v129, v130, v131
	v_cvt_pk_bf16_f32 v132, v132, v133
	v_cvt_pk_bf16_f32 v133, v134, v135
	v_cvt_pk_bf16_f32 v136, v136, v137
	v_cvt_pk_bf16_f32 v137, v138, v139
	v_cvt_pk_bf16_f32 v140, v140, v141
	v_cvt_pk_bf16_f32 v141, v142, v143
	global_store_dwordx2 v2, v[128:129], s[42:43] offset:0
	global_store_dwordx2 v2, v[132:133], s[42:43] offset:512
	global_store_dwordx2 v2, v[136:137], s[42:43] offset:1024
	global_store_dwordx2 v2, v[140:141], s[42:43] offset:1536
	v_mul_f32_e32 v160, v176, v15
	v_mul_f32_e32 v161, v177, v15
	v_mul_f32_e32 v162, v178, v15
	v_mul_f32_e32 v163, v179, v15
	v_mul_f32_e32 v164, v180, v15
	v_mul_f32_e32 v165, v181, v15
	v_mul_f32_e32 v166, v182, v15
	v_mul_f32_e32 v167, v183, v15
	v_mul_f32_e32 v168, v184, v15
	v_mul_f32_e32 v169, v185, v15
	v_mul_f32_e32 v170, v186, v15
	v_mul_f32_e32 v171, v187, v15
	v_mul_f32_e32 v172, v188, v15
	v_mul_f32_e32 v173, v189, v15
	v_mul_f32_e32 v174, v190, v15
	v_mul_f32_e32 v175, v191, v15
	v_mul_f32_e32 v160, v160, v36
	v_mul_f32_e32 v161, v161, v37
	v_mul_f32_e32 v162, v162, v38
	v_mul_f32_e32 v163, v163, v39
	v_mul_f32_e32 v164, v164, v40
	v_mul_f32_e32 v165, v165, v41
	v_mul_f32_e32 v166, v166, v42
	v_mul_f32_e32 v167, v167, v43
	v_mul_f32_e32 v168, v168, v44
	v_mul_f32_e32 v169, v169, v45
	v_mul_f32_e32 v170, v170, v46
	v_mul_f32_e32 v171, v171, v47
	v_mul_f32_e32 v172, v172, v48
	v_mul_f32_e32 v173, v173, v49
	v_mul_f32_e32 v174, v174, v50
	v_mul_f32_e32 v175, v175, v51
	v_cvt_pk_bf16_f32 v160, v160, v161
	v_cvt_pk_bf16_f32 v161, v162, v163
	v_cvt_pk_bf16_f32 v164, v164, v165
	v_cvt_pk_bf16_f32 v165, v166, v167
	v_cvt_pk_bf16_f32 v168, v168, v169
	v_cvt_pk_bf16_f32 v169, v170, v171
	v_cvt_pk_bf16_f32 v172, v172, v173
	v_cvt_pk_bf16_f32 v173, v174, v175
	global_store_dwordx2 v2, v[160:161], s[50:51] offset:0
	global_store_dwordx2 v2, v[164:165], s[50:51] offset:512
	global_store_dwordx2 v2, v[168:169], s[50:51] offset:1024
	global_store_dwordx2 v2, v[172:173], s[50:51] offset:1536
	s_add_u32 s53, s16, 0x3000
	s_lshl_b32 s18, s53, 12
	s_lshl_b32 s19, s53, 11
	s_add_u32 s36, s4, s18
	s_addc_u32 s37, s5, 0
	s_add_u32 s38, s6, s19
	s_addc_u32 s39, s7, 0
	s_add_u32 s38, s38, 0x5200000
	s_addc_u32 s39, s39, 0
	s_add_u32 s40, s4, s18
	s_addc_u32 s41, s5, 0
	s_add_u32 s42, s6, s19
	s_addc_u32 s43, s7, 0
	s_add_u32 s42, s42, 0x3100000
	s_addc_u32 s43, s43, 0
	global_load_dwordx2 v[130:131], v2, s[38:39] offset:0
	global_load_dwordx2 v[134:135], v2, s[38:39] offset:512
	global_load_dwordx2 v[138:139], v2, s[38:39] offset:1024
	global_load_dwordx2 v[142:143], v2, s[38:39] offset:1536
	global_load_dwordx4 v[144:147], v1, s[36:37] offset:0
	global_load_dwordx4 v[148:151], v1, s[36:37] offset:1024
	global_load_dwordx4 v[152:155], v1, s[36:37] offset:2048
	global_load_dwordx4 v[156:159], v1, s[36:37] offset:3072
	s_add_u32 s53, s16, 0x3800
	s_lshl_b32 s18, s53, 12
	s_lshl_b32 s19, s53, 11
	s_add_u32 s44, s4, s18
	s_addc_u32 s45, s5, 0
	s_add_u32 s46, s6, s19
	s_addc_u32 s47, s7, 0
	s_add_u32 s46, s46, 0x5200000
	s_addc_u32 s47, s47, 0
	s_add_u32 s48, s4, s18
	s_addc_u32 s49, s5, 0
	s_add_u32 s50, s6, s19
	s_addc_u32 s51, s7, 0
	s_add_u32 s50, s50, 0x3100000
	s_addc_u32 s51, s51, 0
	global_load_dwordx2 v[162:163], v2, s[46:47] offset:0
	global_load_dwordx2 v[166:167], v2, s[46:47] offset:512
	global_load_dwordx2 v[170:171], v2, s[46:47] offset:1024
	global_load_dwordx2 v[174:175], v2, s[46:47] offset:1536
	global_load_dwordx4 v[176:179], v1, s[44:45] offset:0
	global_load_dwordx4 v[180:183], v1, s[44:45] offset:1024
	global_load_dwordx4 v[184:187], v1, s[44:45] offset:2048
	global_load_dwordx4 v[188:191], v1, s[44:45] offset:3072
	s_waitcnt vmcnt(32)
	v_lshlrev_b32_e32 v64, 16, v66
	v_and_b32_e32 v65, 0xffff0000, v66
	v_lshlrev_b32_e32 v66, 16, v67
	v_and_b32_e32 v67, 0xffff0000, v67
	v_lshlrev_b32_e32 v68, 16, v70
	v_and_b32_e32 v69, 0xffff0000, v70
	v_lshlrev_b32_e32 v70, 16, v71
	v_and_b32_e32 v71, 0xffff0000, v71
	v_lshlrev_b32_e32 v72, 16, v74
	v_and_b32_e32 v73, 0xffff0000, v74
	v_lshlrev_b32_e32 v74, 16, v75
	v_and_b32_e32 v75, 0xffff0000, v75
	v_lshlrev_b32_e32 v76, 16, v78
	v_and_b32_e32 v77, 0xffff0000, v78
	v_lshlrev_b32_e32 v78, 16, v79
	v_and_b32_e32 v79, 0xffff0000, v79
	v_lshlrev_b32_e32 v96, 16, v98
	v_and_b32_e32 v97, 0xffff0000, v98
	v_lshlrev_b32_e32 v98, 16, v99
	v_and_b32_e32 v99, 0xffff0000, v99
	v_lshlrev_b32_e32 v100, 16, v102
	v_and_b32_e32 v101, 0xffff0000, v102
	v_lshlrev_b32_e32 v102, 16, v103
	v_and_b32_e32 v103, 0xffff0000, v103
	v_lshlrev_b32_e32 v104, 16, v106
	v_and_b32_e32 v105, 0xffff0000, v106
	v_lshlrev_b32_e32 v106, 16, v107
	v_and_b32_e32 v107, 0xffff0000, v107
	v_lshlrev_b32_e32 v108, 16, v110
	v_and_b32_e32 v109, 0xffff0000, v110
	v_lshlrev_b32_e32 v110, 16, v111
	v_and_b32_e32 v111, 0xffff0000, v111
	v_mul_f32_e32 v10, v64, v64
	v_fmac_f32_e32 v10, v65, v65
	v_fmac_f32_e32 v10, v66, v66
	v_fmac_f32_e32 v10, v67, v67
	v_fmac_f32_e32 v10, v68, v68
	v_fmac_f32_e32 v10, v69, v69
	v_fmac_f32_e32 v10, v70, v70
	v_fmac_f32_e32 v10, v71, v71
	v_fmac_f32_e32 v10, v72, v72
	v_fmac_f32_e32 v10, v73, v73
	v_fmac_f32_e32 v10, v74, v74
	v_fmac_f32_e32 v10, v75, v75
	v_fmac_f32_e32 v10, v76, v76
	v_fmac_f32_e32 v10, v77, v77
	v_fmac_f32_e32 v10, v78, v78
	v_fmac_f32_e32 v10, v79, v79
	v_mul_f32_e32 v11, v96, v96
	v_fmac_f32_e32 v11, v97, v97
	v_fmac_f32_e32 v11, v98, v98
	v_fmac_f32_e32 v11, v99, v99
	v_fmac_f32_e32 v11, v100, v100
	v_fmac_f32_e32 v11, v101, v101
	v_fmac_f32_e32 v11, v102, v102
	v_fmac_f32_e32 v11, v103, v103
	v_fmac_f32_e32 v11, v104, v104
	v_fmac_f32_e32 v11, v105, v105
	v_fmac_f32_e32 v11, v106, v106
	v_fmac_f32_e32 v11, v107, v107
	v_fmac_f32_e32 v11, v108, v108
	v_fmac_f32_e32 v11, v109, v109
	v_fmac_f32_e32 v11, v110, v110
	v_fmac_f32_e32 v11, v111, v111
	ds_bpermute_b32 v12, v4, v10
	ds_bpermute_b32 v13, v4, v11
	s_waitcnt lgkmcnt(0)
	v_add_f32_e32 v10, v10, v12
	v_add_f32_e32 v11, v11, v13
	ds_bpermute_b32 v12, v5, v10
	ds_bpermute_b32 v13, v5, v11
	s_waitcnt lgkmcnt(0)
	v_add_f32_e32 v10, v10, v12
	v_add_f32_e32 v11, v11, v13
	ds_bpermute_b32 v12, v6, v10
	ds_bpermute_b32 v13, v6, v11
	s_waitcnt lgkmcnt(0)
	v_add_f32_e32 v10, v10, v12
	v_add_f32_e32 v11, v11, v13
	ds_bpermute_b32 v12, v7, v10
	ds_bpermute_b32 v13, v7, v11
	s_waitcnt lgkmcnt(0)
	v_add_f32_e32 v10, v10, v12
	v_add_f32_e32 v11, v11, v13
	ds_bpermute_b32 v12, v8, v10
	ds_bpermute_b32 v13, v8, v11
	s_waitcnt lgkmcnt(0)
	v_add_f32_e32 v10, v10, v12
	v_add_f32_e32 v11, v11, v13
	ds_bpermute_b32 v12, v9, v10
	ds_bpermute_b32 v13, v9, v11
	s_waitcnt lgkmcnt(0)
	v_add_f32_e32 v10, v10, v12
	v_add_f32_e32 v11, v11, v13
	v_fma_f32 v14, v10, s17, v3
	v_fma_f32 v15, v11, s17, v3
	v_rsq_f32_e32 v14, v14
	v_rsq_f32_e32 v15, v15
	s_nop 0
	v_mul_f32_e32 v64, v64, v14
	v_mul_f32_e32 v65, v65, v14
	v_mul_f32_e32 v66, v66, v14
	v_mul_f32_e32 v67, v67, v14
	v_mul_f32_e32 v68, v68, v14
	v_mul_f32_e32 v69, v69, v14
	v_mul_f32_e32 v70, v70, v14
	v_mul_f32_e32 v71, v71, v14
	v_mul_f32_e32 v72, v72, v14
	v_mul_f32_e32 v73, v73, v14
	v_mul_f32_e32 v74, v74, v14
	v_mul_f32_e32 v75, v75, v14
	v_mul_f32_e32 v76, v76, v14
	v_mul_f32_e32 v77, v77, v14
	v_mul_f32_e32 v78, v78, v14
	v_mul_f32_e32 v79, v79, v14
	v_fmac_f32_e32 v80, v64, v20
	v_fmac_f32_e32 v81, v65, v21
	v_fmac_f32_e32 v82, v66, v22
	v_fmac_f32_e32 v83, v67, v23
	v_fmac_f32_e32 v84, v68, v24
	v_fmac_f32_e32 v85, v69, v25
	v_fmac_f32_e32 v86, v70, v26
	v_fmac_f32_e32 v87, v71, v27
	v_fmac_f32_e32 v88, v72, v28
	v_fmac_f32_e32 v89, v73, v29
	v_fmac_f32_e32 v90, v74, v30
	v_fmac_f32_e32 v91, v75, v31
	v_fmac_f32_e32 v92, v76, v32
	v_fmac_f32_e32 v93, v77, v33
	v_fmac_f32_e32 v94, v78, v34
	v_fmac_f32_e32 v95, v79, v35
	global_store_dwordx4 v1, v[80:83], s[24:25] offset:0 nt
	global_store_dwordx4 v1, v[84:87], s[24:25] offset:1024 nt
	global_store_dwordx4 v1, v[88:91], s[24:25] offset:2048 nt
	global_store_dwordx4 v1, v[92:95], s[24:25] offset:3072 nt
	v_mul_f32_e32 v96, v96, v15
	v_mul_f32_e32 v97, v97, v15
	v_mul_f32_e32 v98, v98, v15
	v_mul_f32_e32 v99, v99, v15
	v_mul_f32_e32 v100, v100, v15
	v_mul_f32_e32 v101, v101, v15
	v_mul_f32_e32 v102, v102, v15
	v_mul_f32_e32 v103, v103, v15
	v_mul_f32_e32 v104, v104, v15
	v_mul_f32_e32 v105, v105, v15
	v_mul_f32_e32 v106, v106, v15
	v_mul_f32_e32 v107, v107, v15
	v_mul_f32_e32 v108, v108, v15
	v_mul_f32_e32 v109, v109, v15
	v_mul_f32_e32 v110, v110, v15
	v_mul_f32_e32 v111, v111, v15
	v_fmac_f32_e32 v112, v96, v20
	v_fmac_f32_e32 v113, v97, v21
	v_fmac_f32_e32 v114, v98, v22
	v_fmac_f32_e32 v115, v99, v23
	v_fmac_f32_e32 v116, v100, v24
	v_fmac_f32_e32 v117, v101, v25
	v_fmac_f32_e32 v118, v102, v26
	v_fmac_f32_e32 v119, v103, v27
	v_fmac_f32_e32 v120, v104, v28
	v_fmac_f32_e32 v121, v105, v29
	v_fmac_f32_e32 v122, v106, v30
	v_fmac_f32_e32 v123, v107, v31
	v_fmac_f32_e32 v124, v108, v32
	v_fmac_f32_e32 v125, v109, v33
	v_fmac_f32_e32 v126, v110, v34
	v_fmac_f32_e32 v127, v111, v35
	global_store_dwordx4 v1, v[112:115], s[32:33] offset:0 nt
	global_store_dwordx4 v1, v[116:119], s[32:33] offset:1024 nt
	global_store_dwordx4 v1, v[120:123], s[32:33] offset:2048 nt
	global_store_dwordx4 v1, v[124:127], s[32:33] offset:3072 nt
	v_mul_f32_e32 v10, v80, v80
	v_fmac_f32_e32 v10, v81, v81
	v_fmac_f32_e32 v10, v82, v82
	v_fmac_f32_e32 v10, v83, v83
	v_fmac_f32_e32 v10, v84, v84
	v_fmac_f32_e32 v10, v85, v85
	v_fmac_f32_e32 v10, v86, v86
	v_fmac_f32_e32 v10, v87, v87
	v_fmac_f32_e32 v10, v88, v88
	v_fmac_f32_e32 v10, v89, v89
	v_fmac_f32_e32 v10, v90, v90
	v_fmac_f32_e32 v10, v91, v91
	v_fmac_f32_e32 v10, v92, v92
	v_fmac_f32_e32 v10, v93, v93
	v_fmac_f32_e32 v10, v94, v94
	v_fmac_f32_e32 v10, v95, v95
	v_mul_f32_e32 v11, v112, v112
	v_fmac_f32_e32 v11, v113, v113
	v_fmac_f32_e32 v11, v114, v114
	v_fmac_f32_e32 v11, v115, v115
	v_fmac_f32_e32 v11, v116, v116
	v_fmac_f32_e32 v11, v117, v117
	v_fmac_f32_e32 v11, v118, v118
	v_fmac_f32_e32 v11, v119, v119
	v_fmac_f32_e32 v11, v120, v120
	v_fmac_f32_e32 v11, v121, v121
	v_fmac_f32_e32 v11, v122, v122
	v_fmac_f32_e32 v11, v123, v123
	v_fmac_f32_e32 v11, v124, v124
	v_fmac_f32_e32 v11, v125, v125
	v_fmac_f32_e32 v11, v126, v126
	v_fmac_f32_e32 v11, v127, v127
	ds_bpermute_b32 v12, v4, v10
	ds_bpermute_b32 v13, v4, v11
	s_waitcnt lgkmcnt(0)
	v_add_f32_e32 v10, v10, v12
	v_add_f32_e32 v11, v11, v13
	ds_bpermute_b32 v12, v5, v10
	ds_bpermute_b32 v13, v5, v11
	s_waitcnt lgkmcnt(0)
	v_add_f32_e32 v10, v10, v12
	v_add_f32_e32 v11, v11, v13
	ds_bpermute_b32 v12, v6, v10
	ds_bpermute_b32 v13, v6, v11
	s_waitcnt lgkmcnt(0)
	v_add_f32_e32 v10, v10, v12
	v_add_f32_e32 v11, v11, v13
	ds_bpermute_b32 v12, v7, v10
	ds_bpermute_b32 v13, v7, v11
	s_waitcnt lgkmcnt(0)
	v_add_f32_e32 v10, v10, v12
	v_add_f32_e32 v11, v11, v13
	ds_bpermute_b32 v12, v8, v10
	ds_bpermute_b32 v13, v8, v11
	s_waitcnt lgkmcnt(0)
	v_add_f32_e32 v10, v10, v12
	v_add_f32_e32 v11, v11, v13
	ds_bpermute_b32 v12, v9, v10
	ds_bpermute_b32 v13, v9, v11
	s_waitcnt lgkmcnt(0)
	v_add_f32_e32 v10, v10, v12
	v_add_f32_e32 v11, v11, v13
	v_fma_f32 v14, v10, s17, v3
	v_fma_f32 v15, v11, s17, v3
	v_rsq_f32_e32 v14, v14
	v_rsq_f32_e32 v15, v15
	s_nop 0
	v_mul_f32_e32 v64, v80, v14
	v_mul_f32_e32 v65, v81, v14
	v_mul_f32_e32 v66, v82, v14
	v_mul_f32_e32 v67, v83, v14
	v_mul_f32_e32 v68, v84, v14
	v_mul_f32_e32 v69, v85, v14
	v_mul_f32_e32 v70, v86, v14
	v_mul_f32_e32 v71, v87, v14
	v_mul_f32_e32 v72, v88, v14
	v_mul_f32_e32 v73, v89, v14
	v_mul_f32_e32 v74, v90, v14
	v_mul_f32_e32 v75, v91, v14
	v_mul_f32_e32 v76, v92, v14
	v_mul_f32_e32 v77, v93, v14
	v_mul_f32_e32 v78, v94, v14
	v_mul_f32_e32 v79, v95, v14
	v_mul_f32_e32 v64, v64, v36
	v_mul_f32_e32 v65, v65, v37
	v_mul_f32_e32 v66, v66, v38
	v_mul_f32_e32 v67, v67, v39
	v_mul_f32_e32 v68, v68, v40
	v_mul_f32_e32 v69, v69, v41
	v_mul_f32_e32 v70, v70, v42
	v_mul_f32_e32 v71, v71, v43
	v_mul_f32_e32 v72, v72, v44
	v_mul_f32_e32 v73, v73, v45
	v_mul_f32_e32 v74, v74, v46
	v_mul_f32_e32 v75, v75, v47
	v_mul_f32_e32 v76, v76, v48
	v_mul_f32_e32 v77, v77, v49
	v_mul_f32_e32 v78, v78, v50
	v_mul_f32_e32 v79, v79, v51
	v_cvt_pk_bf16_f32 v64, v64, v65
	v_cvt_pk_bf16_f32 v65, v66, v67
	v_cvt_pk_bf16_f32 v68, v68, v69
	v_cvt_pk_bf16_f32 v69, v70, v71
	v_cvt_pk_bf16_f32 v72, v72, v73
	v_cvt_pk_bf16_f32 v73, v74, v75
	v_cvt_pk_bf16_f32 v76, v76, v77
	v_cvt_pk_bf16_f32 v77, v78, v79
	global_store_dwordx2 v2, v[64:65], s[26:27] offset:0
	global_store_dwordx2 v2, v[68:69], s[26:27] offset:512
	global_store_dwordx2 v2, v[72:73], s[26:27] offset:1024
	global_store_dwordx2 v2, v[76:77], s[26:27] offset:1536
	v_mul_f32_e32 v96, v112, v15
	v_mul_f32_e32 v97, v113, v15
	v_mul_f32_e32 v98, v114, v15
	v_mul_f32_e32 v99, v115, v15
	v_mul_f32_e32 v100, v116, v15
	v_mul_f32_e32 v101, v117, v15
	v_mul_f32_e32 v102, v118, v15
	v_mul_f32_e32 v103, v119, v15
	v_mul_f32_e32 v104, v120, v15
	v_mul_f32_e32 v105, v121, v15
	v_mul_f32_e32 v106, v122, v15
	v_mul_f32_e32 v107, v123, v15
	v_mul_f32_e32 v108, v124, v15
	v_mul_f32_e32 v109, v125, v15
	v_mul_f32_e32 v110, v126, v15
	v_mul_f32_e32 v111, v127, v15
	v_mul_f32_e32 v96, v96, v36
	v_mul_f32_e32 v97, v97, v37
	v_mul_f32_e32 v98, v98, v38
	v_mul_f32_e32 v99, v99, v39
	v_mul_f32_e32 v100, v100, v40
	v_mul_f32_e32 v101, v101, v41
	v_mul_f32_e32 v102, v102, v42
	v_mul_f32_e32 v103, v103, v43
	v_mul_f32_e32 v104, v104, v44
	v_mul_f32_e32 v105, v105, v45
	v_mul_f32_e32 v106, v106, v46
	v_mul_f32_e32 v107, v107, v47
	v_mul_f32_e32 v108, v108, v48
	v_mul_f32_e32 v109, v109, v49
	v_mul_f32_e32 v110, v110, v50
	v_mul_f32_e32 v111, v111, v51
	v_cvt_pk_bf16_f32 v96, v96, v97
	v_cvt_pk_bf16_f32 v97, v98, v99
	v_cvt_pk_bf16_f32 v100, v100, v101
	v_cvt_pk_bf16_f32 v101, v102, v103
	v_cvt_pk_bf16_f32 v104, v104, v105
	v_cvt_pk_bf16_f32 v105, v106, v107
	v_cvt_pk_bf16_f32 v108, v108, v109
	v_cvt_pk_bf16_f32 v109, v110, v111
	global_store_dwordx2 v2, v[96:97], s[34:35] offset:0
	global_store_dwordx2 v2, v[100:101], s[34:35] offset:512
	global_store_dwordx2 v2, v[104:105], s[34:35] offset:1024
	global_store_dwordx2 v2, v[108:109], s[34:35] offset:1536
	s_waitcnt vmcnt(16)
	v_lshlrev_b32_e32 v128, 16, v130
	v_and_b32_e32 v129, 0xffff0000, v130
	v_lshlrev_b32_e32 v130, 16, v131
	v_and_b32_e32 v131, 0xffff0000, v131
	v_lshlrev_b32_e32 v132, 16, v134
	v_and_b32_e32 v133, 0xffff0000, v134
	v_lshlrev_b32_e32 v134, 16, v135
	v_and_b32_e32 v135, 0xffff0000, v135
	v_lshlrev_b32_e32 v136, 16, v138
	v_and_b32_e32 v137, 0xffff0000, v138
	v_lshlrev_b32_e32 v138, 16, v139
	v_and_b32_e32 v139, 0xffff0000, v139
	v_lshlrev_b32_e32 v140, 16, v142
	v_and_b32_e32 v141, 0xffff0000, v142
	v_lshlrev_b32_e32 v142, 16, v143
	v_and_b32_e32 v143, 0xffff0000, v143
	v_lshlrev_b32_e32 v160, 16, v162
	v_and_b32_e32 v161, 0xffff0000, v162
	v_lshlrev_b32_e32 v162, 16, v163
	v_and_b32_e32 v163, 0xffff0000, v163
	v_lshlrev_b32_e32 v164, 16, v166
	v_and_b32_e32 v165, 0xffff0000, v166
	v_lshlrev_b32_e32 v166, 16, v167
	v_and_b32_e32 v167, 0xffff0000, v167
	v_lshlrev_b32_e32 v168, 16, v170
	v_and_b32_e32 v169, 0xffff0000, v170
	v_lshlrev_b32_e32 v170, 16, v171
	v_and_b32_e32 v171, 0xffff0000, v171
	v_lshlrev_b32_e32 v172, 16, v174
	v_and_b32_e32 v173, 0xffff0000, v174
	v_lshlrev_b32_e32 v174, 16, v175
	v_and_b32_e32 v175, 0xffff0000, v175
	v_mul_f32_e32 v10, v128, v128
	v_fmac_f32_e32 v10, v129, v129
	v_fmac_f32_e32 v10, v130, v130
	v_fmac_f32_e32 v10, v131, v131
	v_fmac_f32_e32 v10, v132, v132
	v_fmac_f32_e32 v10, v133, v133
	v_fmac_f32_e32 v10, v134, v134
	v_fmac_f32_e32 v10, v135, v135
	v_fmac_f32_e32 v10, v136, v136
	v_fmac_f32_e32 v10, v137, v137
	v_fmac_f32_e32 v10, v138, v138
	v_fmac_f32_e32 v10, v139, v139
	v_fmac_f32_e32 v10, v140, v140
	v_fmac_f32_e32 v10, v141, v141
	v_fmac_f32_e32 v10, v142, v142
	v_fmac_f32_e32 v10, v143, v143
	v_mul_f32_e32 v11, v160, v160
	v_fmac_f32_e32 v11, v161, v161
	v_fmac_f32_e32 v11, v162, v162
	v_fmac_f32_e32 v11, v163, v163
	v_fmac_f32_e32 v11, v164, v164
	v_fmac_f32_e32 v11, v165, v165
	v_fmac_f32_e32 v11, v166, v166
	v_fmac_f32_e32 v11, v167, v167
	v_fmac_f32_e32 v11, v168, v168
	v_fmac_f32_e32 v11, v169, v169
	v_fmac_f32_e32 v11, v170, v170
	v_fmac_f32_e32 v11, v171, v171
	v_fmac_f32_e32 v11, v172, v172
	v_fmac_f32_e32 v11, v173, v173
	v_fmac_f32_e32 v11, v174, v174
	v_fmac_f32_e32 v11, v175, v175
	ds_bpermute_b32 v12, v4, v10
	ds_bpermute_b32 v13, v4, v11
	s_waitcnt lgkmcnt(0)
	v_add_f32_e32 v10, v10, v12
	v_add_f32_e32 v11, v11, v13
	ds_bpermute_b32 v12, v5, v10
	ds_bpermute_b32 v13, v5, v11
	s_waitcnt lgkmcnt(0)
	v_add_f32_e32 v10, v10, v12
	v_add_f32_e32 v11, v11, v13
	ds_bpermute_b32 v12, v6, v10
	ds_bpermute_b32 v13, v6, v11
	s_waitcnt lgkmcnt(0)
	v_add_f32_e32 v10, v10, v12
	v_add_f32_e32 v11, v11, v13
	ds_bpermute_b32 v12, v7, v10
	ds_bpermute_b32 v13, v7, v11
	s_waitcnt lgkmcnt(0)
	v_add_f32_e32 v10, v10, v12
	v_add_f32_e32 v11, v11, v13
	ds_bpermute_b32 v12, v8, v10
	ds_bpermute_b32 v13, v8, v11
	s_waitcnt lgkmcnt(0)
	v_add_f32_e32 v10, v10, v12
	v_add_f32_e32 v11, v11, v13
	ds_bpermute_b32 v12, v9, v10
	ds_bpermute_b32 v13, v9, v11
	s_waitcnt lgkmcnt(0)
	v_add_f32_e32 v10, v10, v12
	v_add_f32_e32 v11, v11, v13
	v_fma_f32 v14, v10, s17, v3
	v_fma_f32 v15, v11, s17, v3
	v_rsq_f32_e32 v14, v14
	v_rsq_f32_e32 v15, v15
	s_nop 0
	v_mul_f32_e32 v128, v128, v14
	v_mul_f32_e32 v129, v129, v14
	v_mul_f32_e32 v130, v130, v14
	v_mul_f32_e32 v131, v131, v14
	v_mul_f32_e32 v132, v132, v14
	v_mul_f32_e32 v133, v133, v14
	v_mul_f32_e32 v134, v134, v14
	v_mul_f32_e32 v135, v135, v14
	v_mul_f32_e32 v136, v136, v14
	v_mul_f32_e32 v137, v137, v14
	v_mul_f32_e32 v138, v138, v14
	v_mul_f32_e32 v139, v139, v14
	v_mul_f32_e32 v140, v140, v14
	v_mul_f32_e32 v141, v141, v14
	v_mul_f32_e32 v142, v142, v14
	v_mul_f32_e32 v143, v143, v14
	v_fmac_f32_e32 v144, v128, v20
	v_fmac_f32_e32 v145, v129, v21
	v_fmac_f32_e32 v146, v130, v22
	v_fmac_f32_e32 v147, v131, v23
	v_fmac_f32_e32 v148, v132, v24
	v_fmac_f32_e32 v149, v133, v25
	v_fmac_f32_e32 v150, v134, v26
	v_fmac_f32_e32 v151, v135, v27
	v_fmac_f32_e32 v152, v136, v28
	v_fmac_f32_e32 v153, v137, v29
	v_fmac_f32_e32 v154, v138, v30
	v_fmac_f32_e32 v155, v139, v31
	v_fmac_f32_e32 v156, v140, v32
	v_fmac_f32_e32 v157, v141, v33
	v_fmac_f32_e32 v158, v142, v34
	v_fmac_f32_e32 v159, v143, v35
	global_store_dwordx4 v1, v[144:147], s[40:41] offset:0 nt
	global_store_dwordx4 v1, v[148:151], s[40:41] offset:1024 nt
	global_store_dwordx4 v1, v[152:155], s[40:41] offset:2048 nt
	global_store_dwordx4 v1, v[156:159], s[40:41] offset:3072 nt
	v_mul_f32_e32 v160, v160, v15
	v_mul_f32_e32 v161, v161, v15
	v_mul_f32_e32 v162, v162, v15
	v_mul_f32_e32 v163, v163, v15
	v_mul_f32_e32 v164, v164, v15
	v_mul_f32_e32 v165, v165, v15
	v_mul_f32_e32 v166, v166, v15
	v_mul_f32_e32 v167, v167, v15
	v_mul_f32_e32 v168, v168, v15
	v_mul_f32_e32 v169, v169, v15
	v_mul_f32_e32 v170, v170, v15
	v_mul_f32_e32 v171, v171, v15
	v_mul_f32_e32 v172, v172, v15
	v_mul_f32_e32 v173, v173, v15
	v_mul_f32_e32 v174, v174, v15
	v_mul_f32_e32 v175, v175, v15
	v_fmac_f32_e32 v176, v160, v20
	v_fmac_f32_e32 v177, v161, v21
	v_fmac_f32_e32 v178, v162, v22
	v_fmac_f32_e32 v179, v163, v23
	v_fmac_f32_e32 v180, v164, v24
	v_fmac_f32_e32 v181, v165, v25
	v_fmac_f32_e32 v182, v166, v26
	v_fmac_f32_e32 v183, v167, v27
	v_fmac_f32_e32 v184, v168, v28
	v_fmac_f32_e32 v185, v169, v29
	v_fmac_f32_e32 v186, v170, v30
	v_fmac_f32_e32 v187, v171, v31
	v_fmac_f32_e32 v188, v172, v32
	v_fmac_f32_e32 v189, v173, v33
	v_fmac_f32_e32 v190, v174, v34
	v_fmac_f32_e32 v191, v175, v35
	global_store_dwordx4 v1, v[176:179], s[48:49] offset:0 nt
	global_store_dwordx4 v1, v[180:183], s[48:49] offset:1024 nt
	global_store_dwordx4 v1, v[184:187], s[48:49] offset:2048 nt
	global_store_dwordx4 v1, v[188:191], s[48:49] offset:3072 nt
	v_mul_f32_e32 v10, v144, v144
	v_fmac_f32_e32 v10, v145, v145
	v_fmac_f32_e32 v10, v146, v146
	v_fmac_f32_e32 v10, v147, v147
	v_fmac_f32_e32 v10, v148, v148
	v_fmac_f32_e32 v10, v149, v149
	v_fmac_f32_e32 v10, v150, v150
	v_fmac_f32_e32 v10, v151, v151
	v_fmac_f32_e32 v10, v152, v152
	v_fmac_f32_e32 v10, v153, v153
	v_fmac_f32_e32 v10, v154, v154
	v_fmac_f32_e32 v10, v155, v155
	v_fmac_f32_e32 v10, v156, v156
	v_fmac_f32_e32 v10, v157, v157
	v_fmac_f32_e32 v10, v158, v158
	v_fmac_f32_e32 v10, v159, v159
	v_mul_f32_e32 v11, v176, v176
	v_fmac_f32_e32 v11, v177, v177
	v_fmac_f32_e32 v11, v178, v178
	v_fmac_f32_e32 v11, v179, v179
	v_fmac_f32_e32 v11, v180, v180
	v_fmac_f32_e32 v11, v181, v181
	v_fmac_f32_e32 v11, v182, v182
	v_fmac_f32_e32 v11, v183, v183
	v_fmac_f32_e32 v11, v184, v184
	v_fmac_f32_e32 v11, v185, v185
	v_fmac_f32_e32 v11, v186, v186
	v_fmac_f32_e32 v11, v187, v187
	v_fmac_f32_e32 v11, v188, v188
	v_fmac_f32_e32 v11, v189, v189
	v_fmac_f32_e32 v11, v190, v190
	v_fmac_f32_e32 v11, v191, v191
	ds_bpermute_b32 v12, v4, v10
	ds_bpermute_b32 v13, v4, v11
	s_waitcnt lgkmcnt(0)
	v_add_f32_e32 v10, v10, v12
	v_add_f32_e32 v11, v11, v13
	ds_bpermute_b32 v12, v5, v10
	ds_bpermute_b32 v13, v5, v11
	s_waitcnt lgkmcnt(0)
	v_add_f32_e32 v10, v10, v12
	v_add_f32_e32 v11, v11, v13
	ds_bpermute_b32 v12, v6, v10
	ds_bpermute_b32 v13, v6, v11
	s_waitcnt lgkmcnt(0)
	v_add_f32_e32 v10, v10, v12
	v_add_f32_e32 v11, v11, v13
	ds_bpermute_b32 v12, v7, v10
	ds_bpermute_b32 v13, v7, v11
	s_waitcnt lgkmcnt(0)
	v_add_f32_e32 v10, v10, v12
	v_add_f32_e32 v11, v11, v13
	ds_bpermute_b32 v12, v8, v10
	ds_bpermute_b32 v13, v8, v11
	s_waitcnt lgkmcnt(0)
	v_add_f32_e32 v10, v10, v12
	v_add_f32_e32 v11, v11, v13
	ds_bpermute_b32 v12, v9, v10
	ds_bpermute_b32 v13, v9, v11
	s_waitcnt lgkmcnt(0)
	v_add_f32_e32 v10, v10, v12
	v_add_f32_e32 v11, v11, v13
	v_fma_f32 v14, v10, s17, v3
	v_fma_f32 v15, v11, s17, v3
	v_rsq_f32_e32 v14, v14
	v_rsq_f32_e32 v15, v15
	s_nop 0
	v_mul_f32_e32 v128, v144, v14
	v_mul_f32_e32 v129, v145, v14
	v_mul_f32_e32 v130, v146, v14
	v_mul_f32_e32 v131, v147, v14
	v_mul_f32_e32 v132, v148, v14
	v_mul_f32_e32 v133, v149, v14
	v_mul_f32_e32 v134, v150, v14
	v_mul_f32_e32 v135, v151, v14
	v_mul_f32_e32 v136, v152, v14
	v_mul_f32_e32 v137, v153, v14
	v_mul_f32_e32 v138, v154, v14
	v_mul_f32_e32 v139, v155, v14
	v_mul_f32_e32 v140, v156, v14
	v_mul_f32_e32 v141, v157, v14
	v_mul_f32_e32 v142, v158, v14
	v_mul_f32_e32 v143, v159, v14
	v_mul_f32_e32 v128, v128, v36
	v_mul_f32_e32 v129, v129, v37
	v_mul_f32_e32 v130, v130, v38
	v_mul_f32_e32 v131, v131, v39
	v_mul_f32_e32 v132, v132, v40
	v_mul_f32_e32 v133, v133, v41
	v_mul_f32_e32 v134, v134, v42
	v_mul_f32_e32 v135, v135, v43
	v_mul_f32_e32 v136, v136, v44
	v_mul_f32_e32 v137, v137, v45
	v_mul_f32_e32 v138, v138, v46
	v_mul_f32_e32 v139, v139, v47
	v_mul_f32_e32 v140, v140, v48
	v_mul_f32_e32 v141, v141, v49
	v_mul_f32_e32 v142, v142, v50
	v_mul_f32_e32 v143, v143, v51
	v_cvt_pk_bf16_f32 v128, v128, v129
	v_cvt_pk_bf16_f32 v129, v130, v131
	v_cvt_pk_bf16_f32 v132, v132, v133
	v_cvt_pk_bf16_f32 v133, v134, v135
	v_cvt_pk_bf16_f32 v136, v136, v137
	v_cvt_pk_bf16_f32 v137, v138, v139
	v_cvt_pk_bf16_f32 v140, v140, v141
	v_cvt_pk_bf16_f32 v141, v142, v143
	global_store_dwordx2 v2, v[128:129], s[42:43] offset:0
	global_store_dwordx2 v2, v[132:133], s[42:43] offset:512
	global_store_dwordx2 v2, v[136:137], s[42:43] offset:1024
	global_store_dwordx2 v2, v[140:141], s[42:43] offset:1536
	v_mul_f32_e32 v160, v176, v15
	v_mul_f32_e32 v161, v177, v15
	v_mul_f32_e32 v162, v178, v15
	v_mul_f32_e32 v163, v179, v15
	v_mul_f32_e32 v164, v180, v15
	v_mul_f32_e32 v165, v181, v15
	v_mul_f32_e32 v166, v182, v15
	v_mul_f32_e32 v167, v183, v15
	v_mul_f32_e32 v168, v184, v15
	v_mul_f32_e32 v169, v185, v15
	v_mul_f32_e32 v170, v186, v15
	v_mul_f32_e32 v171, v187, v15
	v_mul_f32_e32 v172, v188, v15
	v_mul_f32_e32 v173, v189, v15
	v_mul_f32_e32 v174, v190, v15
	v_mul_f32_e32 v175, v191, v15
	v_mul_f32_e32 v160, v160, v36
	v_mul_f32_e32 v161, v161, v37
	v_mul_f32_e32 v162, v162, v38
	v_mul_f32_e32 v163, v163, v39
	v_mul_f32_e32 v164, v164, v40
	v_mul_f32_e32 v165, v165, v41
	v_mul_f32_e32 v166, v166, v42
	v_mul_f32_e32 v167, v167, v43
	v_mul_f32_e32 v168, v168, v44
	v_mul_f32_e32 v169, v169, v45
	v_mul_f32_e32 v170, v170, v46
	v_mul_f32_e32 v171, v171, v47
	v_mul_f32_e32 v172, v172, v48
	v_mul_f32_e32 v173, v173, v49
	v_mul_f32_e32 v174, v174, v50
	v_mul_f32_e32 v175, v175, v51
	v_cvt_pk_bf16_f32 v160, v160, v161
	v_cvt_pk_bf16_f32 v161, v162, v163
	v_cvt_pk_bf16_f32 v164, v164, v165
	v_cvt_pk_bf16_f32 v165, v166, v167
	v_cvt_pk_bf16_f32 v168, v168, v169
	v_cvt_pk_bf16_f32 v169, v170, v171
	v_cvt_pk_bf16_f32 v172, v172, v173
	v_cvt_pk_bf16_f32 v173, v174, v175
	global_store_dwordx2 v2, v[160:161], s[50:51] offset:0
	global_store_dwordx2 v2, v[164:165], s[50:51] offset:512
	global_store_dwordx2 v2, v[168:169], s[50:51] offset:1024
	global_store_dwordx2 v2, v[172:173], s[50:51] offset:1536
	v_add_f32_e32 v208, v208, v212
	v_add_f32_e32 v209, v209, v213
	v_add_f32_e32 v210, v210, v214
	v_add_f32_e32 v211, v211, v215
	v_readfirstlane_b32 s18, v0
	s_lshr_b32 s18, s18, 6
	s_lshl_b32 s19, s18, 2
	s_and_b32 s52, s18, 4
	s_lshl_b32 s52, s52, 2
	v_mov_b32_e32 v16, s19
	v_mov_b32_e32 v17, s52
	v_mul_f32_e32 v10, v208, v208
	v_fmac_f32_e32 v10, v209, v209
	v_fmac_f32_e32 v10, v210, v210
	v_fmac_f32_e32 v10, v211, v211
	ds_bpermute_b32 v11, v4, v10
	s_waitcnt lgkmcnt(0)
	v_add_f32_e32 v10, v10, v11
	ds_bpermute_b32 v11, v5, v10
	s_waitcnt lgkmcnt(0)
	v_add_f32_e32 v10, v10, v11
	ds_bpermute_b32 v11, v6, v10
	s_waitcnt lgkmcnt(0)
	v_add_f32_e32 v10, v10, v11
	ds_bpermute_b32 v11, v7, v10
	s_waitcnt lgkmcnt(0)
	v_add_f32_e32 v10, v10, v11
	ds_bpermute_b32 v11, v8, v10
	s_waitcnt lgkmcnt(0)
	v_add_f32_e32 v10, v10, v11
	ds_bpermute_b32 v11, v9, v10
	s_waitcnt lgkmcnt(0)
	v_add_f32_e32 v10, v10, v11
	ds_write_b32 v16, v10 offset:0
	s_waitcnt lgkmcnt(0)
	s_barrier
	ds_read_b128 v[12:15], v17 offset:0
	s_waitcnt lgkmcnt(0)
	v_add_f32_e32 v12, v12, v13
	v_add_f32_e32 v14, v14, v15
	v_add_f32_e32 v10, v12, v14
	v_fma_f32 v11, v10, s17, v3
	v_rsq_f32_e32 v11, v11
	s_nop 0
	v_mul_f32_e32 v208, v208, v11
	v_mul_f32_e32 v209, v209, v11
	v_mul_f32_e32 v210, v210, v11
	v_mul_f32_e32 v211, v211, v11
	v_fmac_f32_e32 v240, v208, v244
	v_fmac_f32_e32 v241, v209, v245
	v_fmac_f32_e32 v242, v210, v246
	v_fmac_f32_e32 v243, v211, v247
	s_lshl_b32 s18, s54, 12
	s_add_u32 s18, s18, s55
	s_add_u32 s56, s4, s18
	s_addc_u32 s57, s5, 0
	s_add_u32 s56, s56, 0x4000000
	s_addc_u32 s57, s57, 0
	global_store_dwordx4 v1, v[240:243], s[56:57]
	v_mul_f32_e32 v10, v240, v240
	v_fmac_f32_e32 v10, v241, v241
	v_fmac_f32_e32 v10, v242, v242
	v_fmac_f32_e32 v10, v243, v243
	ds_bpermute_b32 v11, v4, v10
	s_waitcnt lgkmcnt(0)
	v_add_f32_e32 v10, v10, v11
	ds_bpermute_b32 v11, v5, v10
	s_waitcnt lgkmcnt(0)
	v_add_f32_e32 v10, v10, v11
	ds_bpermute_b32 v11, v6, v10
	s_waitcnt lgkmcnt(0)
	v_add_f32_e32 v10, v10, v11
	ds_bpermute_b32 v11, v7, v10
	s_waitcnt lgkmcnt(0)
	v_add_f32_e32 v10, v10, v11
	ds_bpermute_b32 v11, v8, v10
	s_waitcnt lgkmcnt(0)
	v_add_f32_e32 v10, v10, v11
	ds_bpermute_b32 v11, v9, v10
	s_waitcnt lgkmcnt(0)
	v_add_f32_e32 v10, v10, v11
	ds_write_b32 v16, v10 offset:64
	s_waitcnt lgkmcnt(0)
	s_barrier
	ds_read_b128 v[12:15], v17 offset:64
	s_waitcnt lgkmcnt(0)
	v_add_f32_e32 v12, v12, v13
	v_add_f32_e32 v14, v14, v15
	v_add_f32_e32 v10, v12, v14
	v_fma_f32 v11, v10, s17, v3
	v_rsq_f32_e32 v11, v11
	s_nop 0
	v_mul_f32_e32 v208, v240, v11
	v_mul_f32_e32 v209, v241, v11
	v_mul_f32_e32 v210, v242, v11
	v_mul_f32_e32 v211, v243, v11
	v_mul_f32_e32 v208, v208, v248
	v_mul_f32_e32 v209, v209, v249
	v_mul_f32_e32 v210, v210, v250
	v_mul_f32_e32 v211, v211, v251
	v_cvt_pk_bf16_f32 v208, v208, v209
	v_cvt_pk_bf16_f32 v209, v210, v211
	s_lshl_b32 s18, s54, 11
	s_lshr_b32 s19, s55, 1
	s_add_u32 s18, s18, s19
	s_add_u32 s56, s6, s18
	s_addc_u32 s57, s7, 0
	s_add_u32 s56, s56, 0x5100000
	s_addc_u32 s57, s57, 0
	global_store_dwordx2 v2, v[208:209], s[56:57]

_Z10fwd_kernelILi14ELi15EEv4Args:
	s_load_dword s3, s[0:1], 0xe8
	s_load_dwordx4 s[4:7], s[0:1], 0xd0
	s_load_dwordx2 s[8:9], s[0:1], 0xb8
	s_waitcnt lgkmcnt(0)
	s_cmp_lg_u32 s3, 0x100
	s_cbranch_scc1 .Lrows14_orig
	s_add_u32 s8, s8, 0x1000
	s_addc_u32 s9, s9, 0
	v_readfirstlane_b32 s16, v0
	s_lshr_b32 s16, s16, 6
	s_lshl_b32 s18, s2, 3
	s_add_u32 s16, s16, s18
	s_mov_b32 s17, 0x3a800000
	v_mov_b32_e32 v3, 0x358637bd
	v_and_b32_e32 v10, 63, v0
	v_lshlrev_b32_e32 v1, 4, v10
	v_lshlrev_b32_e32 v2, 3, v10
	v_xor_b32_e32 v4, 1, v10
	v_xor_b32_e32 v5, 2, v10
	v_xor_b32_e32 v6, 4, v10
	v_xor_b32_e32 v7, 8, v10
	v_xor_b32_e32 v8, 16, v10
	v_xor_b32_e32 v9, 32, v10
	v_lshlrev_b32_e32 v4, 2, v4
	v_lshlrev_b32_e32 v5, 2, v5
	v_lshlrev_b32_e32 v6, 2, v6
	v_lshlrev_b32_e32 v7, 2, v7
	v_lshlrev_b32_e32 v8, 2, v8
	v_lshlrev_b32_e32 v9, 2, v9
	global_load_dwordx4 v[20:23], v1, s[8:9] offset:0
	global_load_dwordx4 v[24:27], v1, s[8:9] offset:1024
	global_load_dwordx4 v[28:31], v1, s[8:9] offset:2048
	global_load_dwordx4 v[32:35], v1, s[8:9] offset:3072
	s_lshr_b32 s54, s16, 2
	s_and_b32 s55, s16, 3
	s_lshl_b32 s55, s55, 10
	s_lshl_b32 s18, s54, 12
	s_add_u32 s18, s18, s55
	s_add_u32 s56, s6, s18
	s_addc_u32 s57, s7, 0
	s_add_u32 s56, s56, 0x100000
	s_addc_u32 s57, s57, 0
	global_load_dwordx4 v[208:211], v1, s[56:57]
	s_add_u32 s56, s56, 0x200000
	s_addc_u32 s57, s57, 0
	global_load_dwordx4 v[212:215], v1, s[56:57]
	s_add_u32 s56, s56, 0x200000
	s_addc_u32 s57, s57, 0
	global_load_dwordx4 v[216:219], v1, s[56:57]
	s_add_u32 s56, s56, 0x200000
	s_addc_u32 s57, s57, 0
	global_load_dwordx4 v[220:223], v1, s[56:57]
	s_add_u32 s56, s56, 0x200000
	s_addc_u32 s57, s57, 0
	global_load_dwordx4 v[224:227], v1, s[56:57]
	s_add_u32 s56, s56, 0x200000
	s_addc_u32 s57, s57, 0
	global_load_dwordx4 v[228:231], v1, s[56:57]
	s_add_u32 s56, s56, 0x200000
	s_addc_u32 s57, s57, 0
	global_load_dwordx4 v[232:235], v1, s[56:57]
	s_add_u32 s56, s56, 0x200000
	s_addc_u32 s57, s57, 0
	global_load_dwordx4 v[236:239], v1, s[56:57]
	s_add_u32 s56, s4, s18
	s_addc_u32 s57, s5, 0
	s_add_u32 s56, s56, 0x4000000
	s_addc_u32 s57, s57, 0
	global_load_dwordx4 v[240:243], v1, s[56:57]
	s_add_u32 s56, s8, s55
	s_addc_u32 s57, s9, 0
	global_load_dwordx4 v[244:247], v1, s[56:57]
	s_add_u32 s53, s16, 0x0
	s_lshl_b32 s18, s53, 12
	s_lshl_b32 s19, s53, 11
	s_add_u32 s20, s4, s18
	s_addc_u32 s21, s5, 0
	s_add_u32 s22, s6, s19
	s_addc_u32 s23, s7, 0
	s_add_u32 s22, s22, 0x5200000
	s_addc_u32 s23, s23, 0
	s_add_u32 s24, s4, s18
	s_addc_u32 s25, s5, 0
	global_load_dwordx2 v[66:67], v2, s[22:23] offset:0
	global_load_dwordx2 v[70:71], v2, s[22:23] offset:512
	global_load_dwordx2 v[74:75], v2, s[22:23] offset:1024
	global_load_dwordx2 v[78:79], v2, s[22:23] offset:1536
	global_load_dwordx4 v[80:83], v1, s[20:21] offset:0
	global_load_dwordx4 v[84:87], v1, s[20:21] offset:1024
	global_load_dwordx4 v[88:91], v1, s[20:21] offset:2048
	global_load_dwordx4 v[92:95], v1, s[20:21] offset:3072
	s_add_u32 s53, s16, 0x800
	s_lshl_b32 s18, s53, 12
	s_lshl_b32 s19, s53, 11
	s_add_u32 s28, s4, s18
	s_addc_u32 s29, s5, 0
	s_add_u32 s30, s6, s19
	s_addc_u32 s31, s7, 0
	s_add_u32 s30, s30, 0x5200000
	s_addc_u32 s31, s31, 0
	s_add_u32 s32, s4, s18
	s_addc_u32 s33, s5, 0
	global_load_dwordx2 v[98:99], v2, s[30:31] offset:0
	global_load_dwordx2 v[102:103], v2, s[30:31] offset:512
	global_load_dwordx2 v[106:107], v2, s[30:31] offset:1024
	global_load_dwordx2 v[110:111], v2, s[30:31] offset:1536
	global_load_dwordx4 v[112:115], v1, s[28:29] offset:0
	global_load_dwordx4 v[116:119], v1, s[28:29] offset:1024
	global_load_dwordx4 v[120:123], v1, s[28:29] offset:2048
	global_load_dwordx4 v[124:127], v1, s[28:29] offset:3072
	s_add_u32 s53, s16, 0x1000
	s_lshl_b32 s18, s53, 12
	s_lshl_b32 s19, s53, 11
	s_add_u32 s36, s4, s18
	s_addc_u32 s37, s5, 0
	s_add_u32 s38, s6, s19
	s_addc_u32 s39, s7, 0
	s_add_u32 s38, s38, 0x5200000
	s_addc_u32 s39, s39, 0
	s_add_u32 s40, s4, s18
	s_addc_u32 s41, s5, 0
	global_load_dwordx2 v[130:131], v2, s[38:39] offset:0
	global_load_dwordx2 v[134:135], v2, s[38:39] offset:512
	global_load_dwordx2 v[138:139], v2, s[38:39] offset:1024
	global_load_dwordx2 v[142:143], v2, s[38:39] offset:1536
	global_load_dwordx4 v[144:147], v1, s[36:37] offset:0
	global_load_dwordx4 v[148:151], v1, s[36:37] offset:1024
	global_load_dwordx4 v[152:155], v1, s[36:37] offset:2048
	global_load_dwordx4 v[156:159], v1, s[36:37] offset:3072
	s_add_u32 s53, s16, 0x1800
	s_lshl_b32 s18, s53, 12
	s_lshl_b32 s19, s53, 11
	s_add_u32 s44, s4, s18
	s_addc_u32 s45, s5, 0
	s_add_u32 s46, s6, s19
	s_addc_u32 s47, s7, 0
	s_add_u32 s46, s46, 0x5200000
	s_addc_u32 s47, s47, 0
	s_add_u32 s48, s4, s18
	s_addc_u32 s49, s5, 0
	global_load_dwordx2 v[162:163], v2, s[46:47] offset:0
	global_load_dwordx2 v[166:167], v2, s[46:47] offset:512
	global_load_dwordx2 v[170:171], v2, s[46:47] offset:1024
	global_load_dwordx2 v[174:175], v2, s[46:47] offset:1536
	global_load_dwordx4 v[176:179], v1, s[44:45] offset:0
	global_load_dwordx4 v[180:183], v1, s[44:45] offset:1024
	global_load_dwordx4 v[184:187], v1, s[44:45] offset:2048
	global_load_dwordx4 v[188:191], v1, s[44:45] offset:3072
	s_waitcnt vmcnt(16)
	v_lshlrev_b32_e32 v64, 16, v66
	v_and_b32_e32 v65, 0xffff0000, v66
	v_lshlrev_b32_e32 v66, 16, v67
	v_and_b32_e32 v67, 0xffff0000, v67
	v_lshlrev_b32_e32 v68, 16, v70
	v_and_b32_e32 v69, 0xffff0000, v70
	v_lshlrev_b32_e32 v70, 16, v71
	v_and_b32_e32 v71, 0xffff0000, v71
	v_lshlrev_b32_e32 v72, 16, v74
	v_and_b32_e32 v73, 0xffff0000, v74
	v_lshlrev_b32_e32 v74, 16, v75
	v_and_b32_e32 v75, 0xffff0000, v75
	v_lshlrev_b32_e32 v76, 16, v78
	v_and_b32_e32 v77, 0xffff0000, v78
	v_lshlrev_b32_e32 v78, 16, v79
	v_and_b32_e32 v79, 0xffff0000, v79
	v_lshlrev_b32_e32 v96, 16, v98
	v_and_b32_e32 v97, 0xffff0000, v98
	v_lshlrev_b32_e32 v98, 16, v99
	v_and_b32_e32 v99, 0xffff0000, v99
	v_lshlrev_b32_e32 v100, 16, v102
	v_and_b32_e32 v101, 0xffff0000, v102
	v_lshlrev_b32_e32 v102, 16, v103
	v_and_b32_e32 v103, 0xffff0000, v103
	v_lshlrev_b32_e32 v104, 16, v106
	v_and_b32_e32 v105, 0xffff0000, v106
	v_lshlrev_b32_e32 v106, 16, v107
	v_and_b32_e32 v107, 0xffff0000, v107
	v_lshlrev_b32_e32 v108, 16, v110
	v_and_b32_e32 v109, 0xffff0000, v110
	v_lshlrev_b32_e32 v110, 16, v111
	v_and_b32_e32 v111, 0xffff0000, v111
	v_mul_f32_e32 v10, v64, v64
	v_fmac_f32_e32 v10, v65, v65
	v_fmac_f32_e32 v10, v66, v66
	v_fmac_f32_e32 v10, v67, v67
	v_fmac_f32_e32 v10, v68, v68
	v_fmac_f32_e32 v10, v69, v69
	v_fmac_f32_e32 v10, v70, v70
	v_fmac_f32_e32 v10, v71, v71
	v_fmac_f32_e32 v10, v72, v72
	v_fmac_f32_e32 v10, v73, v73
	v_fmac_f32_e32 v10, v74, v74
	v_fmac_f32_e32 v10, v75, v75
	v_fmac_f32_e32 v10, v76, v76
	v_fmac_f32_e32 v10, v77, v77
	v_fmac_f32_e32 v10, v78, v78
	v_fmac_f32_e32 v10, v79, v79
	v_mul_f32_e32 v11, v96, v96
	v_fmac_f32_e32 v11, v97, v97
	v_fmac_f32_e32 v11, v98, v98
	v_fmac_f32_e32 v11, v99, v99
	v_fmac_f32_e32 v11, v100, v100
	v_fmac_f32_e32 v11, v101, v101
	v_fmac_f32_e32 v11, v102, v102
	v_fmac_f32_e32 v11, v103, v103
	v_fmac_f32_e32 v11, v104, v104
	v_fmac_f32_e32 v11, v105, v105
	v_fmac_f32_e32 v11, v106, v106
	v_fmac_f32_e32 v11, v107, v107
	v_fmac_f32_e32 v11, v108, v108
	v_fmac_f32_e32 v11, v109, v109
	v_fmac_f32_e32 v11, v110, v110
	v_fmac_f32_e32 v11, v111, v111
	ds_bpermute_b32 v12, v4, v10
	ds_bpermute_b32 v13, v4, v11
	s_waitcnt lgkmcnt(0)
	v_add_f32_e32 v10, v10, v12
	v_add_f32_e32 v11, v11, v13
	ds_bpermute_b32 v12, v5, v10
	ds_bpermute_b32 v13, v5, v11
	s_waitcnt lgkmcnt(0)
	v_add_f32_e32 v10, v10, v12
	v_add_f32_e32 v11, v11, v13
	ds_bpermute_b32 v12, v6, v10
	ds_bpermute_b32 v13, v6, v11
	s_waitcnt lgkmcnt(0)
	v_add_f32_e32 v10, v10, v12
	v_add_f32_e32 v11, v11, v13
	ds_bpermute_b32 v12, v7, v10
	ds_bpermute_b32 v13, v7, v11
	s_waitcnt lgkmcnt(0)
	v_add_f32_e32 v10, v10, v12
	v_add_f32_e32 v11, v11, v13
	ds_bpermute_b32 v12, v8, v10
	ds_bpermute_b32 v13, v8, v11
	s_waitcnt lgkmcnt(0)
	v_add_f32_e32 v10, v10, v12
	v_add_f32_e32 v11, v11, v13
	ds_bpermute_b32 v12, v9, v10
	ds_bpermute_b32 v13, v9, v11
	s_waitcnt lgkmcnt(0)
	v_add_f32_e32 v10, v10, v12
	v_add_f32_e32 v11, v11, v13
	v_fma_f32 v14, v10, s17, v3
	v_fma_f32 v15, v11, s17, v3
	v_rsq_f32_e32 v14, v14
	v_rsq_f32_e32 v15, v15
	s_nop 0
	v_mul_f32_e32 v64, v64, v14
	v_mul_f32_e32 v65, v65, v14
	v_mul_f32_e32 v66, v66, v14
	v_mul_f32_e32 v67, v67, v14
	v_mul_f32_e32 v68, v68, v14
	v_mul_f32_e32 v69, v69, v14
	v_mul_f32_e32 v70, v70, v14
	v_mul_f32_e32 v71, v71, v14
	v_mul_f32_e32 v72, v72, v14
	v_mul_f32_e32 v73, v73, v14
	v_mul_f32_e32 v74, v74, v14
	v_mul_f32_e32 v75, v75, v14
	v_mul_f32_e32 v76, v76, v14
	v_mul_f32_e32 v77, v77, v14
	v_mul_f32_e32 v78, v78, v14
	v_mul_f32_e32 v79, v79, v14
	v_fmac_f32_e32 v80, v64, v20
	v_fmac_f32_e32 v81, v65, v21
	v_fmac_f32_e32 v82, v66, v22
	v_fmac_f32_e32 v83, v67, v23
	v_fmac_f32_e32 v84, v68, v24
	v_fmac_f32_e32 v85, v69, v25
	v_fmac_f32_e32 v86, v70, v26
	v_fmac_f32_e32 v87, v71, v27
	v_fmac_f32_e32 v88, v72, v28
	v_fmac_f32_e32 v89, v73, v29
	v_fmac_f32_e32 v90, v74, v30
	v_fmac_f32_e32 v91, v75, v31
	v_fmac_f32_e32 v92, v76, v32
	v_fmac_f32_e32 v93, v77, v33
	v_fmac_f32_e32 v94, v78, v34
	v_fmac_f32_e32 v95, v79, v35
	global_store_dwordx4 v1, v[80:83], s[24:25] offset:0 nt
	global_store_dwordx4 v1, v[84:87], s[24:25] offset:1024 nt
	global_store_dwordx4 v1, v[88:91], s[24:25] offset:2048 nt
	global_store_dwordx4 v1, v[92:95], s[24:25] offset:3072 nt
	v_mul_f32_e32 v96, v96, v15
	v_mul_f32_e32 v97, v97, v15
	v_mul_f32_e32 v98, v98, v15
	v_mul_f32_e32 v99, v99, v15
	v_mul_f32_e32 v100, v100, v15
	v_mul_f32_e32 v101, v101, v15
	v_mul_f32_e32 v102, v102, v15
	v_mul_f32_e32 v103, v103, v15
	v_mul_f32_e32 v104, v104, v15
	v_mul_f32_e32 v105, v105, v15
	v_mul_f32_e32 v106, v106, v15
	v_mul_f32_e32 v107, v107, v15
	v_mul_f32_e32 v108, v108, v15
	v_mul_f32_e32 v109, v109, v15
	v_mul_f32_e32 v110, v110, v15
	v_mul_f32_e32 v111, v111, v15
	v_fmac_f32_e32 v112, v96, v20
	v_fmac_f32_e32 v113, v97, v21
	v_fmac_f32_e32 v114, v98, v22
	v_fmac_f32_e32 v115, v99, v23
	v_fmac_f32_e32 v116, v100, v24
	v_fmac_f32_e32 v117, v101, v25
	v_fmac_f32_e32 v118, v102, v26
	v_fmac_f32_e32 v119, v103, v27
	v_fmac_f32_e32 v120, v104, v28
	v_fmac_f32_e32 v121, v105, v29
	v_fmac_f32_e32 v122, v106, v30
	v_fmac_f32_e32 v123, v107, v31
	v_fmac_f32_e32 v124, v108, v32
	v_fmac_f32_e32 v125, v109, v33
	v_fmac_f32_e32 v126, v110, v34
	v_fmac_f32_e32 v127, v111, v35
	global_store_dwordx4 v1, v[112:115], s[32:33] offset:0 nt
	global_store_dwordx4 v1, v[116:119], s[32:33] offset:1024 nt
	global_store_dwordx4 v1, v[120:123], s[32:33] offset:2048 nt
	global_store_dwordx4 v1, v[124:127], s[32:33] offset:3072 nt
	s_add_u32 s53, s16, 0x2000
	s_lshl_b32 s18, s53, 12
	s_lshl_b32 s19, s53, 11
	s_add_u32 s20, s4, s18
	s_addc_u32 s21, s5, 0
	s_add_u32 s22, s6, s19
	s_addc_u32 s23, s7, 0
	s_add_u32 s22, s22, 0x5200000
	s_addc_u32 s23, s23, 0
	s_add_u32 s24, s4, s18
	s_addc_u32 s25, s5, 0
	global_load_dwordx2 v[66:67], v2, s[22:23] offset:0
	global_load_dwordx2 v[70:71], v2, s[22:23] offset:512
	global_load_dwordx2 v[74:75], v2, s[22:23] offset:1024
	global_load_dwordx2 v[78:79], v2, s[22:23] offset:1536
	global_load_dwordx4 v[80:83], v1, s[20:21] offset:0
	global_load_dwordx4 v[84:87], v1, s[20:21] offset:1024
	global_load_dwordx4 v[88:91], v1, s[20:21] offset:2048
	global_load_dwordx4 v[92:95], v1, s[20:21] offset:3072
	s_add_u32 s53, s16, 0x2800
	s_lshl_b32 s18, s53, 12
	s_lshl_b32 s19, s53, 11
	s_add_u32 s28, s4, s18
	s_addc_u32 s29, s5, 0
	s_add_u32 s30, s6, s19
	s_addc_u32 s31, s7, 0
	s_add_u32 s30, s30, 0x5200000
	s_addc_u32 s31, s31, 0
	s_add_u32 s32, s4, s18
	s_addc_u32 s33, s5, 0
	global_load_dwordx2 v[98:99], v2, s[30:31] offset:0
	global_load_dwordx2 v[102:103], v2, s[30:31] offset:512
	global_load_dwordx2 v[106:107], v2, s[30:31] offset:1024
	global_load_dwordx2 v[110:111], v2, s[30:31] offset:1536
	global_load_dwordx4 v[112:115], v1, s[28:29] offset:0
	global_load_dwordx4 v[116:119], v1, s[28:29] offset:1024
	global_load_dwordx4 v[120:123], v1, s[28:29] offset:2048
	global_load_dwordx4 v[124:127], v1, s[28:29] offset:3072
	s_waitcnt vmcnt(24)
	v_lshlrev_b32_e32 v128, 16, v130
	v_and_b32_e32 v129, 0xffff0000, v130
	v_lshlrev_b32_e32 v130, 16, v131
	v_and_b32_e32 v131, 0xffff0000, v131
	v_lshlrev_b32_e32 v132, 16, v134
	v_and_b32_e32 v133, 0xffff0000, v134
	v_lshlrev_b32_e32 v134, 16, v135
	v_and_b32_e32 v135, 0xffff0000, v135
	v_lshlrev_b32_e32 v136, 16, v138
	v_and_b32_e32 v137, 0xffff0000, v138
	v_lshlrev_b32_e32 v138, 16, v139
	v_and_b32_e32 v139, 0xffff0000, v139
	v_lshlrev_b32_e32 v140, 16, v142
	v_and_b32_e32 v141, 0xffff0000, v142
	v_lshlrev_b32_e32 v142, 16, v143
	v_and_b32_e32 v143, 0xffff0000, v143
	v_lshlrev_b32_e32 v160, 16, v162
	v_and_b32_e32 v161, 0xffff0000, v162
	v_lshlrev_b32_e32 v162, 16, v163
	v_and_b32_e32 v163, 0xffff0000, v163
	v_lshlrev_b32_e32 v164, 16, v166
	v_and_b32_e32 v165, 0xffff0000, v166
	v_lshlrev_b32_e32 v166, 16, v167
	v_and_b32_e32 v167, 0xffff0000, v167
	v_lshlrev_b32_e32 v168, 16, v170
	v_and_b32_e32 v169, 0xffff0000, v170
	v_lshlrev_b32_e32 v170, 16, v171
	v_and_b32_e32 v171, 0xffff0000, v171
	v_lshlrev_b32_e32 v172, 16, v174
	v_and_b32_e32 v173, 0xffff0000, v174
	v_lshlrev_b32_e32 v174, 16, v175
	v_and_b32_e32 v175, 0xffff0000, v175
	v_mul_f32_e32 v10, v128, v128
	v_fmac_f32_e32 v10, v129, v129
	v_fmac_f32_e32 v10, v130, v130
	v_fmac_f32_e32 v10, v131, v131
	v_fmac_f32_e32 v10, v132, v132
	v_fmac_f32_e32 v10, v133, v133
	v_fmac_f32_e32 v10, v134, v134
	v_fmac_f32_e32 v10, v135, v135
	v_fmac_f32_e32 v10, v136, v136
	v_fmac_f32_e32 v10, v137, v137
	v_fmac_f32_e32 v10, v138, v138
	v_fmac_f32_e32 v10, v139, v139
	v_fmac_f32_e32 v10, v140, v140
	v_fmac_f32_e32 v10, v141, v141
	v_fmac_f32_e32 v10, v142, v142
	v_fmac_f32_e32 v10, v143, v143
	v_mul_f32_e32 v11, v160, v160
	v_fmac_f32_e32 v11, v161, v161
	v_fmac_f32_e32 v11, v162, v162
	v_fmac_f32_e32 v11, v163, v163
	v_fmac_f32_e32 v11, v164, v164
	v_fmac_f32_e32 v11, v165, v165
	v_fmac_f32_e32 v11, v166, v166
	v_fmac_f32_e32 v11, v167, v167
	v_fmac_f32_e32 v11, v168, v168
	v_fmac_f32_e32 v11, v169, v169
	v_fmac_f32_e32 v11, v170, v170
	v_fmac_f32_e32 v11, v171, v171
	v_fmac_f32_e32 v11, v172, v172
	v_fmac_f32_e32 v11, v173, v173
	v_fmac_f32_e32 v11, v174, v174
	v_fmac_f32_e32 v11, v175, v175
	ds_bpermute_b32 v12, v4, v10
	ds_bpermute_b32 v13, v4, v11
	s_waitcnt lgkmcnt(0)
	v_add_f32_e32 v10, v10, v12
	v_add_f32_e32 v11, v11, v13
	ds_bpermute_b32 v12, v5, v10
	ds_bpermute_b32 v13, v5, v11
	s_waitcnt lgkmcnt(0)
	v_add_f32_e32 v10, v10, v12
	v_add_f32_e32 v11, v11, v13
	ds_bpermute_b32 v12, v6, v10
	ds_bpermute_b32 v13, v6, v11
	s_waitcnt lgkmcnt(0)
	v_add_f32_e32 v10, v10, v12
	v_add_f32_e32 v11, v11, v13
	ds_bpermute_b32 v12, v7, v10
	ds_bpermute_b32 v13, v7, v11
	s_waitcnt lgkmcnt(0)
	v_add_f32_e32 v10, v10, v12
	v_add_f32_e32 v11, v11, v13
	ds_bpermute_b32 v12, v8, v10
	ds_bpermute_b32 v13, v8, v11
	s_waitcnt lgkmcnt(0)
	v_add_f32_e32 v10, v10, v12
	v_add_f32_e32 v11, v11, v13
	ds_bpermute_b32 v12, v9, v10
	ds_bpermute_b32 v13, v9, v11
	s_waitcnt lgkmcnt(0)
	v_add_f32_e32 v10, v10, v12
	v_add_f32_e32 v11, v11, v13
	v_fma_f32 v14, v10, s17, v3
	v_fma_f32 v15, v11, s17, v3
	v_rsq_f32_e32 v14, v14
	v_rsq_f32_e32 v15, v15
	s_nop 0
	v_mul_f32_e32 v128, v128, v14
	v_mul_f32_e32 v129, v129, v14
	v_mul_f32_e32 v130, v130, v14
	v_mul_f32_e32 v131, v131, v14
	v_mul_f32_e32 v132, v132, v14
	v_mul_f32_e32 v133, v133, v14
	v_mul_f32_e32 v134, v134, v14
	v_mul_f32_e32 v135, v135, v14
	v_mul_f32_e32 v136, v136, v14
	v_mul_f32_e32 v137, v137, v14
	v_mul_f32_e32 v138, v138, v14
	v_mul_f32_e32 v139, v139, v14
	v_mul_f32_e32 v140, v140, v14
	v_mul_f32_e32 v141, v141, v14
	v_mul_f32_e32 v142, v142, v14
	v_mul_f32_e32 v143, v143, v14
	v_fmac_f32_e32 v144, v128, v20
	v_fmac_f32_e32 v145, v129, v21
	v_fmac_f32_e32 v146, v130, v22
	v_fmac_f32_e32 v147, v131, v23
	v_fmac_f32_e32 v148, v132, v24
	v_fmac_f32_e32 v149, v133, v25
	v_fmac_f32_e32 v150, v134, v26
	v_fmac_f32_e32 v151, v135, v27
	v_fmac_f32_e32 v152, v136, v28
	v_fmac_f32_e32 v153, v137, v29
	v_fmac_f32_e32 v154, v138, v30
	v_fmac_f32_e32 v155, v139, v31
	v_fmac_f32_e32 v156, v140, v32
	v_fmac_f32_e32 v157, v141, v33
	v_fmac_f32_e32 v158, v142, v34
	v_fmac_f32_e32 v159, v143, v35
	global_store_dwordx4 v1, v[144:147], s[40:41] offset:0 nt
	global_store_dwordx4 v1, v[148:151], s[40:41] offset:1024 nt
	global_store_dwordx4 v1, v[152:155], s[40:41] offset:2048 nt
	global_store_dwordx4 v1, v[156:159], s[40:41] offset:3072 nt
	v_mul_f32_e32 v160, v160, v15
	v_mul_f32_e32 v161, v161, v15
	v_mul_f32_e32 v162, v162, v15
	v_mul_f32_e32 v163, v163, v15
	v_mul_f32_e32 v164, v164, v15
	v_mul_f32_e32 v165, v165, v15
	v_mul_f32_e32 v166, v166, v15
	v_mul_f32_e32 v167, v167, v15
	v_mul_f32_e32 v168, v168, v15
	v_mul_f32_e32 v169, v169, v15
	v_mul_f32_e32 v170, v170, v15
	v_mul_f32_e32 v171, v171, v15
	v_mul_f32_e32 v172, v172, v15
	v_mul_f32_e32 v173, v173, v15
	v_mul_f32_e32 v174, v174, v15
	v_mul_f32_e32 v175, v175, v15
	v_fmac_f32_e32 v176, v160, v20
	v_fmac_f32_e32 v177, v161, v21
	v_fmac_f32_e32 v178, v162, v22
	v_fmac_f32_e32 v179, v163, v23
	v_fmac_f32_e32 v180, v164, v24
	v_fmac_f32_e32 v181, v165, v25
	v_fmac_f32_e32 v182, v166, v26
	v_fmac_f32_e32 v183, v167, v27
	v_fmac_f32_e32 v184, v168, v28
	v_fmac_f32_e32 v185, v169, v29
	v_fmac_f32_e32 v186, v170, v30
	v_fmac_f32_e32 v187, v171, v31
	v_fmac_f32_e32 v188, v172, v32
	v_fmac_f32_e32 v189, v173, v33
	v_fmac_f32_e32 v190, v174, v34
	v_fmac_f32_e32 v191, v175, v35
	global_store_dwordx4 v1, v[176:179], s[48:49] offset:0 nt
	global_store_dwordx4 v1, v[180:183], s[48:49] offset:1024 nt
	global_store_dwordx4 v1, v[184:187], s[48:49] offset:2048 nt
	global_store_dwordx4 v1, v[188:191], s[48:49] offset:3072 nt
	s_add_u32 s53, s16, 0x3000
	s_lshl_b32 s18, s53, 12
	s_lshl_b32 s19, s53, 11
	s_add_u32 s36, s4, s18
	s_addc_u32 s37, s5, 0
	s_add_u32 s38, s6, s19
	s_addc_u32 s39, s7, 0
	s_add_u32 s38, s38, 0x5200000
	s_addc_u32 s39, s39, 0
	s_add_u32 s40, s4, s18
	s_addc_u32 s41, s5, 0
	global_load_dwordx2 v[130:131], v2, s[38:39] offset:0
	global_load_dwordx2 v[134:135], v2, s[38:39] offset:512
	global_load_dwordx2 v[138:139], v2, s[38:39] offset:1024
	global_load_dwordx2 v[142:143], v2, s[38:39] offset:1536
	global_load_dwordx4 v[144:147], v1, s[36:37] offset:0
	global_load_dwordx4 v[148:151], v1, s[36:37] offset:1024
	global_load_dwordx4 v[152:155], v1, s[36:37] offset:2048
	global_load_dwordx4 v[156:159], v1, s[36:37] offset:3072
	s_add_u32 s53, s16, 0x3800
	s_lshl_b32 s18, s53, 12
	s_lshl_b32 s19, s53, 11
	s_add_u32 s44, s4, s18
	s_addc_u32 s45, s5, 0
	s_add_u32 s46, s6, s19
	s_addc_u32 s47, s7, 0
	s_add_u32 s46, s46, 0x5200000
	s_addc_u32 s47, s47, 0
	s_add_u32 s48, s4, s18
	s_addc_u32 s49, s5, 0
	global_load_dwordx2 v[162:163], v2, s[46:47] offset:0
	global_load_dwordx2 v[166:167], v2, s[46:47] offset:512
	global_load_dwordx2 v[170:171], v2, s[46:47] offset:1024
	global_load_dwordx2 v[174:175], v2, s[46:47] offset:1536
	global_load_dwordx4 v[176:179], v1, s[44:45] offset:0
	global_load_dwordx4 v[180:183], v1, s[44:45] offset:1024
	global_load_dwordx4 v[184:187], v1, s[44:45] offset:2048
	global_load_dwordx4 v[188:191], v1, s[44:45] offset:3072
	s_waitcnt vmcnt(24)
	v_lshlrev_b32_e32 v64, 16, v66
	v_and_b32_e32 v65, 0xffff0000, v66
	v_lshlrev_b32_e32 v66, 16, v67
	v_and_b32_e32 v67, 0xffff0000, v67
	v_lshlrev_b32_e32 v68, 16, v70
	v_and_b32_e32 v69, 0xffff0000, v70
	v_lshlrev_b32_e32 v70, 16, v71
	v_and_b32_e32 v71, 0xffff0000, v71
	v_lshlrev_b32_e32 v72, 16, v74
	v_and_b32_e32 v73, 0xffff0000, v74
	v_lshlrev_b32_e32 v74, 16, v75
	v_and_b32_e32 v75, 0xffff0000, v75
	v_lshlrev_b32_e32 v76, 16, v78
	v_and_b32_e32 v77, 0xffff0000, v78
	v_lshlrev_b32_e32 v78, 16, v79
	v_and_b32_e32 v79, 0xffff0000, v79
	v_lshlrev_b32_e32 v96, 16, v98
	v_and_b32_e32 v97, 0xffff0000, v98
	v_lshlrev_b32_e32 v98, 16, v99
	v_and_b32_e32 v99, 0xffff0000, v99
	v_lshlrev_b32_e32 v100, 16, v102
	v_and_b32_e32 v101, 0xffff0000, v102
	v_lshlrev_b32_e32 v102, 16, v103
	v_and_b32_e32 v103, 0xffff0000, v103
	v_lshlrev_b32_e32 v104, 16, v106
	v_and_b32_e32 v105, 0xffff0000, v106
	v_lshlrev_b32_e32 v106, 16, v107
	v_and_b32_e32 v107, 0xffff0000, v107
	v_lshlrev_b32_e32 v108, 16, v110
	v_and_b32_e32 v109, 0xffff0000, v110
	v_lshlrev_b32_e32 v110, 16, v111
	v_and_b32_e32 v111, 0xffff0000, v111
	v_mul_f32_e32 v10, v64, v64
	v_fmac_f32_e32 v10, v65, v65
	v_fmac_f32_e32 v10, v66, v66
	v_fmac_f32_e32 v10, v67, v67
	v_fmac_f32_e32 v10, v68, v68
	v_fmac_f32_e32 v10, v69, v69
	v_fmac_f32_e32 v10, v70, v70
	v_fmac_f32_e32 v10, v71, v71
	v_fmac_f32_e32 v10, v72, v72
	v_fmac_f32_e32 v10, v73, v73
	v_fmac_f32_e32 v10, v74, v74
	v_fmac_f32_e32 v10, v75, v75
	v_fmac_f32_e32 v10, v76, v76
	v_fmac_f32_e32 v10, v77, v77
	v_fmac_f32_e32 v10, v78, v78
	v_fmac_f32_e32 v10, v79, v79
	v_mul_f32_e32 v11, v96, v96
	v_fmac_f32_e32 v11, v97, v97
	v_fmac_f32_e32 v11, v98, v98
	v_fmac_f32_e32 v11, v99, v99
	v_fmac_f32_e32 v11, v100, v100
	v_fmac_f32_e32 v11, v101, v101
	v_fmac_f32_e32 v11, v102, v102
	v_fmac_f32_e32 v11, v103, v103
	v_fmac_f32_e32 v11, v104, v104
	v_fmac_f32_e32 v11, v105, v105
	v_fmac_f32_e32 v11, v106, v106
	v_fmac_f32_e32 v11, v107, v107
	v_fmac_f32_e32 v11, v108, v108
	v_fmac_f32_e32 v11, v109, v109
	v_fmac_f32_e32 v11, v110, v110
	v_fmac_f32_e32 v11, v111, v111
	ds_bpermute_b32 v12, v4, v10
	ds_bpermute_b32 v13, v4, v11
	s_waitcnt lgkmcnt(0)
	v_add_f32_e32 v10, v10, v12
	v_add_f32_e32 v11, v11, v13
	ds_bpermute_b32 v12, v5, v10
	ds_bpermute_b32 v13, v5, v11
	s_waitcnt lgkmcnt(0)
	v_add_f32_e32 v10, v10, v12
	v_add_f32_e32 v11, v11, v13
	ds_bpermute_b32 v12, v6, v10
	ds_bpermute_b32 v13, v6, v11
	s_waitcnt lgkmcnt(0)
	v_add_f32_e32 v10, v10, v12
	v_add_f32_e32 v11, v11, v13
	ds_bpermute_b32 v12, v7, v10
	ds_bpermute_b32 v13, v7, v11
	s_waitcnt lgkmcnt(0)
	v_add_f32_e32 v10, v10, v12
	v_add_f32_e32 v11, v11, v13
	ds_bpermute_b32 v12, v8, v10
	ds_bpermute_b32 v13, v8, v11
	s_waitcnt lgkmcnt(0)
	v_add_f32_e32 v10, v10, v12
	v_add_f32_e32 v11, v11, v13
	ds_bpermute_b32 v12, v9, v10
	ds_bpermute_b32 v13, v9, v11
	s_waitcnt lgkmcnt(0)
	v_add_f32_e32 v10, v10, v12
	v_add_f32_e32 v11, v11, v13
	v_fma_f32 v14, v10, s17, v3
	v_fma_f32 v15, v11, s17, v3
	v_rsq_f32_e32 v14, v14
	v_rsq_f32_e32 v15, v15
	s_nop 0
	v_mul_f32_e32 v64, v64, v14
	v_mul_f32_e32 v65, v65, v14
	v_mul_f32_e32 v66, v66, v14
	v_mul_f32_e32 v67, v67, v14
	v_mul_f32_e32 v68, v68, v14
	v_mul_f32_e32 v69, v69, v14
	v_mul_f32_e32 v70, v70, v14
	v_mul_f32_e32 v71, v71, v14
	v_mul_f32_e32 v72, v72, v14
	v_mul_f32_e32 v73, v73, v14
	v_mul_f32_e32 v74, v74, v14
	v_mul_f32_e32 v75, v75, v14
	v_mul_f32_e32 v76, v76, v14
	v_mul_f32_e32 v77, v77, v14
	v_mul_f32_e32 v78, v78, v14
	v_mul_f32_e32 v79, v79, v14
	v_fmac_f32_e32 v80, v64, v20
	v_fmac_f32_e32 v81, v65, v21
	v_fmac_f32_e32 v82, v66, v22
	v_fmac_f32_e32 v83, v67, v23
	v_fmac_f32_e32 v84, v68, v24
	v_fmac_f32_e32 v85, v69, v25
	v_fmac_f32_e32 v86, v70, v26
	v_fmac_f32_e32 v87, v71, v27
	v_fmac_f32_e32 v88, v72, v28
	v_fmac_f32_e32 v89, v73, v29
	v_fmac_f32_e32 v90, v74, v30
	v_fmac_f32_e32 v91, v75, v31
	v_fmac_f32_e32 v92, v76, v32
	v_fmac_f32_e32 v93, v77, v33
	v_fmac_f32_e32 v94, v78, v34
	v_fmac_f32_e32 v95, v79, v35
	global_store_dwordx4 v1, v[80:83], s[24:25] offset:0 nt
	global_store_dwordx4 v1, v[84:87], s[24:25] offset:1024 nt
	global_store_dwordx4 v1, v[88:91], s[24:25] offset:2048 nt
	global_store_dwordx4 v1, v[92:95], s[24:25] offset:3072 nt
	v_mul_f32_e32 v96, v96, v15
	v_mul_f32_e32 v97, v97, v15
	v_mul_f32_e32 v98, v98, v15
	v_mul_f32_e32 v99, v99, v15
	v_mul_f32_e32 v100, v100, v15
	v_mul_f32_e32 v101, v101, v15
	v_mul_f32_e32 v102, v102, v15
	v_mul_f32_e32 v103, v103, v15
	v_mul_f32_e32 v104, v104, v15
	v_mul_f32_e32 v105, v105, v15
	v_mul_f32_e32 v106, v106, v15
	v_mul_f32_e32 v107, v107, v15
	v_mul_f32_e32 v108, v108, v15
	v_mul_f32_e32 v109, v109, v15
	v_mul_f32_e32 v110, v110, v15
	v_mul_f32_e32 v111, v111, v15
	v_fmac_f32_e32 v112, v96, v20
	v_fmac_f32_e32 v113, v97, v21
	v_fmac_f32_e32 v114, v98, v22
	v_fmac_f32_e32 v115, v99, v23
	v_fmac_f32_e32 v116, v100, v24
	v_fmac_f32_e32 v117, v101, v25
	v_fmac_f32_e32 v118, v102, v26
	v_fmac_f32_e32 v119, v103, v27
	v_fmac_f32_e32 v120, v104, v28
	v_fmac_f32_e32 v121, v105, v29
	v_fmac_f32_e32 v122, v106, v30
	v_fmac_f32_e32 v123, v107, v31
	v_fmac_f32_e32 v124, v108, v32
	v_fmac_f32_e32 v125, v109, v33
	v_fmac_f32_e32 v126, v110, v34
	v_fmac_f32_e32 v127, v111, v35
	global_store_dwordx4 v1, v[112:115], s[32:33] offset:0 nt
	global_store_dwordx4 v1, v[116:119], s[32:33] offset:1024 nt
	global_store_dwordx4 v1, v[120:123], s[32:33] offset:2048 nt
	global_store_dwordx4 v1, v[124:127], s[32:33] offset:3072 nt
	s_waitcnt vmcnt(8)
	v_lshlrev_b32_e32 v128, 16, v130
	v_and_b32_e32 v129, 0xffff0000, v130
	v_lshlrev_b32_e32 v130, 16, v131
	v_and_b32_e32 v131, 0xffff0000, v131
	v_lshlrev_b32_e32 v132, 16, v134
	v_and_b32_e32 v133, 0xffff0000, v134
	v_lshlrev_b32_e32 v134, 16, v135
	v_and_b32_e32 v135, 0xffff0000, v135
	v_lshlrev_b32_e32 v136, 16, v138
	v_and_b32_e32 v137, 0xffff0000, v138
	v_lshlrev_b32_e32 v138, 16, v139
	v_and_b32_e32 v139, 0xffff0000, v139
	v_lshlrev_b32_e32 v140, 16, v142
	v_and_b32_e32 v141, 0xffff0000, v142
	v_lshlrev_b32_e32 v142, 16, v143
	v_and_b32_e32 v143, 0xffff0000, v143
	v_lshlrev_b32_e32 v160, 16, v162
	v_and_b32_e32 v161, 0xffff0000, v162
	v_lshlrev_b32_e32 v162, 16, v163
	v_and_b32_e32 v163, 0xffff0000, v163
	v_lshlrev_b32_e32 v164, 16, v166
	v_and_b32_e32 v165, 0xffff0000, v166
	v_lshlrev_b32_e32 v166, 16, v167
	v_and_b32_e32 v167, 0xffff0000, v167
	v_lshlrev_b32_e32 v168, 16, v170
	v_and_b32_e32 v169, 0xffff0000, v170
	v_lshlrev_b32_e32 v170, 16, v171
	v_and_b32_e32 v171, 0xffff0000, v171
	v_lshlrev_b32_e32 v172, 16, v174
	v_and_b32_e32 v173, 0xffff0000, v174
	v_lshlrev_b32_e32 v174, 16, v175
	v_and_b32_e32 v175, 0xffff0000, v175
	v_mul_f32_e32 v10, v128, v128
	v_fmac_f32_e32 v10, v129, v129
	v_fmac_f32_e32 v10, v130, v130
	v_fmac_f32_e32 v10, v131, v131
	v_fmac_f32_e32 v10, v132, v132
	v_fmac_f32_e32 v10, v133, v133
	v_fmac_f32_e32 v10, v134, v134
	v_fmac_f32_e32 v10, v135, v135
	v_fmac_f32_e32 v10, v136, v136
	v_fmac_f32_e32 v10, v137, v137
	v_fmac_f32_e32 v10, v138, v138
	v_fmac_f32_e32 v10, v139, v139
	v_fmac_f32_e32 v10, v140, v140
	v_fmac_f32_e32 v10, v141, v141
	v_fmac_f32_e32 v10, v142, v142
	v_fmac_f32_e32 v10, v143, v143
	v_mul_f32_e32 v11, v160, v160
	v_fmac_f32_e32 v11, v161, v161
	v_fmac_f32_e32 v11, v162, v162
	v_fmac_f32_e32 v11, v163, v163
	v_fmac_f32_e32 v11, v164, v164
	v_fmac_f32_e32 v11, v165, v165
	v_fmac_f32_e32 v11, v166, v166
	v_fmac_f32_e32 v11, v167, v167
	v_fmac_f32_e32 v11, v168, v168
	v_fmac_f32_e32 v11, v169, v169
	v_fmac_f32_e32 v11, v170, v170
	v_fmac_f32_e32 v11, v171, v171
	v_fmac_f32_e32 v11, v172, v172
	v_fmac_f32_e32 v11, v173, v173
	v_fmac_f32_e32 v11, v174, v174
	v_fmac_f32_e32 v11, v175, v175
	ds_bpermute_b32 v12, v4, v10
	ds_bpermute_b32 v13, v4, v11
	s_waitcnt lgkmcnt(0)
	v_add_f32_e32 v10, v10, v12
	v_add_f32_e32 v11, v11, v13
	ds_bpermute_b32 v12, v5, v10
	ds_bpermute_b32 v13, v5, v11
	s_waitcnt lgkmcnt(0)
	v_add_f32_e32 v10, v10, v12
	v_add_f32_e32 v11, v11, v13
	ds_bpermute_b32 v12, v6, v10
	ds_bpermute_b32 v13, v6, v11
	s_waitcnt lgkmcnt(0)
	v_add_f32_e32 v10, v10, v12
	v_add_f32_e32 v11, v11, v13
	ds_bpermute_b32 v12, v7, v10
	ds_bpermute_b32 v13, v7, v11
	s_waitcnt lgkmcnt(0)
	v_add_f32_e32 v10, v10, v12
	v_add_f32_e32 v11, v11, v13
	ds_bpermute_b32 v12, v8, v10
	ds_bpermute_b32 v13, v8, v11
	s_waitcnt lgkmcnt(0)
	v_add_f32_e32 v10, v10, v12
	v_add_f32_e32 v11, v11, v13
	ds_bpermute_b32 v12, v9, v10
	ds_bpermute_b32 v13, v9, v11
	s_waitcnt lgkmcnt(0)
	v_add_f32_e32 v10, v10, v12
	v_add_f32_e32 v11, v11, v13
	v_fma_f32 v14, v10, s17, v3
	v_fma_f32 v15, v11, s17, v3
	v_rsq_f32_e32 v14, v14
	v_rsq_f32_e32 v15, v15
	s_nop 0
	v_mul_f32_e32 v128, v128, v14
	v_mul_f32_e32 v129, v129, v14
	v_mul_f32_e32 v130, v130, v14
	v_mul_f32_e32 v131, v131, v14
	v_mul_f32_e32 v132, v132, v14
	v_mul_f32_e32 v133, v133, v14
	v_mul_f32_e32 v134, v134, v14
	v_mul_f32_e32 v135, v135, v14
	v_mul_f32_e32 v136, v136, v14
	v_mul_f32_e32 v137, v137, v14
	v_mul_f32_e32 v138, v138, v14
	v_mul_f32_e32 v139, v139, v14
	v_mul_f32_e32 v140, v140, v14
	v_mul_f32_e32 v141, v141, v14
	v_mul_f32_e32 v142, v142, v14
	v_mul_f32_e32 v143, v143, v14
	v_fmac_f32_e32 v144, v128, v20
	v_fmac_f32_e32 v145, v129, v21
	v_fmac_f32_e32 v146, v130, v22
	v_fmac_f32_e32 v147, v131, v23
	v_fmac_f32_e32 v148, v132, v24
	v_fmac_f32_e32 v149, v133, v25
	v_fmac_f32_e32 v150, v134, v26
	v_fmac_f32_e32 v151, v135, v27
	v_fmac_f32_e32 v152, v136, v28
	v_fmac_f32_e32 v153, v137, v29
	v_fmac_f32_e32 v154, v138, v30
	v_fmac_f32_e32 v155, v139, v31
	v_fmac_f32_e32 v156, v140, v32
	v_fmac_f32_e32 v157, v141, v33
	v_fmac_f32_e32 v158, v142, v34
	v_fmac_f32_e32 v159, v143, v35
	global_store_dwordx4 v1, v[144:147], s[40:41] offset:0 nt
	global_store_dwordx4 v1, v[148:151], s[40:41] offset:1024 nt
	global_store_dwordx4 v1, v[152:155], s[40:41] offset:2048 nt
	global_store_dwordx4 v1, v[156:159], s[40:41] offset:3072 nt
	v_mul_f32_e32 v160, v160, v15
	v_mul_f32_e32 v161, v161, v15
	v_mul_f32_e32 v162, v162, v15
	v_mul_f32_e32 v163, v163, v15
	v_mul_f32_e32 v164, v164, v15
	v_mul_f32_e32 v165, v165, v15
	v_mul_f32_e32 v166, v166, v15
	v_mul_f32_e32 v167, v167, v15
	v_mul_f32_e32 v168, v168, v15
	v_mul_f32_e32 v169, v169, v15
	v_mul_f32_e32 v170, v170, v15
	v_mul_f32_e32 v171, v171, v15
	v_mul_f32_e32 v172, v172, v15
	v_mul_f32_e32 v173, v173, v15
	v_mul_f32_e32 v174, v174, v15
	v_mul_f32_e32 v175, v175, v15
	v_fmac_f32_e32 v176, v160, v20
	v_fmac_f32_e32 v177, v161, v21
	v_fmac_f32_e32 v178, v162, v22
	v_fmac_f32_e32 v179, v163, v23
	v_fmac_f32_e32 v180, v164, v24
	v_fmac_f32_e32 v181, v165, v25
	v_fmac_f32_e32 v182, v166, v26
	v_fmac_f32_e32 v183, v167, v27
	v_fmac_f32_e32 v184, v168, v28
	v_fmac_f32_e32 v185, v169, v29
	v_fmac_f32_e32 v186, v170, v30
	v_fmac_f32_e32 v187, v171, v31
	v_fmac_f32_e32 v188, v172, v32
	v_fmac_f32_e32 v189, v173, v33
	v_fmac_f32_e32 v190, v174, v34
	v_fmac_f32_e32 v191, v175, v35
	global_store_dwordx4 v1, v[176:179], s[48:49] offset:0 nt
	global_store_dwordx4 v1, v[180:183], s[48:49] offset:1024 nt
	global_store_dwordx4 v1, v[184:187], s[48:49] offset:2048 nt
	global_store_dwordx4 v1, v[188:191], s[48:49] offset:3072 nt
	v_add_f32_e32 v208, v208, v212
	v_add_f32_e32 v209, v209, v213
	v_add_f32_e32 v210, v210, v214
	v_add_f32_e32 v211, v211, v215
	v_add_f32_e32 v216, v216, v220
	v_add_f32_e32 v217, v217, v221
	v_add_f32_e32 v218, v218, v222
	v_add_f32_e32 v219, v219, v223
	v_add_f32_e32 v224, v224, v228
	v_add_f32_e32 v225, v225, v229
	v_add_f32_e32 v226, v226, v230
	v_add_f32_e32 v227, v227, v231
	v_add_f32_e32 v232, v232, v236
	v_add_f32_e32 v233, v233, v237
	v_add_f32_e32 v234, v234, v238
	v_add_f32_e32 v235, v235, v239
	v_add_f32_e32 v208, v208, v216
	v_add_f32_e32 v209, v209, v217
	v_add_f32_e32 v210, v210, v218
	v_add_f32_e32 v211, v211, v219
	v_add_f32_e32 v224, v224, v232
	v_add_f32_e32 v225, v225, v233
	v_add_f32_e32 v226, v226, v234
	v_add_f32_e32 v227, v227, v235
	v_add_f32_e32 v208, v208, v224
	v_add_f32_e32 v209, v209, v225
	v_add_f32_e32 v210, v210, v226
	v_add_f32_e32 v211, v211, v227
	v_readfirstlane_b32 s18, v0
	s_lshr_b32 s18, s18, 6
	s_lshl_b32 s19, s18, 2
	s_and_b32 s52, s18, 4
	s_lshl_b32 s52, s52, 2
	v_mov_b32_e32 v16, s19
	v_mov_b32_e32 v17, s52
	v_mul_f32_e32 v10, v208, v208
	v_fmac_f32_e32 v10, v209, v209
	v_fmac_f32_e32 v10, v210, v210
	v_fmac_f32_e32 v10, v211, v211
	ds_bpermute_b32 v11, v4, v10
	s_waitcnt lgkmcnt(0)
	v_add_f32_e32 v10, v10, v11
	ds_bpermute_b32 v11, v5, v10
	s_waitcnt lgkmcnt(0)
	v_add_f32_e32 v10, v10, v11
	ds_bpermute_b32 v11, v6, v10
	s_waitcnt lgkmcnt(0)
	v_add_f32_e32 v10, v10, v11
	ds_bpermute_b32 v11, v7, v10
	s_waitcnt lgkmcnt(0)
	v_add_f32_e32 v10, v10, v11
	ds_bpermute_b32 v11, v8, v10
	s_waitcnt lgkmcnt(0)
	v_add_f32_e32 v10, v10, v11
	ds_bpermute_b32 v11, v9, v10
	s_waitcnt lgkmcnt(0)
	v_add_f32_e32 v10, v10, v11
	ds_write_b32 v16, v10 offset:0
	s_waitcnt lgkmcnt(0)
	s_barrier
	ds_read_b128 v[12:15], v17 offset:0
	s_waitcnt lgkmcnt(0)
	v_add_f32_e32 v12, v12, v13
	v_add_f32_e32 v14, v14, v15
	v_add_f32_e32 v10, v12, v14
	v_fma_f32 v11, v10, s17, v3
	v_rsq_f32_e32 v11, v11
	s_nop 0
	v_mul_f32_e32 v208, v208, v11
	v_mul_f32_e32 v209, v209, v11
	v_mul_f32_e32 v210, v210, v11
	v_mul_f32_e32 v211, v211, v11
	v_fmac_f32_e32 v240, v208, v244
	v_fmac_f32_e32 v241, v209, v245
	v_fmac_f32_e32 v242, v210, v246
	v_fmac_f32_e32 v243, v211, v247
	s_lshl_b32 s18, s54, 12
	s_add_u32 s18, s18, s55
	s_add_u32 s56, s4, s18
	s_addc_u32 s57, s5, 0
	s_add_u32 s56, s56, 0x4000000
	s_addc_u32 s57, s57, 0
	global_store_dwordx4 v1, v[240:243], s[56:57]
